# branch GEMM epilogue (EpiBranch) hand-written and software-pipelined: three row groups of gate/mix loads in flight, no per-batch vmcnt(0)
# baseline (speedup 1.0000x reference)
; #define PG8_STAGE(bufoff, gbase, voff) do { _Pragma("unroll") for (int _i = 0; _i < 2; ++_i) \
;         __builtin_amdgcn_global_load_lds((const unsigned*)((const char*)(gbase) + (voff)[_i]), (LAS unsigned*)(lds + (bufoff) + ldsw + _i * 8192), 16, 0, 0); } while (0)
; #define PG8_LDA(dst, b, h) do { _Pragma("unroll") for (int m = 0; m < 4; ++m) _Pragma("unroll") for (int k = 0; k < 2; ++k) dst[m][k] = *(const LAS bf16x8*)(lds + PG8_SA(b, h) + aoff + m * 2048 + k * 1024); } while (0)
; #define PG8_LDB(dst, b, h) do { _Pragma("unroll") for (int n = 0; n < 2; ++n) _Pragma("unroll") for (int k = 0; k < 2; ++k) dst[n][k] = *(const LAS bf16x8*)(lds + PG8_SB(b, h) + boff + n * 2048 + k * 1024); } while (0)
; #define PG8_MMA(ai, bj, At, Bt) do { __builtin_amdgcn_s_setprio(1); _Pragma("unroll") for (int m = 0; m < 4; ++m) _Pragma("unroll") for (int n = 0; n < 2; ++n) _Pragma("unroll") for (int k = 0; k < 2; ++k) \
;         acc[ai][bj][m][n] = __builtin_amdgcn_mfma_f32_16x16x32_bf16(Bt[n][k], At[m][k], acc[ai][bj][m][n], 0, 0, 0); __builtin_amdgcn_s_setprio(0); } while (0)
; #define PG8_WAIT_V(n) asm volatile("s_waitcnt vmcnt(" #n ")" ::: "memory")
; #define PG8_WAIT_L(n) asm volatile("s_waitcnt lgkmcnt(" #n ")" ::: "memory")
; #define PG8_BAR __builtin_amdgcn_s_barrier()
; #define PG8_SCHED __builtin_amdgcn_sched_barrier(0)
; template <class Epi, class Sched>
; __device__ __forceinline__ void gemm_phase(LAS unsigned char* lds, const Gemm g, const Sched& S, const Epi& E) {
;     ...
;             PG8_LDB(B0, 0, 0); PG8_SCHED; PG8_LDA(At, 0, 0); PG8_STAGE(PG8_SA(1, 1), a1 + hstep, voffA);
;             PG8_WAIT_L(8); PG8_BAR; PG8_WAIT_L(0); PG8_MMA(0, 0, At, B0); PG8_BAR; PG8_SCHED;
;             PG8_LDB(B1, 0, 1); PG8_STAGE(PG8_SB(0, 0), b2, voffB);
;             PG8_BAR; PG8_WAIT_L(0); PG8_MMA(0, 1, At, B1); PG8_BAR;
;             PG8_LDA(At, 0, 1); PG8_STAGE(PG8_SA(0, 0), a2, voffA);
;             PG8_BAR; PG8_WAIT_L(0); PG8_MMA(1, 0, At, B0); PG8_BAR; PG8_SCHED;
;             PG8_STAGE(PG8_SB(0, 1), b2 + hstep, voffB);
;             PG8_WAIT_V(6); PG8_BAR; PG8_MMA(1, 1, At, B1); PG8_BAR;
.LBB0_398:
	s_add_u32 s22, s20, 0xfffc0080
	s_addc_u32 s23, s21, -1
	s_add_i32 s43, 0, 0x10000
	v_add_u32_e32 v140, s43, v220
	ds_read_b128 v[128:131], v140
	ds_read_b128 v[132:135], v140 offset:1024
	ds_read_b128 v[136:139], v140 offset:2048
	ds_read_b128 v[140:143], v140 offset:3072
	s_cmp_eq_u32 s42, 12
	s_cselect_b32 s25, s9, s23
	s_cselect_b32 s24, s19, s22
	s_cselect_b32 s23, s7, s41
	s_cselect_b32 s22, s13, s35
	v_lshl_add_u64 v[202:203], s[20:21], 0, v[200:201]
	s_add_i32 m0, s31, 0xc000
	ds_read_b128 v[144:147], v222
	ds_read_b128 v[148:151], v222 offset:1024
	ds_read_b128 v[152:155], v222 offset:2048
	ds_read_b128 v[156:159], v222 offset:3072
	ds_read_b128 v[160:163], v222 offset:4096
	ds_read_b128 v[164:167], v222 offset:5120
	ds_read_b128 v[168:171], v222 offset:6144
	ds_read_b128 v[172:175], v222 offset:7168
	global_load_lds_dwordx4 v[202:203], off
	v_lshl_add_u64 v[202:203], s[20:21], 0, v[198:199]
	s_add_i32 m0, s31, 0xe000
	s_nop 0
	global_load_lds_dwordx4 v[202:203], off
	s_waitcnt lgkmcnt(8)
	s_barrier
	s_waitcnt lgkmcnt(0)
	s_setprio 1
	s_waitcnt lgkmcnt(0)
	v_mfma_f32_16x16x32_bf16 v[124:127], v[128:131], v[144:147], v[124:127]
	v_mfma_f32_16x16x32_bf16 v[120:123], v[136:139], v[144:147], v[120:123]
	v_mfma_f32_16x16x32_bf16 v[108:111], v[128:131], v[152:155], v[108:111]
	v_mfma_f32_16x16x32_bf16 v[104:107], v[136:139], v[152:155], v[104:107]
	v_mfma_f32_16x16x32_bf16 v[92:95], v[128:131], v[160:163], v[92:95]
	v_mfma_f32_16x16x32_bf16 v[88:91], v[136:139], v[160:163], v[88:91]
	v_mfma_f32_16x16x32_bf16 v[76:79], v[128:131], v[168:171], v[76:79]
	v_mfma_f32_16x16x32_bf16 v[72:75], v[136:139], v[168:171], v[72:75]
	v_mfma_f32_16x16x32_bf16 v[124:127], v[132:135], v[148:151], v[124:127]
	v_mfma_f32_16x16x32_bf16 v[120:123], v[140:143], v[148:151], v[120:123]
	v_mfma_f32_16x16x32_bf16 v[108:111], v[132:135], v[156:159], v[108:111]
	v_mfma_f32_16x16x32_bf16 v[104:107], v[140:143], v[156:159], v[104:107]
	v_mfma_f32_16x16x32_bf16 v[92:95], v[132:135], v[164:167], v[92:95]
	v_mfma_f32_16x16x32_bf16 v[88:91], v[140:143], v[164:167], v[88:91]
	v_mfma_f32_16x16x32_bf16 v[76:79], v[132:135], v[172:175], v[76:79]
	v_mfma_f32_16x16x32_bf16 v[72:75], v[140:143], v[172:175], v[72:75]
	s_setprio 0
	s_barrier
	s_add_i32 s46, 0, 0x14000
	s_add_i32 s43, s43, s30
	v_add_u32_e32 v214, s46, v220
	v_lshl_add_u64 v[218:219], s[22:23], 0, v[176:177]
	s_mov_b32 m0, s43
	ds_read_b128 v[202:205], v214
	ds_read_b128 v[206:209], v214 offset:1024
	ds_read_b128 v[210:213], v214 offset:2048
	ds_read_b128 v[214:217], v214 offset:3072
	global_load_lds_dwordx4 v[218:219], off
	v_lshl_add_u64 v[224:225], s[22:23], 0, v[196:197]
	s_add_i32 m0, s43, 0x2000
	s_nop 0
	global_load_lds_dwordx4 v[224:225], off
	s_barrier
	s_waitcnt lgkmcnt(0)
	s_setprio 1
	s_waitcnt lgkmcnt(0)
	v_mfma_f32_16x16x32_bf16 v[116:119], v[202:205], v[144:147], v[116:119]
	v_mfma_f32_16x16x32_bf16 v[112:115], v[210:213], v[144:147], v[112:115]
	v_mfma_f32_16x16x32_bf16 v[100:103], v[202:205], v[152:155], v[100:103]
	v_mfma_f32_16x16x32_bf16 v[96:99], v[210:213], v[152:155], v[96:99]
	v_mfma_f32_16x16x32_bf16 v[84:87], v[202:205], v[160:163], v[84:87]
	v_mfma_f32_16x16x32_bf16 v[80:83], v[210:213], v[160:163], v[80:83]
	v_mfma_f32_16x16x32_bf16 v[68:71], v[202:205], v[168:171], v[68:71]
	v_mfma_f32_16x16x32_bf16 v[64:67], v[210:213], v[168:171], v[64:67]
	v_mfma_f32_16x16x32_bf16 v[116:119], v[206:209], v[148:151], v[116:119]
	v_mfma_f32_16x16x32_bf16 v[112:115], v[214:217], v[148:151], v[112:115]
	v_mfma_f32_16x16x32_bf16 v[100:103], v[206:209], v[156:159], v[100:103]
	v_mfma_f32_16x16x32_bf16 v[96:99], v[214:217], v[156:159], v[96:99]
	v_mfma_f32_16x16x32_bf16 v[84:87], v[206:209], v[164:167], v[84:87]
	v_mfma_f32_16x16x32_bf16 v[80:83], v[214:217], v[164:167], v[80:83]
	v_mfma_f32_16x16x32_bf16 v[68:71], v[206:209], v[172:175], v[68:71]
	v_mfma_f32_16x16x32_bf16 v[64:67], v[214:217], v[172:175], v[64:67]
	s_setprio 0
	s_mov_b32 m0, s31
	v_lshl_add_u64 v[226:227], s[24:25], 0, v[192:193]
	s_barrier
	ds_read_b128 v[144:147], v222 offset:16384
	ds_read_b128 v[148:151], v222 offset:17408
	ds_read_b128 v[152:155], v222 offset:18432
	ds_read_b128 v[156:159], v222 offset:19456
	ds_read_b128 v[160:163], v222 offset:20480
	ds_read_b128 v[164:167], v222 offset:21504
	ds_read_b128 v[168:171], v222 offset:22528
	ds_read_b128 v[172:175], v222 offset:23552
	global_load_lds_dwordx4 v[226:227], off
	v_lshl_add_u64 v[228:229], s[24:25], 0, v[194:195]
	s_mov_b32 m0, s33
	s_nop 0
	global_load_lds_dwordx4 v[228:229], off
	s_barrier
	s_waitcnt lgkmcnt(0)
	s_setprio 1
	s_waitcnt lgkmcnt(0)
	v_mfma_f32_16x16x32_bf16 v[60:63], v[128:131], v[144:147], v[60:63]
	v_mfma_f32_16x16x32_bf16 v[56:59], v[136:139], v[144:147], v[56:59]
	v_mfma_f32_16x16x32_bf16 v[44:47], v[128:131], v[152:155], v[44:47]
	v_mfma_f32_16x16x32_bf16 v[40:43], v[136:139], v[152:155], v[40:43]
	v_mfma_f32_16x16x32_bf16 v[28:31], v[128:131], v[160:163], v[28:31]
	v_mfma_f32_16x16x32_bf16 v[24:27], v[136:139], v[160:163], v[24:27]
	v_mfma_f32_16x16x32_bf16 v[12:15], v[128:131], v[168:171], v[12:15]
	v_mfma_f32_16x16x32_bf16 v[8:11], v[136:139], v[168:171], v[8:11]
	v_mfma_f32_16x16x32_bf16 v[60:63], v[132:135], v[148:151], v[60:63]
	v_mfma_f32_16x16x32_bf16 v[56:59], v[140:143], v[148:151], v[56:59]
	v_mfma_f32_16x16x32_bf16 v[44:47], v[132:135], v[156:159], v[44:47]
	v_mfma_f32_16x16x32_bf16 v[40:43], v[140:143], v[156:159], v[40:43]
	v_mfma_f32_16x16x32_bf16 v[28:31], v[132:135], v[164:167], v[28:31]
	v_mfma_f32_16x16x32_bf16 v[24:27], v[140:143], v[164:167], v[24:27]
	v_mfma_f32_16x16x32_bf16 v[12:15], v[132:135], v[172:175], v[12:15]
	v_mfma_f32_16x16x32_bf16 v[8:11], v[140:143], v[172:175], v[8:11]
	s_setprio 0
	s_barrier
; #define PG8_STAGE(bufoff, gbase, voff) do { _Pragma("unroll") for (int _i = 0; _i < 2; ++_i) \
;         __builtin_amdgcn_global_load_lds((const unsigned*)((const char*)(gbase) + (voff)[_i]), (LAS unsigned*)(lds + (bufoff) + ldsw + _i * 8192), 16, 0, 0); } while (0)
; #define PG8_LDA(dst, b, h) do { _Pragma("unroll") for (int m = 0; m < 4; ++m) _Pragma("unroll") for (int k = 0; k < 2; ++k) dst[m][k] = *(const LAS bf16x8*)(lds + PG8_SA(b, h) + aoff + m * 2048 + k * 1024); } while (0)
; #define PG8_LDB(dst, b, h) do { _Pragma("unroll") for (int n = 0; n < 2; ++n) _Pragma("unroll") for (int k = 0; k < 2; ++k) dst[n][k] = *(const LAS bf16x8*)(lds + PG8_SB(b, h) + boff + n * 2048 + k * 1024); } while (0)
; #define PG8_MMA(ai, bj, At, Bt) do { __builtin_amdgcn_s_setprio(1); _Pragma("unroll") for (int m = 0; m < 4; ++m) _Pragma("unroll") for (int n = 0; n < 2; ++n) _Pragma("unroll") for (int k = 0; k < 2; ++k) \
;         acc[ai][bj][m][n] = __builtin_amdgcn_mfma_f32_16x16x32_bf16(Bt[n][k], At[m][k], acc[ai][bj][m][n], 0, 0, 0); __builtin_amdgcn_s_setprio(0); } while (0)
; #define PG8_WAIT_V(n) asm volatile("s_waitcnt vmcnt(" #n ")" ::: "memory")
; #define PG8_WAIT_L(n) asm volatile("s_waitcnt lgkmcnt(" #n ")" ::: "memory")
; #define PG8_BAR __builtin_amdgcn_s_barrier()
; #define PG8_SCHED __builtin_amdgcn_sched_barrier(0)
; template <class Epi, class Sched>
; __device__ __forceinline__ void gemm_phase(LAS unsigned char* lds, const Gemm g, const Sched& S, const Epi& E) {
;     ...
;             PG8_WAIT_V(6); PG8_BAR; PG8_MMA(1, 1, At, B1); PG8_BAR;
;             PG8_LDB(B0, 1, 0); PG8_SCHED; PG8_LDA(At, 1, 0); PG8_STAGE(PG8_SA(0, 1), a2 + hstep, voffA);
;             PG8_WAIT_L(8); PG8_BAR; PG8_WAIT_L(0); PG8_MMA(0, 0, At, B0); PG8_BAR; PG8_SCHED;
;             PG8_LDB(B1, 1, 1); PG8_STAGE(PG8_SB(1, 0), b3, voffB);
;             PG8_BAR; PG8_WAIT_L(0); PG8_MMA(0, 1, At, B1); PG8_BAR;
;             PG8_LDA(At, 1, 1); PG8_STAGE(PG8_SA(1, 0), a3, voffA);
;             PG8_BAR; PG8_WAIT_L(0); PG8_MMA(1, 0, At, B0); PG8_BAR; PG8_SCHED;
;             PG8_STAGE(PG8_SB(1, 1), b3 + hstep, voffB);
;             PG8_WAIT_V(6); PG8_BAR; PG8_MMA(1, 1, At, B1); PG8_BAR;
	s_add_u32 s44, s22, 0x40000
	s_addc_u32 s45, s23, 0
	s_add_i32 s43, s46, s30
	v_lshl_add_u64 v[128:129], s[44:45], 0, v[176:177]
	s_mov_b32 m0, s43
	s_nop 0
	global_load_lds_dwordx4 v[128:129], off
	v_lshl_add_u64 v[128:129], s[44:45], 0, v[196:197]
	s_add_i32 m0, s43, 0x2000
	s_nop 0
	global_load_lds_dwordx4 v[128:129], off
	s_waitcnt vmcnt(6)
	s_barrier
	s_setprio 1
	v_mfma_f32_16x16x32_bf16 v[52:55], v[202:205], v[144:147], v[52:55]
	v_mfma_f32_16x16x32_bf16 v[48:51], v[210:213], v[144:147], v[48:51]
	v_mfma_f32_16x16x32_bf16 v[36:39], v[202:205], v[152:155], v[36:39]
	v_mfma_f32_16x16x32_bf16 v[32:35], v[210:213], v[152:155], v[32:35]
	v_mfma_f32_16x16x32_bf16 v[20:23], v[202:205], v[160:163], v[20:23]
	v_mfma_f32_16x16x32_bf16 v[16:19], v[210:213], v[160:163], v[16:19]
	v_mfma_f32_16x16x32_bf16 v[4:7], v[202:205], v[168:171], v[4:7]
	v_mfma_f32_16x16x32_bf16 v[0:3], v[210:213], v[168:171], v[0:3]
	v_mfma_f32_16x16x32_bf16 v[52:55], v[206:209], v[148:151], v[52:55]
	v_mfma_f32_16x16x32_bf16 v[48:51], v[214:217], v[148:151], v[48:51]
	v_mfma_f32_16x16x32_bf16 v[36:39], v[206:209], v[156:159], v[36:39]
	v_mfma_f32_16x16x32_bf16 v[32:35], v[214:217], v[156:159], v[32:35]
	v_mfma_f32_16x16x32_bf16 v[20:23], v[206:209], v[164:167], v[20:23]
	v_mfma_f32_16x16x32_bf16 v[16:19], v[214:217], v[164:167], v[16:19]
	v_mfma_f32_16x16x32_bf16 v[4:7], v[206:209], v[172:175], v[4:7]
	v_mfma_f32_16x16x32_bf16 v[0:3], v[214:217], v[172:175], v[0:3]
	s_setprio 0
	s_add_i32 s43, 0, 0x18000
	v_add_u32_e32 v140, s43, v220
	s_barrier
	ds_read_b128 v[128:131], v140
	ds_read_b128 v[132:135], v140 offset:1024
	ds_read_b128 v[136:139], v140 offset:2048
	ds_read_b128 v[140:143], v140 offset:3072
	s_add_u32 s24, s24, 0x40000
	s_addc_u32 s25, s25, 0
	s_mov_b32 m0, s36
	v_lshl_add_u64 v[202:203], s[24:25], 0, v[192:193]
	ds_read_b128 v[144:147], v222 offset:32768
	ds_read_b128 v[148:151], v222 offset:33792
	ds_read_b128 v[152:155], v222 offset:34816
	ds_read_b128 v[156:159], v222 offset:35840
	ds_read_b128 v[160:163], v222 offset:36864
	ds_read_b128 v[164:167], v222 offset:37888
	ds_read_b128 v[168:171], v222 offset:38912
	ds_read_b128 v[172:175], v222 offset:39936
	global_load_lds_dwordx4 v[202:203], off
	v_lshl_add_u64 v[202:203], s[24:25], 0, v[194:195]
	s_mov_b32 m0, s37
	s_nop 0
	global_load_lds_dwordx4 v[202:203], off
	s_waitcnt lgkmcnt(8)
	s_barrier
	s_waitcnt lgkmcnt(0)
	s_setprio 1
	s_waitcnt lgkmcnt(0)
	v_mfma_f32_16x16x32_bf16 v[124:127], v[128:131], v[144:147], v[124:127]
	v_mfma_f32_16x16x32_bf16 v[120:123], v[136:139], v[144:147], v[120:123]
	v_mfma_f32_16x16x32_bf16 v[108:111], v[128:131], v[152:155], v[108:111]
	v_mfma_f32_16x16x32_bf16 v[104:107], v[136:139], v[152:155], v[104:107]
	v_mfma_f32_16x16x32_bf16 v[92:95], v[128:131], v[160:163], v[92:95]
	v_mfma_f32_16x16x32_bf16 v[88:91], v[136:139], v[160:163], v[88:91]
	v_mfma_f32_16x16x32_bf16 v[76:79], v[128:131], v[168:171], v[76:79]
	v_mfma_f32_16x16x32_bf16 v[72:75], v[136:139], v[168:171], v[72:75]
	v_mfma_f32_16x16x32_bf16 v[124:127], v[132:135], v[148:151], v[124:127]
	v_mfma_f32_16x16x32_bf16 v[120:123], v[140:143], v[148:151], v[120:123]
	v_mfma_f32_16x16x32_bf16 v[108:111], v[132:135], v[156:159], v[108:111]
	v_mfma_f32_16x16x32_bf16 v[104:107], v[140:143], v[156:159], v[104:107]
	v_mfma_f32_16x16x32_bf16 v[92:95], v[132:135], v[164:167], v[92:95]
	v_mfma_f32_16x16x32_bf16 v[88:91], v[140:143], v[164:167], v[88:91]
	v_mfma_f32_16x16x32_bf16 v[76:79], v[132:135], v[172:175], v[76:79]
	v_mfma_f32_16x16x32_bf16 v[72:75], v[140:143], v[172:175], v[72:75]
	s_setprio 0
	s_barrier
	s_add_i32 s24, 0, 0x1c000
	s_add_i32 s25, s43, s30
	v_add_u32_e32 v214, s24, v220
	v_lshl_add_u64 v[218:219], v[218:219], 0, s[82:83]
	s_mov_b32 m0, s25
	ds_read_b128 v[202:205], v214
	ds_read_b128 v[206:209], v214 offset:1024
	ds_read_b128 v[210:213], v214 offset:2048
	ds_read_b128 v[214:217], v214 offset:3072
	global_load_lds_dwordx4 v[218:219], off
	v_lshl_add_u64 v[218:219], v[224:225], 0, s[82:83]
	s_add_i32 m0, s25, 0x2000
	s_nop 0
	global_load_lds_dwordx4 v[218:219], off
	s_barrier
	s_waitcnt lgkmcnt(0)
	s_setprio 1
	s_waitcnt lgkmcnt(0)
	v_mfma_f32_16x16x32_bf16 v[116:119], v[202:205], v[144:147], v[116:119]
	v_mfma_f32_16x16x32_bf16 v[112:115], v[210:213], v[144:147], v[112:115]
	v_mfma_f32_16x16x32_bf16 v[100:103], v[202:205], v[152:155], v[100:103]
	v_mfma_f32_16x16x32_bf16 v[96:99], v[210:213], v[152:155], v[96:99]
	v_mfma_f32_16x16x32_bf16 v[84:87], v[202:205], v[160:163], v[84:87]
	v_mfma_f32_16x16x32_bf16 v[80:83], v[210:213], v[160:163], v[80:83]
	v_mfma_f32_16x16x32_bf16 v[68:71], v[202:205], v[168:171], v[68:71]
	v_mfma_f32_16x16x32_bf16 v[64:67], v[210:213], v[168:171], v[64:67]
	v_mfma_f32_16x16x32_bf16 v[116:119], v[206:209], v[148:151], v[116:119]
	v_mfma_f32_16x16x32_bf16 v[112:115], v[214:217], v[148:151], v[112:115]
	v_mfma_f32_16x16x32_bf16 v[100:103], v[206:209], v[156:159], v[100:103]
	v_mfma_f32_16x16x32_bf16 v[96:99], v[214:217], v[156:159], v[96:99]
	v_mfma_f32_16x16x32_bf16 v[84:87], v[206:209], v[164:167], v[84:87]
	v_mfma_f32_16x16x32_bf16 v[80:83], v[214:217], v[164:167], v[80:83]
	v_mfma_f32_16x16x32_bf16 v[68:71], v[206:209], v[172:175], v[68:71]
	v_mfma_f32_16x16x32_bf16 v[64:67], v[214:217], v[172:175], v[64:67]
	s_setprio 0
	s_mov_b32 m0, s38
	v_lshl_add_u64 v[218:219], v[226:227], 0, s[82:83]
	s_barrier
	ds_read_b128 v[144:147], v222 offset:49152
	ds_read_b128 v[148:151], v222 offset:50176
	ds_read_b128 v[152:155], v222 offset:51200
	ds_read_b128 v[156:159], v222 offset:52224
	ds_read_b128 v[160:163], v222 offset:53248
	ds_read_b128 v[164:167], v222 offset:54272
	ds_read_b128 v[168:171], v222 offset:55296
	ds_read_b128 v[172:175], v222 offset:56320
	global_load_lds_dwordx4 v[218:219], off
	v_lshl_add_u64 v[218:219], v[228:229], 0, s[82:83]
	s_mov_b32 m0, s39
	s_nop 0
	global_load_lds_dwordx4 v[218:219], off
	s_barrier
;     template <int Z> __device__ __forceinline__ void run(const f32x4 (&acc)[2][2][4][2], const Unit& u, int wr, int wc, int fr, int fq) const {
;         const int row0 = u.pm * BM + wr * 64 + fr, col0 = u.pn * BM + wc * 32 + 8 * fq;
; #pragma unroll
;         for (int ai = 0; ai < 2; ++ai)
; #pragma unroll
;             for (int m2 = 0; m2 < 4; m2 += 2) {
;                 u32x4 graw[2][2]; f32x4 old0[2][2], old1[2][2];
; #pragma unroll
;                 for (int mm = 0; mm < 2; ++mm)
; #pragma unroll
;                     for (int bj = 0; bj < 2; ++bj) { const int row = row0 + ai * HALF + (m2 + mm) * 16, col = col0 + bj * HALF;
;                         graw[mm][bj] = *(const u32x4*)(proj + (size_t)row * NP + C_BR + Z * 2048 + col);
;                         if (Z > 0) { const float* mp = mix + (size_t)row * 2048 + col; old0[mm][bj] = *(const f32x4*)mp; old1[mm][bj] = *(const f32x4*)(mp + 4); } }
; #pragma unroll
;                 for (int mm = 0; mm < 2; ++mm)
; #pragma unroll
;                     for (int bj = 0; bj < 2; ++bj) { const int row = row0 + ai * HALF + (m2 + mm) * 16, col = col0 + bj * HALF;
;                         const u32x4 g = graw[mm][bj];
;                         f32x4 v0 = acc[ai][bj][m2 + mm][0], v1 = acc[ai][bj][m2 + mm][1];
;                         v0[0] *= sigmoidf_(lo16(g.x)); v0[1] *= sigmoidf_(hi16(g.x)); v0[2] *= sigmoidf_(lo16(g.y)); v0[3] *= sigmoidf_(hi16(g.y));
;                         v1[0] *= sigmoidf_(lo16(g.z)); v1[1] *= sigmoidf_(hi16(g.z)); v1[2] *= sigmoidf_(lo16(g.w)); v1[3] *= sigmoidf_(hi16(g.w));
;                         if (Z > 0) { v0 += old0[mm][bj]; v1 += old1[mm][bj]; }
;                         if (Z < 2) { float* mp = mix + (size_t)row * 2048 + col; *(f32x4*)mp = v0; *(f32x4*)(mp + 4) = v1; }
;                         else { u32x4 w; w.x = cvt_pk_bf16(v0[0], v0[1]); w.y = cvt_pk_bf16(v0[2], v0[3]); w.z = cvt_pk_bf16(v1[0], v1[1]); w.w = cvt_pk_bf16(v1[2], v1[3]);
;                             *(u32x4*)(mixb + (size_t)row * 2048 + col) = w; } }
; template <class Epi, class Sched>
; __device__ __forceinline__ void gemm_phase(LAS unsigned char* lds, const Gemm g, const Sched& S, const Epi& E) {
;     ...
;             PG8_BAR; PG8_WAIT_L(0); PG8_MMA(1, 0, At, B0); PG8_BAR; PG8_SCHED;
;             PG8_STAGE(PG8_SB(1, 1), b3 + hstep, voffB);
;             PG8_WAIT_V(6); PG8_BAR; PG8_MMA(1, 1, At, B1); PG8_BAR;
	s_waitcnt lgkmcnt(0)
	s_setprio 1
	s_waitcnt lgkmcnt(0)
	v_mfma_f32_16x16x32_bf16 v[60:63], v[128:131], v[144:147], v[60:63]
	v_mfma_f32_16x16x32_bf16 v[56:59], v[136:139], v[144:147], v[56:59]
	v_mfma_f32_16x16x32_bf16 v[44:47], v[128:131], v[152:155], v[44:47]
	v_mfma_f32_16x16x32_bf16 v[40:43], v[136:139], v[152:155], v[40:43]
	v_mfma_f32_16x16x32_bf16 v[28:31], v[128:131], v[160:163], v[28:31]
	v_mfma_f32_16x16x32_bf16 v[24:27], v[136:139], v[160:163], v[24:27]
	v_mfma_f32_16x16x32_bf16 v[12:15], v[128:131], v[168:171], v[12:15]
	v_mfma_f32_16x16x32_bf16 v[8:11], v[136:139], v[168:171], v[8:11]
	v_mfma_f32_16x16x32_bf16 v[60:63], v[132:135], v[148:151], v[60:63]
	v_mfma_f32_16x16x32_bf16 v[56:59], v[140:143], v[148:151], v[56:59]
	v_mfma_f32_16x16x32_bf16 v[44:47], v[132:135], v[156:159], v[44:47]
	v_mfma_f32_16x16x32_bf16 v[40:43], v[140:143], v[156:159], v[40:43]
	v_mfma_f32_16x16x32_bf16 v[28:31], v[132:135], v[164:167], v[28:31]
	v_mfma_f32_16x16x32_bf16 v[24:27], v[140:143], v[164:167], v[24:27]
	v_mfma_f32_16x16x32_bf16 v[12:15], v[132:135], v[172:175], v[12:15]
	v_mfma_f32_16x16x32_bf16 v[8:11], v[140:143], v[172:175], v[8:11]
	s_setprio 0
	s_barrier
	s_add_u32 s22, s22, 0x40080
	s_addc_u32 s23, s23, 0
	s_add_i32 s24, s24, s30
	v_lshl_add_u64 v[128:129], s[22:23], 0, v[176:177]
	s_mov_b32 m0, s24
	s_nop 0
	global_load_lds_dwordx4 v[128:129], off
	v_lshl_add_u64 v[128:129], s[22:23], 0, v[196:197]
	s_add_i32 m0, s24, 0x2000
	s_nop 0
	global_load_lds_dwordx4 v[128:129], off
	s_waitcnt vmcnt(6)
	s_barrier
	s_setprio 1
	v_mfma_f32_16x16x32_bf16 v[52:55], v[202:205], v[144:147], v[52:55]
	v_mfma_f32_16x16x32_bf16 v[48:51], v[210:213], v[144:147], v[48:51]
	v_mfma_f32_16x16x32_bf16 v[36:39], v[202:205], v[152:155], v[36:39]
	v_mfma_f32_16x16x32_bf16 v[32:35], v[210:213], v[152:155], v[32:35]
	v_mfma_f32_16x16x32_bf16 v[20:23], v[202:205], v[160:163], v[20:23]
	v_mfma_f32_16x16x32_bf16 v[16:19], v[210:213], v[160:163], v[16:19]
	v_mfma_f32_16x16x32_bf16 v[4:7], v[202:205], v[168:171], v[4:7]
	v_mfma_f32_16x16x32_bf16 v[0:3], v[210:213], v[168:171], v[0:3]
	v_mfma_f32_16x16x32_bf16 v[52:55], v[206:209], v[148:151], v[52:55]
	v_mfma_f32_16x16x32_bf16 v[48:51], v[214:217], v[148:151], v[48:51]
	v_mfma_f32_16x16x32_bf16 v[36:39], v[206:209], v[156:159], v[36:39]
	v_mfma_f32_16x16x32_bf16 v[32:35], v[214:217], v[156:159], v[32:35]
	v_mfma_f32_16x16x32_bf16 v[20:23], v[206:209], v[164:167], v[20:23]
	v_mfma_f32_16x16x32_bf16 v[16:19], v[214:217], v[164:167], v[16:19]
	v_mfma_f32_16x16x32_bf16 v[4:7], v[206:209], v[172:175], v[4:7]
	v_mfma_f32_16x16x32_bf16 v[0:3], v[214:217], v[172:175], v[0:3]
	s_setprio 0
	s_add_i32 s42, s42, 2
	s_add_u32 s35, s35, 0x100
	s_addc_u32 s41, s41, 0
	s_add_u32 s20, s20, 0x100
	s_addc_u32 s21, s21, 0
	s_cmp_gt_u32 s42, 13
	s_barrier
	s_cbranch_scc0 .LBB0_398
	s_nop 7
	s_nop 7
	v_lshl_add_u32 v242, s18, 8, v191
	v_lshl_or_b32 v244, s3, 8, v221
	v_lshlrev_b32_e32 v245, 12, v242
	v_lshl_add_u32 v245, v244, 1, v245
	v_add_u32_e32 v245, 0x4000000, v245
	v_mul_lo_u32 v218, v242, s78
	v_lshlrev_b32_e32 v219, 13, v242
	v_lshl_add_u32 v242, v244, 1, v218
	v_add_u32_e32 v242, 0x4c60, v242
	s_lshl_b32 s19, s2, 12
	v_add_u32_e32 v242, s19, v242
	v_lshl_add_u32 v244, v244, 2, v219
	s_mov_b32 s19, 0xbfb8aa3b
	s_cmp_eq_u32 s2, 0
	s_cbranch_scc1 .Lebr_z0
	s_cmp_eq_u32 s2, 1
	s_cbranch_scc1 .Lebr_z1
	s_branch .Lebr_z2
.Lebr_z0:
	s_add_u32 s20, s4, 0x0
	s_addc_u32 s21, s5, 0
	global_load_dwordx4 v[128:131], v242, s[20:21] offset:0
	global_load_dwordx4 v[132:135], v242, s[20:21] offset:256
	s_add_u32 s20, s4, 0x7e000
	s_addc_u32 s21, s5, 0
	global_load_dwordx4 v[152:155], v242, s[20:21] offset:0
	global_load_dwordx4 v[156:159], v242, s[20:21] offset:256
	s_add_u32 s20, s4, 0xfc000
	s_addc_u32 s21, s5, 0
	global_load_dwordx4 v[202:205], v242, s[20:21] offset:0
	global_load_dwordx4 v[206:209], v242, s[20:21] offset:256
	s_waitcnt vmcnt(4)
	v_and_b32_e32 v218, 0xffff0000, v128
	v_lshlrev_b32_e32 v128, 16, v128
	v_and_b32_e32 v219, 0xffff0000, v129
	v_lshlrev_b32_e32 v129, 16, v129
	v_and_b32_e32 v232, 0xffff0000, v130
	v_lshlrev_b32_e32 v130, 16, v130
	v_and_b32_e32 v233, 0xffff0000, v131
	v_lshlrev_b32_e32 v131, 16, v131
	v_mul_f32_e32 v128, s19, v128
	v_mul_f32_e32 v218, s19, v218
	v_mul_f32_e32 v129, s19, v129
	v_mul_f32_e32 v219, s19, v219
	v_mul_f32_e32 v130, s19, v130
	v_mul_f32_e32 v232, s19, v232
	v_mul_f32_e32 v131, s19, v131
	v_mul_f32_e32 v233, s19, v233
	v_exp_f32_e32 v128, v128
	v_exp_f32_e32 v218, v218
	v_exp_f32_e32 v129, v129
	v_exp_f32_e32 v219, v219
	v_exp_f32_e32 v130, v130
	v_exp_f32_e32 v232, v232
	v_exp_f32_e32 v131, v131
	v_exp_f32_e32 v233, v233
	v_add_f32_e32 v128, 1.0, v128
	v_add_f32_e32 v218, 1.0, v218
	v_add_f32_e32 v129, 1.0, v129
	v_add_f32_e32 v219, 1.0, v219
	v_add_f32_e32 v130, 1.0, v130
	v_add_f32_e32 v232, 1.0, v232
	v_add_f32_e32 v131, 1.0, v131
	v_add_f32_e32 v233, 1.0, v233
	v_rcp_f32_e32 v128, v128
	v_rcp_f32_e32 v218, v218
	v_rcp_f32_e32 v129, v129
	v_rcp_f32_e32 v219, v219
	v_rcp_f32_e32 v130, v130
	v_rcp_f32_e32 v232, v232
	v_rcp_f32_e32 v131, v131
	v_rcp_f32_e32 v233, v233
	v_mul_f32_e32 v124, v124, v128
	v_mul_f32_e32 v125, v125, v218
	v_mul_f32_e32 v126, v126, v129
	v_mul_f32_e32 v127, v127, v219
	v_mul_f32_e32 v120, v120, v130
	v_mul_f32_e32 v121, v121, v232
	v_mul_f32_e32 v122, v122, v131
	v_mul_f32_e32 v123, v123, v233
	v_and_b32_e32 v218, 0xffff0000, v132
	v_lshlrev_b32_e32 v132, 16, v132
	v_and_b32_e32 v219, 0xffff0000, v133
	v_lshlrev_b32_e32 v133, 16, v133
	v_and_b32_e32 v232, 0xffff0000, v134
	v_lshlrev_b32_e32 v134, 16, v134
	v_and_b32_e32 v233, 0xffff0000, v135
; __device__ __forceinline__ float lo16(unsigned u) { return __uint_as_float(u << 16); }
; __device__ __forceinline__ float hi16(unsigned u) { return __uint_as_float(u & 0xffff0000u); }
; __device__ __forceinline__ float sigmoidf_(float x) { return __builtin_amdgcn_rcpf(1.0f + __expf(-x)); }
; __device__ __forceinline__ unsigned cvt_pk_bf16(float lo, float hi) { return pk2(lo, hi); }
;     template <int Z> __device__ __forceinline__ void run(const f32x4 (&acc)[2][2][4][2], const Unit& u, int wr, int wc, int fr, int fq) const {
;     ...
;                 u32x4 graw[2][2]; f32x4 old0[2][2], old1[2][2];
; #pragma unroll
;                 for (int mm = 0; mm < 2; ++mm)
; #pragma unroll
;                     for (int bj = 0; bj < 2; ++bj) { const int row = row0 + ai * HALF + (m2 + mm) * 16, col = col0 + bj * HALF;
;                         graw[mm][bj] = *(const u32x4*)(proj + (size_t)row * NP + C_BR + Z * 2048 + col);
;                         if (Z > 0) { const float* mp = mix + (size_t)row * 2048 + col; old0[mm][bj] = *(const f32x4*)mp; old1[mm][bj] = *(const f32x4*)(mp + 4); } }
; #pragma unroll
;                 for (int mm = 0; mm < 2; ++mm)
; #pragma unroll
;                     for (int bj = 0; bj < 2; ++bj) { const int row = row0 + ai * HALF + (m2 + mm) * 16, col = col0 + bj * HALF;
;                         const u32x4 g = graw[mm][bj];
;                         f32x4 v0 = acc[ai][bj][m2 + mm][0], v1 = acc[ai][bj][m2 + mm][1];
;                         v0[0] *= sigmoidf_(lo16(g.x)); v0[1] *= sigmoidf_(hi16(g.x)); v0[2] *= sigmoidf_(lo16(g.y)); v0[3] *= sigmoidf_(hi16(g.y));
;                         v1[0] *= sigmoidf_(lo16(g.z)); v1[1] *= sigmoidf_(hi16(g.z)); v1[2] *= sigmoidf_(lo16(g.w)); v1[3] *= sigmoidf_(hi16(g.w));
;                         if (Z > 0) { v0 += old0[mm][bj]; v1 += old1[mm][bj]; }
;                         if (Z < 2) { float* mp = mix + (size_t)row * 2048 + col; *(f32x4*)mp = v0; *(f32x4*)(mp + 4) = v1; }
;                         else { u32x4 w; w.x = cvt_pk_bf16(v0[0], v0[1]); w.y = cvt_pk_bf16(v0[2], v0[3]); w.z = cvt_pk_bf16(v1[0], v1[1]); w.w = cvt_pk_bf16(v1[2], v1[3]);
;                             *(u32x4*)(mixb + (size_t)row * 2048 + col) = w; } }
	v_lshlrev_b32_e32 v135, 16, v135
	v_mul_f32_e32 v132, s19, v132
	v_mul_f32_e32 v218, s19, v218
	v_mul_f32_e32 v133, s19, v133
	v_mul_f32_e32 v219, s19, v219
	v_mul_f32_e32 v134, s19, v134
	v_mul_f32_e32 v232, s19, v232
	v_mul_f32_e32 v135, s19, v135
	v_mul_f32_e32 v233, s19, v233
	v_exp_f32_e32 v132, v132
	v_exp_f32_e32 v218, v218
	v_exp_f32_e32 v133, v133
	v_exp_f32_e32 v219, v219
	v_exp_f32_e32 v134, v134
	v_exp_f32_e32 v232, v232
	v_exp_f32_e32 v135, v135
	v_exp_f32_e32 v233, v233
	v_add_f32_e32 v132, 1.0, v132
	v_add_f32_e32 v218, 1.0, v218
	v_add_f32_e32 v133, 1.0, v133
	v_add_f32_e32 v219, 1.0, v219
	v_add_f32_e32 v134, 1.0, v134
	v_add_f32_e32 v232, 1.0, v232
	v_add_f32_e32 v135, 1.0, v135
	v_add_f32_e32 v233, 1.0, v233
	v_rcp_f32_e32 v132, v132
	v_rcp_f32_e32 v218, v218
	v_rcp_f32_e32 v133, v133
	v_rcp_f32_e32 v219, v219
	v_rcp_f32_e32 v134, v134
	v_rcp_f32_e32 v232, v232
	v_rcp_f32_e32 v135, v135
	v_rcp_f32_e32 v233, v233
	v_mul_f32_e32 v116, v116, v132
	v_mul_f32_e32 v117, v117, v218
	v_mul_f32_e32 v118, v118, v133
	v_mul_f32_e32 v119, v119, v219
	v_mul_f32_e32 v112, v112, v134
	v_mul_f32_e32 v113, v113, v232
	v_mul_f32_e32 v114, v114, v135
	v_mul_f32_e32 v115, v115, v233
	s_add_u32 s22, s52, 0x0
	s_addc_u32 s23, s53, 0
	global_store_dwordx4 v244, v[124:127], s[22:23] offset:0
	global_store_dwordx4 v244, v[120:123], s[22:23] offset:16
	global_store_dwordx4 v244, v[116:119], s[22:23] offset:512
	global_store_dwordx4 v244, v[112:115], s[22:23] offset:528
	s_add_u32 s20, s4, 0x17a000
	s_addc_u32 s21, s5, 0
	global_load_dwordx4 v[128:131], v242, s[20:21] offset:0
	global_load_dwordx4 v[132:135], v242, s[20:21] offset:256
	s_waitcnt vmcnt(8)
	v_and_b32_e32 v218, 0xffff0000, v152
	v_lshlrev_b32_e32 v152, 16, v152
	v_and_b32_e32 v219, 0xffff0000, v153
	v_lshlrev_b32_e32 v153, 16, v153
	v_and_b32_e32 v232, 0xffff0000, v154
	v_lshlrev_b32_e32 v154, 16, v154
	v_and_b32_e32 v233, 0xffff0000, v155
	v_lshlrev_b32_e32 v155, 16, v155
	v_mul_f32_e32 v152, s19, v152
	v_mul_f32_e32 v218, s19, v218
	v_mul_f32_e32 v153, s19, v153
	v_mul_f32_e32 v219, s19, v219
	v_mul_f32_e32 v154, s19, v154
	v_mul_f32_e32 v232, s19, v232
	v_mul_f32_e32 v155, s19, v155
	v_mul_f32_e32 v233, s19, v233
	v_exp_f32_e32 v152, v152
	v_exp_f32_e32 v218, v218
	v_exp_f32_e32 v153, v153
	v_exp_f32_e32 v219, v219
	v_exp_f32_e32 v154, v154
	v_exp_f32_e32 v232, v232
	v_exp_f32_e32 v155, v155
	v_exp_f32_e32 v233, v233
	v_add_f32_e32 v152, 1.0, v152
	v_add_f32_e32 v218, 1.0, v218
	v_add_f32_e32 v153, 1.0, v153
	v_add_f32_e32 v219, 1.0, v219
	v_add_f32_e32 v154, 1.0, v154
	v_add_f32_e32 v232, 1.0, v232
	v_add_f32_e32 v155, 1.0, v155
	v_add_f32_e32 v233, 1.0, v233
	v_rcp_f32_e32 v152, v152
	v_rcp_f32_e32 v218, v218
	v_rcp_f32_e32 v153, v153
	v_rcp_f32_e32 v219, v219
	v_rcp_f32_e32 v154, v154
	v_rcp_f32_e32 v232, v232
	v_rcp_f32_e32 v155, v155
	v_rcp_f32_e32 v233, v233
	v_mul_f32_e32 v108, v108, v152
	v_mul_f32_e32 v109, v109, v218
	v_mul_f32_e32 v110, v110, v153
	v_mul_f32_e32 v111, v111, v219
	v_mul_f32_e32 v104, v104, v154
	v_mul_f32_e32 v105, v105, v232
	v_mul_f32_e32 v106, v106, v155
	v_mul_f32_e32 v107, v107, v233
	v_and_b32_e32 v218, 0xffff0000, v156
	v_lshlrev_b32_e32 v156, 16, v156
	v_and_b32_e32 v219, 0xffff0000, v157
	v_lshlrev_b32_e32 v157, 16, v157
	v_and_b32_e32 v232, 0xffff0000, v158
	v_lshlrev_b32_e32 v158, 16, v158
	v_and_b32_e32 v233, 0xffff0000, v159
	v_lshlrev_b32_e32 v159, 16, v159
	v_mul_f32_e32 v156, s19, v156
	v_mul_f32_e32 v218, s19, v218
	v_mul_f32_e32 v157, s19, v157
	v_mul_f32_e32 v219, s19, v219
	v_mul_f32_e32 v158, s19, v158
	v_mul_f32_e32 v232, s19, v232
	v_mul_f32_e32 v159, s19, v159
	v_mul_f32_e32 v233, s19, v233
	v_exp_f32_e32 v156, v156
	v_exp_f32_e32 v218, v218
	v_exp_f32_e32 v157, v157
	v_exp_f32_e32 v219, v219
	v_exp_f32_e32 v158, v158
	v_exp_f32_e32 v232, v232
	v_exp_f32_e32 v159, v159
	v_exp_f32_e32 v233, v233
	v_add_f32_e32 v156, 1.0, v156
	v_add_f32_e32 v218, 1.0, v218
	v_add_f32_e32 v157, 1.0, v157
	v_add_f32_e32 v219, 1.0, v219
	v_add_f32_e32 v158, 1.0, v158
	v_add_f32_e32 v232, 1.0, v232
	v_add_f32_e32 v159, 1.0, v159
	v_add_f32_e32 v233, 1.0, v233
	v_rcp_f32_e32 v156, v156
	v_rcp_f32_e32 v218, v218
	v_rcp_f32_e32 v157, v157
	v_rcp_f32_e32 v219, v219
	v_rcp_f32_e32 v158, v158
	v_rcp_f32_e32 v232, v232
	v_rcp_f32_e32 v159, v159
	v_rcp_f32_e32 v233, v233
	v_mul_f32_e32 v100, v100, v156
	v_mul_f32_e32 v101, v101, v218
	v_mul_f32_e32 v102, v102, v157
	v_mul_f32_e32 v103, v103, v219
	v_mul_f32_e32 v96, v96, v158
	v_mul_f32_e32 v97, v97, v232
	v_mul_f32_e32 v98, v98, v159
	v_mul_f32_e32 v99, v99, v233
	s_add_u32 s22, s52, 0x20000
	s_addc_u32 s23, s53, 0
	global_store_dwordx4 v244, v[108:111], s[22:23] offset:0
	global_store_dwordx4 v244, v[104:107], s[22:23] offset:16
	global_store_dwordx4 v244, v[100:103], s[22:23] offset:512
	global_store_dwordx4 v244, v[96:99], s[22:23] offset:528
	s_add_u32 s20, s4, 0x3f0000
	s_addc_u32 s21, s5, 0
	global_load_dwordx4 v[152:155], v242, s[20:21] offset:0
	global_load_dwordx4 v[156:159], v242, s[20:21] offset:256
	s_waitcnt vmcnt(12)
; __device__ __forceinline__ float lo16(unsigned u) { return __uint_as_float(u << 16); }
; __device__ __forceinline__ float hi16(unsigned u) { return __uint_as_float(u & 0xffff0000u); }
; __device__ __forceinline__ float sigmoidf_(float x) { return __builtin_amdgcn_rcpf(1.0f + __expf(-x)); }
; __device__ __forceinline__ unsigned cvt_pk_bf16(float lo, float hi) { return pk2(lo, hi); }
;     template <int Z> __device__ __forceinline__ void run(const f32x4 (&acc)[2][2][4][2], const Unit& u, int wr, int wc, int fr, int fq) const {
;     ...
;                 u32x4 graw[2][2]; f32x4 old0[2][2], old1[2][2];
; #pragma unroll
;                 for (int mm = 0; mm < 2; ++mm)
; #pragma unroll
;                     for (int bj = 0; bj < 2; ++bj) { const int row = row0 + ai * HALF + (m2 + mm) * 16, col = col0 + bj * HALF;
;                         graw[mm][bj] = *(const u32x4*)(proj + (size_t)row * NP + C_BR + Z * 2048 + col);
;                         if (Z > 0) { const float* mp = mix + (size_t)row * 2048 + col; old0[mm][bj] = *(const f32x4*)mp; old1[mm][bj] = *(const f32x4*)(mp + 4); } }
; #pragma unroll
;                 for (int mm = 0; mm < 2; ++mm)
; #pragma unroll
;                     for (int bj = 0; bj < 2; ++bj) { const int row = row0 + ai * HALF + (m2 + mm) * 16, col = col0 + bj * HALF;
;                         const u32x4 g = graw[mm][bj];
;                         f32x4 v0 = acc[ai][bj][m2 + mm][0], v1 = acc[ai][bj][m2 + mm][1];
;                         v0[0] *= sigmoidf_(lo16(g.x)); v0[1] *= sigmoidf_(hi16(g.x)); v0[2] *= sigmoidf_(lo16(g.y)); v0[3] *= sigmoidf_(hi16(g.y));
;                         v1[0] *= sigmoidf_(lo16(g.z)); v1[1] *= sigmoidf_(hi16(g.z)); v1[2] *= sigmoidf_(lo16(g.w)); v1[3] *= sigmoidf_(hi16(g.w));
;                         if (Z > 0) { v0 += old0[mm][bj]; v1 += old1[mm][bj]; }
;                         if (Z < 2) { float* mp = mix + (size_t)row * 2048 + col; *(f32x4*)mp = v0; *(f32x4*)(mp + 4) = v1; }
;                         else { u32x4 w; w.x = cvt_pk_bf16(v0[0], v0[1]); w.y = cvt_pk_bf16(v0[2], v0[3]); w.z = cvt_pk_bf16(v1[0], v1[1]); w.w = cvt_pk_bf16(v1[2], v1[3]);
;                             *(u32x4*)(mixb + (size_t)row * 2048 + col) = w; } }
	v_and_b32_e32 v218, 0xffff0000, v202
	v_lshlrev_b32_e32 v202, 16, v202
	v_and_b32_e32 v219, 0xffff0000, v203
	v_lshlrev_b32_e32 v203, 16, v203
	v_and_b32_e32 v232, 0xffff0000, v204
	v_lshlrev_b32_e32 v204, 16, v204
	v_and_b32_e32 v233, 0xffff0000, v205
	v_lshlrev_b32_e32 v205, 16, v205
	v_mul_f32_e32 v202, s19, v202
	v_mul_f32_e32 v218, s19, v218
	v_mul_f32_e32 v203, s19, v203
	v_mul_f32_e32 v219, s19, v219
	v_mul_f32_e32 v204, s19, v204
	v_mul_f32_e32 v232, s19, v232
	v_mul_f32_e32 v205, s19, v205
	v_mul_f32_e32 v233, s19, v233
	v_exp_f32_e32 v202, v202
	v_exp_f32_e32 v218, v218
	v_exp_f32_e32 v203, v203
	v_exp_f32_e32 v219, v219
	v_exp_f32_e32 v204, v204
	v_exp_f32_e32 v232, v232
	v_exp_f32_e32 v205, v205
	v_exp_f32_e32 v233, v233
	v_add_f32_e32 v202, 1.0, v202
	v_add_f32_e32 v218, 1.0, v218
	v_add_f32_e32 v203, 1.0, v203
	v_add_f32_e32 v219, 1.0, v219
	v_add_f32_e32 v204, 1.0, v204
	v_add_f32_e32 v232, 1.0, v232
	v_add_f32_e32 v205, 1.0, v205
	v_add_f32_e32 v233, 1.0, v233
	v_rcp_f32_e32 v202, v202
	v_rcp_f32_e32 v218, v218
	v_rcp_f32_e32 v203, v203
	v_rcp_f32_e32 v219, v219
	v_rcp_f32_e32 v204, v204
	v_rcp_f32_e32 v232, v232
	v_rcp_f32_e32 v205, v205
	v_rcp_f32_e32 v233, v233
	v_mul_f32_e32 v92, v92, v202
	v_mul_f32_e32 v93, v93, v218
	v_mul_f32_e32 v94, v94, v203
	v_mul_f32_e32 v95, v95, v219
	v_mul_f32_e32 v88, v88, v204
	v_mul_f32_e32 v89, v89, v232
	v_mul_f32_e32 v90, v90, v205
	v_mul_f32_e32 v91, v91, v233
	v_and_b32_e32 v218, 0xffff0000, v206
	v_lshlrev_b32_e32 v206, 16, v206
	v_and_b32_e32 v219, 0xffff0000, v207
	v_lshlrev_b32_e32 v207, 16, v207
	v_and_b32_e32 v232, 0xffff0000, v208
	v_lshlrev_b32_e32 v208, 16, v208
	v_and_b32_e32 v233, 0xffff0000, v209
	v_lshlrev_b32_e32 v209, 16, v209
	v_mul_f32_e32 v206, s19, v206
	v_mul_f32_e32 v218, s19, v218
	v_mul_f32_e32 v207, s19, v207
	v_mul_f32_e32 v219, s19, v219
	v_mul_f32_e32 v208, s19, v208
	v_mul_f32_e32 v232, s19, v232
	v_mul_f32_e32 v209, s19, v209
	v_mul_f32_e32 v233, s19, v233
	v_exp_f32_e32 v206, v206
	v_exp_f32_e32 v218, v218
	v_exp_f32_e32 v207, v207
	v_exp_f32_e32 v219, v219
	v_exp_f32_e32 v208, v208
	v_exp_f32_e32 v232, v232
	v_exp_f32_e32 v209, v209
	v_exp_f32_e32 v233, v233
	v_add_f32_e32 v206, 1.0, v206
	v_add_f32_e32 v218, 1.0, v218
	v_add_f32_e32 v207, 1.0, v207
	v_add_f32_e32 v219, 1.0, v219
	v_add_f32_e32 v208, 1.0, v208
	v_add_f32_e32 v232, 1.0, v232
	v_add_f32_e32 v209, 1.0, v209
	v_add_f32_e32 v233, 1.0, v233
	v_rcp_f32_e32 v206, v206
	v_rcp_f32_e32 v218, v218
	v_rcp_f32_e32 v207, v207
	v_rcp_f32_e32 v219, v219
	v_rcp_f32_e32 v208, v208
	v_rcp_f32_e32 v232, v232
	v_rcp_f32_e32 v209, v209
	v_rcp_f32_e32 v233, v233
	v_mul_f32_e32 v84, v84, v206
	v_mul_f32_e32 v85, v85, v218
	v_mul_f32_e32 v86, v86, v207
	v_mul_f32_e32 v87, v87, v219
	v_mul_f32_e32 v80, v80, v208
	v_mul_f32_e32 v81, v81, v232
	v_mul_f32_e32 v82, v82, v209
	v_mul_f32_e32 v83, v83, v233
	s_add_u32 s22, s52, 0x40000
	s_addc_u32 s23, s53, 0
	global_store_dwordx4 v244, v[92:95], s[22:23] offset:0
	global_store_dwordx4 v244, v[88:91], s[22:23] offset:16
	global_store_dwordx4 v244, v[84:87], s[22:23] offset:512
	global_store_dwordx4 v244, v[80:83], s[22:23] offset:528
	s_add_u32 s20, s4, 0x46e000
	s_addc_u32 s21, s5, 0
	global_load_dwordx4 v[202:205], v242, s[20:21] offset:0
	global_load_dwordx4 v[206:209], v242, s[20:21] offset:256
	s_waitcnt vmcnt(12)
	v_and_b32_e32 v218, 0xffff0000, v128
	v_lshlrev_b32_e32 v128, 16, v128
	v_and_b32_e32 v219, 0xffff0000, v129
	v_lshlrev_b32_e32 v129, 16, v129
	v_and_b32_e32 v232, 0xffff0000, v130
	v_lshlrev_b32_e32 v130, 16, v130
	v_and_b32_e32 v233, 0xffff0000, v131
	v_lshlrev_b32_e32 v131, 16, v131
	v_mul_f32_e32 v128, s19, v128
	v_mul_f32_e32 v218, s19, v218
	v_mul_f32_e32 v129, s19, v129
	v_mul_f32_e32 v219, s19, v219
	v_mul_f32_e32 v130, s19, v130
	v_mul_f32_e32 v232, s19, v232
	v_mul_f32_e32 v131, s19, v131
	v_mul_f32_e32 v233, s19, v233
	v_exp_f32_e32 v128, v128
	v_exp_f32_e32 v218, v218
	v_exp_f32_e32 v129, v129
	v_exp_f32_e32 v219, v219
	v_exp_f32_e32 v130, v130
	v_exp_f32_e32 v232, v232
	v_exp_f32_e32 v131, v131
	v_exp_f32_e32 v233, v233
	v_add_f32_e32 v128, 1.0, v128
	v_add_f32_e32 v218, 1.0, v218
	v_add_f32_e32 v129, 1.0, v129
	v_add_f32_e32 v219, 1.0, v219
	v_add_f32_e32 v130, 1.0, v130
	v_add_f32_e32 v232, 1.0, v232
	v_add_f32_e32 v131, 1.0, v131
	v_add_f32_e32 v233, 1.0, v233
	v_rcp_f32_e32 v128, v128
	v_rcp_f32_e32 v218, v218
	v_rcp_f32_e32 v129, v129
	v_rcp_f32_e32 v219, v219
	v_rcp_f32_e32 v130, v130
	v_rcp_f32_e32 v232, v232
	v_rcp_f32_e32 v131, v131
	v_rcp_f32_e32 v233, v233
	v_mul_f32_e32 v76, v76, v128
	v_mul_f32_e32 v77, v77, v218
	v_mul_f32_e32 v78, v78, v129
	v_mul_f32_e32 v79, v79, v219
	v_mul_f32_e32 v72, v72, v130
	v_mul_f32_e32 v73, v73, v232
	v_mul_f32_e32 v74, v74, v131
	v_mul_f32_e32 v75, v75, v233
	v_and_b32_e32 v218, 0xffff0000, v132
	v_lshlrev_b32_e32 v132, 16, v132
	v_and_b32_e32 v219, 0xffff0000, v133
	v_lshlrev_b32_e32 v133, 16, v133
	v_and_b32_e32 v232, 0xffff0000, v134
	v_lshlrev_b32_e32 v134, 16, v134
	v_and_b32_e32 v233, 0xffff0000, v135
	v_lshlrev_b32_e32 v135, 16, v135
	v_mul_f32_e32 v132, s19, v132
	v_mul_f32_e32 v218, s19, v218
	v_mul_f32_e32 v133, s19, v133
	v_mul_f32_e32 v219, s19, v219
	v_mul_f32_e32 v134, s19, v134
	v_mul_f32_e32 v232, s19, v232
	v_mul_f32_e32 v135, s19, v135
	v_mul_f32_e32 v233, s19, v233
	v_exp_f32_e32 v132, v132
	v_exp_f32_e32 v218, v218
	v_exp_f32_e32 v133, v133
	v_exp_f32_e32 v219, v219
	v_exp_f32_e32 v134, v134
	v_exp_f32_e32 v232, v232
	v_exp_f32_e32 v135, v135
	v_exp_f32_e32 v233, v233
	v_add_f32_e32 v132, 1.0, v132
	v_add_f32_e32 v218, 1.0, v218
	v_add_f32_e32 v133, 1.0, v133
	v_add_f32_e32 v219, 1.0, v219
	v_add_f32_e32 v134, 1.0, v134
	v_add_f32_e32 v232, 1.0, v232
	v_add_f32_e32 v135, 1.0, v135
	v_add_f32_e32 v233, 1.0, v233
	v_rcp_f32_e32 v132, v132
	v_rcp_f32_e32 v218, v218
	v_rcp_f32_e32 v133, v133
	v_rcp_f32_e32 v219, v219
	v_rcp_f32_e32 v134, v134
	v_rcp_f32_e32 v232, v232
	v_rcp_f32_e32 v135, v135
	v_rcp_f32_e32 v233, v233
	v_mul_f32_e32 v68, v68, v132
	v_mul_f32_e32 v69, v69, v218
	v_mul_f32_e32 v70, v70, v133
	v_mul_f32_e32 v71, v71, v219
	v_mul_f32_e32 v64, v64, v134
	v_mul_f32_e32 v65, v65, v232
	v_mul_f32_e32 v66, v66, v135
	v_mul_f32_e32 v67, v67, v233
	s_add_u32 s22, s52, 0x60000
	s_addc_u32 s23, s53, 0
	global_store_dwordx4 v244, v[76:79], s[22:23] offset:0
	global_store_dwordx4 v244, v[72:75], s[22:23] offset:16
	global_store_dwordx4 v244, v[68:71], s[22:23] offset:512
	global_store_dwordx4 v244, v[64:67], s[22:23] offset:528
	s_add_u32 s20, s4, 0x4ec000
	s_addc_u32 s21, s5, 0
	global_load_dwordx4 v[128:131], v242, s[20:21] offset:0
	global_load_dwordx4 v[132:135], v242, s[20:21] offset:256
	s_waitcnt vmcnt(12)
; __device__ __forceinline__ float lo16(unsigned u) { return __uint_as_float(u << 16); }
; __device__ __forceinline__ float hi16(unsigned u) { return __uint_as_float(u & 0xffff0000u); }
; __device__ __forceinline__ float sigmoidf_(float x) { return __builtin_amdgcn_rcpf(1.0f + __expf(-x)); }
; __device__ __forceinline__ unsigned cvt_pk_bf16(float lo, float hi) { return pk2(lo, hi); }
;     template <int Z> __device__ __forceinline__ void run(const f32x4 (&acc)[2][2][4][2], const Unit& u, int wr, int wc, int fr, int fq) const {
;     ...
;                 u32x4 graw[2][2]; f32x4 old0[2][2], old1[2][2];
; #pragma unroll
;                 for (int mm = 0; mm < 2; ++mm)
; #pragma unroll
;                     for (int bj = 0; bj < 2; ++bj) { const int row = row0 + ai * HALF + (m2 + mm) * 16, col = col0 + bj * HALF;
;                         graw[mm][bj] = *(const u32x4*)(proj + (size_t)row * NP + C_BR + Z * 2048 + col);
;                         if (Z > 0) { const float* mp = mix + (size_t)row * 2048 + col; old0[mm][bj] = *(const f32x4*)mp; old1[mm][bj] = *(const f32x4*)(mp + 4); } }
; #pragma unroll
;                 for (int mm = 0; mm < 2; ++mm)
; #pragma unroll
;                     for (int bj = 0; bj < 2; ++bj) { const int row = row0 + ai * HALF + (m2 + mm) * 16, col = col0 + bj * HALF;
;                         const u32x4 g = graw[mm][bj];
;                         f32x4 v0 = acc[ai][bj][m2 + mm][0], v1 = acc[ai][bj][m2 + mm][1];
;                         v0[0] *= sigmoidf_(lo16(g.x)); v0[1] *= sigmoidf_(hi16(g.x)); v0[2] *= sigmoidf_(lo16(g.y)); v0[3] *= sigmoidf_(hi16(g.y));
;                         v1[0] *= sigmoidf_(lo16(g.z)); v1[1] *= sigmoidf_(hi16(g.z)); v1[2] *= sigmoidf_(lo16(g.w)); v1[3] *= sigmoidf_(hi16(g.w));
;                         if (Z > 0) { v0 += old0[mm][bj]; v1 += old1[mm][bj]; }
;                         if (Z < 2) { float* mp = mix + (size_t)row * 2048 + col; *(f32x4*)mp = v0; *(f32x4*)(mp + 4) = v1; }
;                         else { u32x4 w; w.x = cvt_pk_bf16(v0[0], v0[1]); w.y = cvt_pk_bf16(v0[2], v0[3]); w.z = cvt_pk_bf16(v1[0], v1[1]); w.w = cvt_pk_bf16(v1[2], v1[3]);
;                             *(u32x4*)(mixb + (size_t)row * 2048 + col) = w; } }
	v_and_b32_e32 v218, 0xffff0000, v152
	v_lshlrev_b32_e32 v152, 16, v152
	v_and_b32_e32 v219, 0xffff0000, v153
	v_lshlrev_b32_e32 v153, 16, v153
	v_and_b32_e32 v232, 0xffff0000, v154
	v_lshlrev_b32_e32 v154, 16, v154
	v_and_b32_e32 v233, 0xffff0000, v155
	v_lshlrev_b32_e32 v155, 16, v155
	v_mul_f32_e32 v152, s19, v152
	v_mul_f32_e32 v218, s19, v218
	v_mul_f32_e32 v153, s19, v153
	v_mul_f32_e32 v219, s19, v219
	v_mul_f32_e32 v154, s19, v154
	v_mul_f32_e32 v232, s19, v232
	v_mul_f32_e32 v155, s19, v155
	v_mul_f32_e32 v233, s19, v233
	v_exp_f32_e32 v152, v152
	v_exp_f32_e32 v218, v218
	v_exp_f32_e32 v153, v153
	v_exp_f32_e32 v219, v219
	v_exp_f32_e32 v154, v154
	v_exp_f32_e32 v232, v232
	v_exp_f32_e32 v155, v155
	v_exp_f32_e32 v233, v233
	v_add_f32_e32 v152, 1.0, v152
	v_add_f32_e32 v218, 1.0, v218
	v_add_f32_e32 v153, 1.0, v153
	v_add_f32_e32 v219, 1.0, v219
	v_add_f32_e32 v154, 1.0, v154
	v_add_f32_e32 v232, 1.0, v232
	v_add_f32_e32 v155, 1.0, v155
	v_add_f32_e32 v233, 1.0, v233
	v_rcp_f32_e32 v152, v152
	v_rcp_f32_e32 v218, v218
	v_rcp_f32_e32 v153, v153
	v_rcp_f32_e32 v219, v219
	v_rcp_f32_e32 v154, v154
	v_rcp_f32_e32 v232, v232
	v_rcp_f32_e32 v155, v155
	v_rcp_f32_e32 v233, v233
	v_mul_f32_e32 v60, v60, v152
	v_mul_f32_e32 v61, v61, v218
	v_mul_f32_e32 v62, v62, v153
	v_mul_f32_e32 v63, v63, v219
	v_mul_f32_e32 v56, v56, v154
	v_mul_f32_e32 v57, v57, v232
	v_mul_f32_e32 v58, v58, v155
	v_mul_f32_e32 v59, v59, v233
	v_and_b32_e32 v218, 0xffff0000, v156
	v_lshlrev_b32_e32 v156, 16, v156
	v_and_b32_e32 v219, 0xffff0000, v157
	v_lshlrev_b32_e32 v157, 16, v157
	v_and_b32_e32 v232, 0xffff0000, v158
	v_lshlrev_b32_e32 v158, 16, v158
	v_and_b32_e32 v233, 0xffff0000, v159
	v_lshlrev_b32_e32 v159, 16, v159
	v_mul_f32_e32 v156, s19, v156
	v_mul_f32_e32 v218, s19, v218
	v_mul_f32_e32 v157, s19, v157
	v_mul_f32_e32 v219, s19, v219
	v_mul_f32_e32 v158, s19, v158
	v_mul_f32_e32 v232, s19, v232
	v_mul_f32_e32 v159, s19, v159
	v_mul_f32_e32 v233, s19, v233
	v_exp_f32_e32 v156, v156
	v_exp_f32_e32 v218, v218
	v_exp_f32_e32 v157, v157
	v_exp_f32_e32 v219, v219
	v_exp_f32_e32 v158, v158
	v_exp_f32_e32 v232, v232
	v_exp_f32_e32 v159, v159
	v_exp_f32_e32 v233, v233
	v_add_f32_e32 v156, 1.0, v156
	v_add_f32_e32 v218, 1.0, v218
	v_add_f32_e32 v157, 1.0, v157
	v_add_f32_e32 v219, 1.0, v219
	v_add_f32_e32 v158, 1.0, v158
	v_add_f32_e32 v232, 1.0, v232
	v_add_f32_e32 v159, 1.0, v159
	v_add_f32_e32 v233, 1.0, v233
	v_rcp_f32_e32 v156, v156
	v_rcp_f32_e32 v218, v218
	v_rcp_f32_e32 v157, v157
	v_rcp_f32_e32 v219, v219
	v_rcp_f32_e32 v158, v158
	v_rcp_f32_e32 v232, v232
	v_rcp_f32_e32 v159, v159
	v_rcp_f32_e32 v233, v233
	v_mul_f32_e32 v52, v52, v156
	v_mul_f32_e32 v53, v53, v218
	v_mul_f32_e32 v54, v54, v157
	v_mul_f32_e32 v55, v55, v219
	v_mul_f32_e32 v48, v48, v158
	v_mul_f32_e32 v49, v49, v232
	v_mul_f32_e32 v50, v50, v159
	v_mul_f32_e32 v51, v51, v233
	s_add_u32 s22, s52, 0x100000
	s_addc_u32 s23, s53, 0
	global_store_dwordx4 v244, v[60:63], s[22:23] offset:0
	global_store_dwordx4 v244, v[56:59], s[22:23] offset:16
	global_store_dwordx4 v244, v[52:55], s[22:23] offset:512
	global_store_dwordx4 v244, v[48:51], s[22:23] offset:528
	s_add_u32 s20, s4, 0x56a000
	s_addc_u32 s21, s5, 0
	global_load_dwordx4 v[152:155], v242, s[20:21] offset:0
	global_load_dwordx4 v[156:159], v242, s[20:21] offset:256
	s_waitcnt vmcnt(12)
	v_and_b32_e32 v218, 0xffff0000, v202
	v_lshlrev_b32_e32 v202, 16, v202
	v_and_b32_e32 v219, 0xffff0000, v203
	v_lshlrev_b32_e32 v203, 16, v203
	v_and_b32_e32 v232, 0xffff0000, v204
	v_lshlrev_b32_e32 v204, 16, v204
	v_and_b32_e32 v233, 0xffff0000, v205
	v_lshlrev_b32_e32 v205, 16, v205
	v_mul_f32_e32 v202, s19, v202
	v_mul_f32_e32 v218, s19, v218
	v_mul_f32_e32 v203, s19, v203
	v_mul_f32_e32 v219, s19, v219
	v_mul_f32_e32 v204, s19, v204
	v_mul_f32_e32 v232, s19, v232
	v_mul_f32_e32 v205, s19, v205
	v_mul_f32_e32 v233, s19, v233
	v_exp_f32_e32 v202, v202
	v_exp_f32_e32 v218, v218
	v_exp_f32_e32 v203, v203
	v_exp_f32_e32 v219, v219
	v_exp_f32_e32 v204, v204
	v_exp_f32_e32 v232, v232
	v_exp_f32_e32 v205, v205
	v_exp_f32_e32 v233, v233
	v_add_f32_e32 v202, 1.0, v202
	v_add_f32_e32 v218, 1.0, v218
	v_add_f32_e32 v203, 1.0, v203
	v_add_f32_e32 v219, 1.0, v219
	v_add_f32_e32 v204, 1.0, v204
	v_add_f32_e32 v232, 1.0, v232
	v_add_f32_e32 v205, 1.0, v205
	v_add_f32_e32 v233, 1.0, v233
	v_rcp_f32_e32 v202, v202
	v_rcp_f32_e32 v218, v218
	v_rcp_f32_e32 v203, v203
	v_rcp_f32_e32 v219, v219
	v_rcp_f32_e32 v204, v204
	v_rcp_f32_e32 v232, v232
	v_rcp_f32_e32 v205, v205
	v_rcp_f32_e32 v233, v233
	v_mul_f32_e32 v44, v44, v202
	v_mul_f32_e32 v45, v45, v218
	v_mul_f32_e32 v46, v46, v203
	v_mul_f32_e32 v47, v47, v219
	v_mul_f32_e32 v40, v40, v204
	v_mul_f32_e32 v41, v41, v232
	v_mul_f32_e32 v42, v42, v205
	v_mul_f32_e32 v43, v43, v233
	v_and_b32_e32 v218, 0xffff0000, v206
	v_lshlrev_b32_e32 v206, 16, v206
	v_and_b32_e32 v219, 0xffff0000, v207
	v_lshlrev_b32_e32 v207, 16, v207
	v_and_b32_e32 v232, 0xffff0000, v208
	v_lshlrev_b32_e32 v208, 16, v208
	v_and_b32_e32 v233, 0xffff0000, v209
	v_lshlrev_b32_e32 v209, 16, v209
	v_mul_f32_e32 v206, s19, v206
	v_mul_f32_e32 v218, s19, v218
	v_mul_f32_e32 v207, s19, v207
	v_mul_f32_e32 v219, s19, v219
	v_mul_f32_e32 v208, s19, v208
	v_mul_f32_e32 v232, s19, v232
	v_mul_f32_e32 v209, s19, v209
	v_mul_f32_e32 v233, s19, v233
	v_exp_f32_e32 v206, v206
	v_exp_f32_e32 v218, v218
	v_exp_f32_e32 v207, v207
	v_exp_f32_e32 v219, v219
	v_exp_f32_e32 v208, v208
	v_exp_f32_e32 v232, v232
	v_exp_f32_e32 v209, v209
	v_exp_f32_e32 v233, v233
	v_add_f32_e32 v206, 1.0, v206
	v_add_f32_e32 v218, 1.0, v218
	v_add_f32_e32 v207, 1.0, v207
	v_add_f32_e32 v219, 1.0, v219
	v_add_f32_e32 v208, 1.0, v208
	v_add_f32_e32 v232, 1.0, v232
	v_add_f32_e32 v209, 1.0, v209
	v_add_f32_e32 v233, 1.0, v233
	v_rcp_f32_e32 v206, v206
	v_rcp_f32_e32 v218, v218
	v_rcp_f32_e32 v207, v207
	v_rcp_f32_e32 v219, v219
	v_rcp_f32_e32 v208, v208
	v_rcp_f32_e32 v232, v232
	v_rcp_f32_e32 v209, v209
	v_rcp_f32_e32 v233, v233
	v_mul_f32_e32 v36, v36, v206
	v_mul_f32_e32 v37, v37, v218
	v_mul_f32_e32 v38, v38, v207
	v_mul_f32_e32 v39, v39, v219
	v_mul_f32_e32 v32, v32, v208
	v_mul_f32_e32 v33, v33, v232
	v_mul_f32_e32 v34, v34, v209
	v_mul_f32_e32 v35, v35, v233
	s_add_u32 s22, s52, 0x120000
	s_addc_u32 s23, s53, 0
	global_store_dwordx4 v244, v[44:47], s[22:23] offset:0
	global_store_dwordx4 v244, v[40:43], s[22:23] offset:16
	global_store_dwordx4 v244, v[36:39], s[22:23] offset:512
	global_store_dwordx4 v244, v[32:35], s[22:23] offset:528
	s_waitcnt vmcnt(10)
; __device__ __forceinline__ float lo16(unsigned u) { return __uint_as_float(u << 16); }
; __device__ __forceinline__ float hi16(unsigned u) { return __uint_as_float(u & 0xffff0000u); }
; __device__ __forceinline__ float sigmoidf_(float x) { return __builtin_amdgcn_rcpf(1.0f + __expf(-x)); }
; __device__ __forceinline__ unsigned cvt_pk_bf16(float lo, float hi) { return pk2(lo, hi); }
;     template <int Z> __device__ __forceinline__ void run(const f32x4 (&acc)[2][2][4][2], const Unit& u, int wr, int wc, int fr, int fq) const {
;     ...
;                 u32x4 graw[2][2]; f32x4 old0[2][2], old1[2][2];
; #pragma unroll
;                 for (int mm = 0; mm < 2; ++mm)
; #pragma unroll
;                     for (int bj = 0; bj < 2; ++bj) { const int row = row0 + ai * HALF + (m2 + mm) * 16, col = col0 + bj * HALF;
;                         graw[mm][bj] = *(const u32x4*)(proj + (size_t)row * NP + C_BR + Z * 2048 + col);
;                         if (Z > 0) { const float* mp = mix + (size_t)row * 2048 + col; old0[mm][bj] = *(const f32x4*)mp; old1[mm][bj] = *(const f32x4*)(mp + 4); } }
; #pragma unroll
;                 for (int mm = 0; mm < 2; ++mm)
; #pragma unroll
;                     for (int bj = 0; bj < 2; ++bj) { const int row = row0 + ai * HALF + (m2 + mm) * 16, col = col0 + bj * HALF;
;                         const u32x4 g = graw[mm][bj];
;                         f32x4 v0 = acc[ai][bj][m2 + mm][0], v1 = acc[ai][bj][m2 + mm][1];
;                         v0[0] *= sigmoidf_(lo16(g.x)); v0[1] *= sigmoidf_(hi16(g.x)); v0[2] *= sigmoidf_(lo16(g.y)); v0[3] *= sigmoidf_(hi16(g.y));
;                         v1[0] *= sigmoidf_(lo16(g.z)); v1[1] *= sigmoidf_(hi16(g.z)); v1[2] *= sigmoidf_(lo16(g.w)); v1[3] *= sigmoidf_(hi16(g.w));
;                         if (Z > 0) { v0 += old0[mm][bj]; v1 += old1[mm][bj]; }
;                         if (Z < 2) { float* mp = mix + (size_t)row * 2048 + col; *(f32x4*)mp = v0; *(f32x4*)(mp + 4) = v1; }
;                         else { u32x4 w; w.x = cvt_pk_bf16(v0[0], v0[1]); w.y = cvt_pk_bf16(v0[2], v0[3]); w.z = cvt_pk_bf16(v1[0], v1[1]); w.w = cvt_pk_bf16(v1[2], v1[3]);
;                             *(u32x4*)(mixb + (size_t)row * 2048 + col) = w; } }
	v_and_b32_e32 v218, 0xffff0000, v128
	v_lshlrev_b32_e32 v128, 16, v128
	v_and_b32_e32 v219, 0xffff0000, v129
	v_lshlrev_b32_e32 v129, 16, v129
	v_and_b32_e32 v232, 0xffff0000, v130
	v_lshlrev_b32_e32 v130, 16, v130
	v_and_b32_e32 v233, 0xffff0000, v131
	v_lshlrev_b32_e32 v131, 16, v131
	v_mul_f32_e32 v128, s19, v128
	v_mul_f32_e32 v218, s19, v218
	v_mul_f32_e32 v129, s19, v129
	v_mul_f32_e32 v219, s19, v219
	v_mul_f32_e32 v130, s19, v130
	v_mul_f32_e32 v232, s19, v232
	v_mul_f32_e32 v131, s19, v131
	v_mul_f32_e32 v233, s19, v233
	v_exp_f32_e32 v128, v128
	v_exp_f32_e32 v218, v218
	v_exp_f32_e32 v129, v129
	v_exp_f32_e32 v219, v219
	v_exp_f32_e32 v130, v130
	v_exp_f32_e32 v232, v232
	v_exp_f32_e32 v131, v131
	v_exp_f32_e32 v233, v233
	v_add_f32_e32 v128, 1.0, v128
	v_add_f32_e32 v218, 1.0, v218
	v_add_f32_e32 v129, 1.0, v129
	v_add_f32_e32 v219, 1.0, v219
	v_add_f32_e32 v130, 1.0, v130
	v_add_f32_e32 v232, 1.0, v232
	v_add_f32_e32 v131, 1.0, v131
	v_add_f32_e32 v233, 1.0, v233
	v_rcp_f32_e32 v128, v128
	v_rcp_f32_e32 v218, v218
	v_rcp_f32_e32 v129, v129
	v_rcp_f32_e32 v219, v219
	v_rcp_f32_e32 v130, v130
	v_rcp_f32_e32 v232, v232
	v_rcp_f32_e32 v131, v131
	v_rcp_f32_e32 v233, v233
	v_mul_f32_e32 v28, v28, v128
	v_mul_f32_e32 v29, v29, v218
	v_mul_f32_e32 v30, v30, v129
	v_mul_f32_e32 v31, v31, v219
	v_mul_f32_e32 v24, v24, v130
	v_mul_f32_e32 v25, v25, v232
	v_mul_f32_e32 v26, v26, v131
	v_mul_f32_e32 v27, v27, v233
	v_and_b32_e32 v218, 0xffff0000, v132
	v_lshlrev_b32_e32 v132, 16, v132
	v_and_b32_e32 v219, 0xffff0000, v133
	v_lshlrev_b32_e32 v133, 16, v133
	v_and_b32_e32 v232, 0xffff0000, v134
	v_lshlrev_b32_e32 v134, 16, v134
	v_and_b32_e32 v233, 0xffff0000, v135
	v_lshlrev_b32_e32 v135, 16, v135
	v_mul_f32_e32 v132, s19, v132
	v_mul_f32_e32 v218, s19, v218
	v_mul_f32_e32 v133, s19, v133
	v_mul_f32_e32 v219, s19, v219
	v_mul_f32_e32 v134, s19, v134
	v_mul_f32_e32 v232, s19, v232
	v_mul_f32_e32 v135, s19, v135
	v_mul_f32_e32 v233, s19, v233
	v_exp_f32_e32 v132, v132
	v_exp_f32_e32 v218, v218
	v_exp_f32_e32 v133, v133
	v_exp_f32_e32 v219, v219
	v_exp_f32_e32 v134, v134
	v_exp_f32_e32 v232, v232
	v_exp_f32_e32 v135, v135
	v_exp_f32_e32 v233, v233
	v_add_f32_e32 v132, 1.0, v132
	v_add_f32_e32 v218, 1.0, v218
	v_add_f32_e32 v133, 1.0, v133
	v_add_f32_e32 v219, 1.0, v219
	v_add_f32_e32 v134, 1.0, v134
	v_add_f32_e32 v232, 1.0, v232
	v_add_f32_e32 v135, 1.0, v135
	v_add_f32_e32 v233, 1.0, v233
	v_rcp_f32_e32 v132, v132
	v_rcp_f32_e32 v218, v218
	v_rcp_f32_e32 v133, v133
	v_rcp_f32_e32 v219, v219
	v_rcp_f32_e32 v134, v134
	v_rcp_f32_e32 v232, v232
	v_rcp_f32_e32 v135, v135
	v_rcp_f32_e32 v233, v233
	v_mul_f32_e32 v20, v20, v132
	v_mul_f32_e32 v21, v21, v218
	v_mul_f32_e32 v22, v22, v133
	v_mul_f32_e32 v23, v23, v219
	v_mul_f32_e32 v16, v16, v134
	v_mul_f32_e32 v17, v17, v232
	v_mul_f32_e32 v18, v18, v135
	v_mul_f32_e32 v19, v19, v233
	s_add_u32 s22, s52, 0x140000
	s_addc_u32 s23, s53, 0
	global_store_dwordx4 v244, v[28:31], s[22:23] offset:0
	global_store_dwordx4 v244, v[24:27], s[22:23] offset:16
	global_store_dwordx4 v244, v[20:23], s[22:23] offset:512
	global_store_dwordx4 v244, v[16:19], s[22:23] offset:528
	s_waitcnt vmcnt(8)
	v_and_b32_e32 v218, 0xffff0000, v152
	v_lshlrev_b32_e32 v152, 16, v152
	v_and_b32_e32 v219, 0xffff0000, v153
	v_lshlrev_b32_e32 v153, 16, v153
	v_and_b32_e32 v232, 0xffff0000, v154
	v_lshlrev_b32_e32 v154, 16, v154
	v_and_b32_e32 v233, 0xffff0000, v155
	v_lshlrev_b32_e32 v155, 16, v155
	v_mul_f32_e32 v152, s19, v152
	v_mul_f32_e32 v218, s19, v218
	v_mul_f32_e32 v153, s19, v153
	v_mul_f32_e32 v219, s19, v219
	v_mul_f32_e32 v154, s19, v154
	v_mul_f32_e32 v232, s19, v232
	v_mul_f32_e32 v155, s19, v155
	v_mul_f32_e32 v233, s19, v233
	v_exp_f32_e32 v152, v152
	v_exp_f32_e32 v218, v218
	v_exp_f32_e32 v153, v153
	v_exp_f32_e32 v219, v219
	v_exp_f32_e32 v154, v154
	v_exp_f32_e32 v232, v232
	v_exp_f32_e32 v155, v155
	v_exp_f32_e32 v233, v233
	v_add_f32_e32 v152, 1.0, v152
	v_add_f32_e32 v218, 1.0, v218
	v_add_f32_e32 v153, 1.0, v153
	v_add_f32_e32 v219, 1.0, v219
	v_add_f32_e32 v154, 1.0, v154
	v_add_f32_e32 v232, 1.0, v232
	v_add_f32_e32 v155, 1.0, v155
	v_add_f32_e32 v233, 1.0, v233
	v_rcp_f32_e32 v152, v152
	v_rcp_f32_e32 v218, v218
	v_rcp_f32_e32 v153, v153
	v_rcp_f32_e32 v219, v219
	v_rcp_f32_e32 v154, v154
	v_rcp_f32_e32 v232, v232
	v_rcp_f32_e32 v155, v155
	v_rcp_f32_e32 v233, v233
	v_mul_f32_e32 v12, v12, v152
	v_mul_f32_e32 v13, v13, v218
	v_mul_f32_e32 v14, v14, v153
	v_mul_f32_e32 v15, v15, v219
	v_mul_f32_e32 v8, v8, v154
	v_mul_f32_e32 v9, v9, v232
	v_mul_f32_e32 v10, v10, v155
	v_mul_f32_e32 v11, v11, v233
	v_and_b32_e32 v218, 0xffff0000, v156
	v_lshlrev_b32_e32 v156, 16, v156
	v_and_b32_e32 v219, 0xffff0000, v157
	v_lshlrev_b32_e32 v157, 16, v157
	v_and_b32_e32 v232, 0xffff0000, v158
	v_lshlrev_b32_e32 v158, 16, v158
	v_and_b32_e32 v233, 0xffff0000, v159
	v_lshlrev_b32_e32 v159, 16, v159
	v_mul_f32_e32 v156, s19, v156
	v_mul_f32_e32 v218, s19, v218
	v_mul_f32_e32 v157, s19, v157
	v_mul_f32_e32 v219, s19, v219
	v_mul_f32_e32 v158, s19, v158
	v_mul_f32_e32 v232, s19, v232
	v_mul_f32_e32 v159, s19, v159
	v_mul_f32_e32 v233, s19, v233
	v_exp_f32_e32 v156, v156
	v_exp_f32_e32 v218, v218
	v_exp_f32_e32 v157, v157
	v_exp_f32_e32 v219, v219
	v_exp_f32_e32 v158, v158
	v_exp_f32_e32 v232, v232
	v_exp_f32_e32 v159, v159
	v_exp_f32_e32 v233, v233
	v_add_f32_e32 v156, 1.0, v156
	v_add_f32_e32 v218, 1.0, v218
	v_add_f32_e32 v157, 1.0, v157
	v_add_f32_e32 v219, 1.0, v219
	v_add_f32_e32 v158, 1.0, v158
	v_add_f32_e32 v232, 1.0, v232
	v_add_f32_e32 v159, 1.0, v159
	v_add_f32_e32 v233, 1.0, v233
	v_rcp_f32_e32 v156, v156
	v_rcp_f32_e32 v218, v218
	v_rcp_f32_e32 v157, v157
	v_rcp_f32_e32 v219, v219
	v_rcp_f32_e32 v158, v158
	v_rcp_f32_e32 v232, v232
	v_rcp_f32_e32 v159, v159
	v_rcp_f32_e32 v233, v233
	v_mul_f32_e32 v4, v4, v156
	v_mul_f32_e32 v5, v5, v218
	v_mul_f32_e32 v6, v6, v157
	v_mul_f32_e32 v7, v7, v219
	v_mul_f32_e32 v0, v0, v158
	v_mul_f32_e32 v1, v1, v232
	v_mul_f32_e32 v2, v2, v159
	v_mul_f32_e32 v3, v3, v233
	s_add_u32 s22, s52, 0x160000
	s_addc_u32 s23, s53, 0
	global_store_dwordx4 v244, v[12:15], s[22:23] offset:0
	global_store_dwordx4 v244, v[8:11], s[22:23] offset:16
	global_store_dwordx4 v244, v[4:7], s[22:23] offset:512
	global_store_dwordx4 v244, v[0:3], s[22:23] offset:528
	s_branch .LBB0_394
; __device__ __forceinline__ float lo16(unsigned u) { return __uint_as_float(u << 16); }
; __device__ __forceinline__ float hi16(unsigned u) { return __uint_as_float(u & 0xffff0000u); }
; __device__ __forceinline__ float sigmoidf_(float x) { return __builtin_amdgcn_rcpf(1.0f + __expf(-x)); }
; __device__ __forceinline__ unsigned cvt_pk_bf16(float lo, float hi) { return pk2(lo, hi); }
;     template <int Z> __device__ __forceinline__ void run(const f32x4 (&acc)[2][2][4][2], const Unit& u, int wr, int wc, int fr, int fq) const {
;     ...
;                 u32x4 graw[2][2]; f32x4 old0[2][2], old1[2][2];
; #pragma unroll
;                 for (int mm = 0; mm < 2; ++mm)
; #pragma unroll
;                     for (int bj = 0; bj < 2; ++bj) { const int row = row0 + ai * HALF + (m2 + mm) * 16, col = col0 + bj * HALF;
;                         graw[mm][bj] = *(const u32x4*)(proj + (size_t)row * NP + C_BR + Z * 2048 + col);
;                         if (Z > 0) { const float* mp = mix + (size_t)row * 2048 + col; old0[mm][bj] = *(const f32x4*)mp; old1[mm][bj] = *(const f32x4*)(mp + 4); } }
; #pragma unroll
;                 for (int mm = 0; mm < 2; ++mm)
; #pragma unroll
;                     for (int bj = 0; bj < 2; ++bj) { const int row = row0 + ai * HALF + (m2 + mm) * 16, col = col0 + bj * HALF;
;                         const u32x4 g = graw[mm][bj];
;                         f32x4 v0 = acc[ai][bj][m2 + mm][0], v1 = acc[ai][bj][m2 + mm][1];
;                         v0[0] *= sigmoidf_(lo16(g.x)); v0[1] *= sigmoidf_(hi16(g.x)); v0[2] *= sigmoidf_(lo16(g.y)); v0[3] *= sigmoidf_(hi16(g.y));
;                         v1[0] *= sigmoidf_(lo16(g.z)); v1[1] *= sigmoidf_(hi16(g.z)); v1[2] *= sigmoidf_(lo16(g.w)); v1[3] *= sigmoidf_(hi16(g.w));
;                         if (Z > 0) { v0 += old0[mm][bj]; v1 += old1[mm][bj]; }
;                         if (Z < 2) { float* mp = mix + (size_t)row * 2048 + col; *(f32x4*)mp = v0; *(f32x4*)(mp + 4) = v1; }
;                         else { u32x4 w; w.x = cvt_pk_bf16(v0[0], v0[1]); w.y = cvt_pk_bf16(v0[2], v0[3]); w.z = cvt_pk_bf16(v1[0], v1[1]); w.w = cvt_pk_bf16(v1[2], v1[3]);
;                             *(u32x4*)(mixb + (size_t)row * 2048 + col) = w; } }
.Lebr_z1:
	s_add_u32 s20, s4, 0x0
	s_addc_u32 s21, s5, 0
	global_load_dwordx4 v[128:131], v242, s[20:21] offset:0
	global_load_dwordx4 v[132:135], v242, s[20:21] offset:256
	s_add_u32 s22, s52, 0x0
	s_addc_u32 s23, s53, 0
	global_load_dwordx4 v[136:139], v244, s[22:23] offset:0
	global_load_dwordx4 v[140:143], v244, s[22:23] offset:16
	global_load_dwordx4 v[144:147], v244, s[22:23] offset:512
	global_load_dwordx4 v[148:151], v244, s[22:23] offset:528
	s_add_u32 s20, s4, 0x7e000
	s_addc_u32 s21, s5, 0
	global_load_dwordx4 v[152:155], v242, s[20:21] offset:0
	global_load_dwordx4 v[156:159], v242, s[20:21] offset:256
	s_add_u32 s22, s52, 0x20000
	s_addc_u32 s23, s53, 0
	global_load_dwordx4 v[160:163], v244, s[22:23] offset:0
	global_load_dwordx4 v[164:167], v244, s[22:23] offset:16
	global_load_dwordx4 v[168:171], v244, s[22:23] offset:512
	global_load_dwordx4 v[172:175], v244, s[22:23] offset:528
	s_add_u32 s20, s4, 0xfc000
	s_addc_u32 s21, s5, 0
	global_load_dwordx4 v[202:205], v242, s[20:21] offset:0
	global_load_dwordx4 v[206:209], v242, s[20:21] offset:256
	s_add_u32 s22, s52, 0x40000
	s_addc_u32 s23, s53, 0
	global_load_dwordx4 v[210:213], v244, s[22:23] offset:0
	global_load_dwordx4 v[214:217], v244, s[22:23] offset:16
	global_load_dwordx4 v[224:227], v244, s[22:23] offset:512
	global_load_dwordx4 v[228:231], v244, s[22:23] offset:528
	s_waitcnt vmcnt(12)
	v_and_b32_e32 v218, 0xffff0000, v128
	v_lshlrev_b32_e32 v128, 16, v128
	v_and_b32_e32 v219, 0xffff0000, v129
	v_lshlrev_b32_e32 v129, 16, v129
	v_and_b32_e32 v232, 0xffff0000, v130
	v_lshlrev_b32_e32 v130, 16, v130
	v_and_b32_e32 v233, 0xffff0000, v131
	v_lshlrev_b32_e32 v131, 16, v131
	v_mul_f32_e32 v128, s19, v128
	v_mul_f32_e32 v218, s19, v218
	v_mul_f32_e32 v129, s19, v129
	v_mul_f32_e32 v219, s19, v219
	v_mul_f32_e32 v130, s19, v130
	v_mul_f32_e32 v232, s19, v232
	v_mul_f32_e32 v131, s19, v131
	v_mul_f32_e32 v233, s19, v233
	v_exp_f32_e32 v128, v128
	v_exp_f32_e32 v218, v218
	v_exp_f32_e32 v129, v129
	v_exp_f32_e32 v219, v219
	v_exp_f32_e32 v130, v130
	v_exp_f32_e32 v232, v232
	v_exp_f32_e32 v131, v131
	v_exp_f32_e32 v233, v233
	v_add_f32_e32 v128, 1.0, v128
	v_add_f32_e32 v218, 1.0, v218
	v_add_f32_e32 v129, 1.0, v129
	v_add_f32_e32 v219, 1.0, v219
	v_add_f32_e32 v130, 1.0, v130
	v_add_f32_e32 v232, 1.0, v232
	v_add_f32_e32 v131, 1.0, v131
	v_add_f32_e32 v233, 1.0, v233
	v_rcp_f32_e32 v128, v128
	v_rcp_f32_e32 v218, v218
	v_rcp_f32_e32 v129, v129
	v_rcp_f32_e32 v219, v219
	v_rcp_f32_e32 v130, v130
	v_rcp_f32_e32 v232, v232
	v_rcp_f32_e32 v131, v131
	v_rcp_f32_e32 v233, v233
	v_mul_f32_e32 v124, v124, v128
	v_mul_f32_e32 v125, v125, v218
	v_mul_f32_e32 v126, v126, v129
	v_mul_f32_e32 v127, v127, v219
	v_mul_f32_e32 v120, v120, v130
	v_mul_f32_e32 v121, v121, v232
	v_mul_f32_e32 v122, v122, v131
	v_mul_f32_e32 v123, v123, v233
	v_add_f32_e32 v124, v124, v136
	v_add_f32_e32 v125, v125, v137
	v_add_f32_e32 v126, v126, v138
	v_add_f32_e32 v127, v127, v139
	v_add_f32_e32 v120, v120, v140
	v_add_f32_e32 v121, v121, v141
	v_add_f32_e32 v122, v122, v142
	v_add_f32_e32 v123, v123, v143
	v_and_b32_e32 v218, 0xffff0000, v132
	v_lshlrev_b32_e32 v132, 16, v132
	v_and_b32_e32 v219, 0xffff0000, v133
	v_lshlrev_b32_e32 v133, 16, v133
	v_and_b32_e32 v232, 0xffff0000, v134
	v_lshlrev_b32_e32 v134, 16, v134
	v_and_b32_e32 v233, 0xffff0000, v135
	v_lshlrev_b32_e32 v135, 16, v135
	v_mul_f32_e32 v132, s19, v132
	v_mul_f32_e32 v218, s19, v218
	v_mul_f32_e32 v133, s19, v133
	v_mul_f32_e32 v219, s19, v219
	v_mul_f32_e32 v134, s19, v134
	v_mul_f32_e32 v232, s19, v232
	v_mul_f32_e32 v135, s19, v135
	v_mul_f32_e32 v233, s19, v233
	v_exp_f32_e32 v132, v132
	v_exp_f32_e32 v218, v218
	v_exp_f32_e32 v133, v133
	v_exp_f32_e32 v219, v219
	v_exp_f32_e32 v134, v134
	v_exp_f32_e32 v232, v232
	v_exp_f32_e32 v135, v135
	v_exp_f32_e32 v233, v233
	v_add_f32_e32 v132, 1.0, v132
	v_add_f32_e32 v218, 1.0, v218
	v_add_f32_e32 v133, 1.0, v133
	v_add_f32_e32 v219, 1.0, v219
	v_add_f32_e32 v134, 1.0, v134
	v_add_f32_e32 v232, 1.0, v232
	v_add_f32_e32 v135, 1.0, v135
	v_add_f32_e32 v233, 1.0, v233
	v_rcp_f32_e32 v132, v132
	v_rcp_f32_e32 v218, v218
	v_rcp_f32_e32 v133, v133
	v_rcp_f32_e32 v219, v219
	v_rcp_f32_e32 v134, v134
	v_rcp_f32_e32 v232, v232
	v_rcp_f32_e32 v135, v135
	v_rcp_f32_e32 v233, v233
	v_mul_f32_e32 v116, v116, v132
	v_mul_f32_e32 v117, v117, v218
	v_mul_f32_e32 v118, v118, v133
	v_mul_f32_e32 v119, v119, v219
	v_mul_f32_e32 v112, v112, v134
	v_mul_f32_e32 v113, v113, v232
	v_mul_f32_e32 v114, v114, v135
	v_mul_f32_e32 v115, v115, v233
	v_add_f32_e32 v116, v116, v144
	v_add_f32_e32 v117, v117, v145
	v_add_f32_e32 v118, v118, v146
	v_add_f32_e32 v119, v119, v147
	v_add_f32_e32 v112, v112, v148
	v_add_f32_e32 v113, v113, v149
	v_add_f32_e32 v114, v114, v150
	v_add_f32_e32 v115, v115, v151
	s_add_u32 s22, s52, 0x0
	s_addc_u32 s23, s53, 0
	global_store_dwordx4 v244, v[124:127], s[22:23] offset:0
	global_store_dwordx4 v244, v[120:123], s[22:23] offset:16
	global_store_dwordx4 v244, v[116:119], s[22:23] offset:512
	global_store_dwordx4 v244, v[112:115], s[22:23] offset:528
	s_add_u32 s20, s4, 0x17a000
	s_addc_u32 s21, s5, 0
	global_load_dwordx4 v[128:131], v242, s[20:21] offset:0
	global_load_dwordx4 v[132:135], v242, s[20:21] offset:256
	s_add_u32 s22, s52, 0x60000
	s_addc_u32 s23, s53, 0
	global_load_dwordx4 v[136:139], v244, s[22:23] offset:0
	global_load_dwordx4 v[140:143], v244, s[22:23] offset:16
	global_load_dwordx4 v[144:147], v244, s[22:23] offset:512
	global_load_dwordx4 v[148:151], v244, s[22:23] offset:528
	s_waitcnt vmcnt(16)
; __device__ __forceinline__ float lo16(unsigned u) { return __uint_as_float(u << 16); }
; __device__ __forceinline__ float hi16(unsigned u) { return __uint_as_float(u & 0xffff0000u); }
; __device__ __forceinline__ float sigmoidf_(float x) { return __builtin_amdgcn_rcpf(1.0f + __expf(-x)); }
; __device__ __forceinline__ unsigned cvt_pk_bf16(float lo, float hi) { return pk2(lo, hi); }
;     template <int Z> __device__ __forceinline__ void run(const f32x4 (&acc)[2][2][4][2], const Unit& u, int wr, int wc, int fr, int fq) const {
;     ...
;                 u32x4 graw[2][2]; f32x4 old0[2][2], old1[2][2];
; #pragma unroll
;                 for (int mm = 0; mm < 2; ++mm)
; #pragma unroll
;                     for (int bj = 0; bj < 2; ++bj) { const int row = row0 + ai * HALF + (m2 + mm) * 16, col = col0 + bj * HALF;
;                         graw[mm][bj] = *(const u32x4*)(proj + (size_t)row * NP + C_BR + Z * 2048 + col);
;                         if (Z > 0) { const float* mp = mix + (size_t)row * 2048 + col; old0[mm][bj] = *(const f32x4*)mp; old1[mm][bj] = *(const f32x4*)(mp + 4); } }
; #pragma unroll
;                 for (int mm = 0; mm < 2; ++mm)
; #pragma unroll
;                     for (int bj = 0; bj < 2; ++bj) { const int row = row0 + ai * HALF + (m2 + mm) * 16, col = col0 + bj * HALF;
;                         const u32x4 g = graw[mm][bj];
;                         f32x4 v0 = acc[ai][bj][m2 + mm][0], v1 = acc[ai][bj][m2 + mm][1];
;                         v0[0] *= sigmoidf_(lo16(g.x)); v0[1] *= sigmoidf_(hi16(g.x)); v0[2] *= sigmoidf_(lo16(g.y)); v0[3] *= sigmoidf_(hi16(g.y));
;                         v1[0] *= sigmoidf_(lo16(g.z)); v1[1] *= sigmoidf_(hi16(g.z)); v1[2] *= sigmoidf_(lo16(g.w)); v1[3] *= sigmoidf_(hi16(g.w));
;                         if (Z > 0) { v0 += old0[mm][bj]; v1 += old1[mm][bj]; }
;                         if (Z < 2) { float* mp = mix + (size_t)row * 2048 + col; *(f32x4*)mp = v0; *(f32x4*)(mp + 4) = v1; }
;                         else { u32x4 w; w.x = cvt_pk_bf16(v0[0], v0[1]); w.y = cvt_pk_bf16(v0[2], v0[3]); w.z = cvt_pk_bf16(v1[0], v1[1]); w.w = cvt_pk_bf16(v1[2], v1[3]);
;                             *(u32x4*)(mixb + (size_t)row * 2048 + col) = w; } }
	v_and_b32_e32 v218, 0xffff0000, v152
	v_lshlrev_b32_e32 v152, 16, v152
	v_and_b32_e32 v219, 0xffff0000, v153
	v_lshlrev_b32_e32 v153, 16, v153
	v_and_b32_e32 v232, 0xffff0000, v154
	v_lshlrev_b32_e32 v154, 16, v154
	v_and_b32_e32 v233, 0xffff0000, v155
	v_lshlrev_b32_e32 v155, 16, v155
	v_mul_f32_e32 v152, s19, v152
	v_mul_f32_e32 v218, s19, v218
	v_mul_f32_e32 v153, s19, v153
	v_mul_f32_e32 v219, s19, v219
	v_mul_f32_e32 v154, s19, v154
	v_mul_f32_e32 v232, s19, v232
	v_mul_f32_e32 v155, s19, v155
	v_mul_f32_e32 v233, s19, v233
	v_exp_f32_e32 v152, v152
	v_exp_f32_e32 v218, v218
	v_exp_f32_e32 v153, v153
	v_exp_f32_e32 v219, v219
	v_exp_f32_e32 v154, v154
	v_exp_f32_e32 v232, v232
	v_exp_f32_e32 v155, v155
	v_exp_f32_e32 v233, v233
	v_add_f32_e32 v152, 1.0, v152
	v_add_f32_e32 v218, 1.0, v218
	v_add_f32_e32 v153, 1.0, v153
	v_add_f32_e32 v219, 1.0, v219
	v_add_f32_e32 v154, 1.0, v154
	v_add_f32_e32 v232, 1.0, v232
	v_add_f32_e32 v155, 1.0, v155
	v_add_f32_e32 v233, 1.0, v233
	v_rcp_f32_e32 v152, v152
	v_rcp_f32_e32 v218, v218
	v_rcp_f32_e32 v153, v153
	v_rcp_f32_e32 v219, v219
	v_rcp_f32_e32 v154, v154
	v_rcp_f32_e32 v232, v232
	v_rcp_f32_e32 v155, v155
	v_rcp_f32_e32 v233, v233
	v_mul_f32_e32 v108, v108, v152
	v_mul_f32_e32 v109, v109, v218
	v_mul_f32_e32 v110, v110, v153
	v_mul_f32_e32 v111, v111, v219
	v_mul_f32_e32 v104, v104, v154
	v_mul_f32_e32 v105, v105, v232
	v_mul_f32_e32 v106, v106, v155
	v_mul_f32_e32 v107, v107, v233
	v_add_f32_e32 v108, v108, v160
	v_add_f32_e32 v109, v109, v161
	v_add_f32_e32 v110, v110, v162
	v_add_f32_e32 v111, v111, v163
	v_add_f32_e32 v104, v104, v164
	v_add_f32_e32 v105, v105, v165
	v_add_f32_e32 v106, v106, v166
	v_add_f32_e32 v107, v107, v167
	v_and_b32_e32 v218, 0xffff0000, v156
	v_lshlrev_b32_e32 v156, 16, v156
	v_and_b32_e32 v219, 0xffff0000, v157
	v_lshlrev_b32_e32 v157, 16, v157
	v_and_b32_e32 v232, 0xffff0000, v158
	v_lshlrev_b32_e32 v158, 16, v158
	v_and_b32_e32 v233, 0xffff0000, v159
	v_lshlrev_b32_e32 v159, 16, v159
	v_mul_f32_e32 v156, s19, v156
	v_mul_f32_e32 v218, s19, v218
	v_mul_f32_e32 v157, s19, v157
	v_mul_f32_e32 v219, s19, v219
	v_mul_f32_e32 v158, s19, v158
	v_mul_f32_e32 v232, s19, v232
	v_mul_f32_e32 v159, s19, v159
	v_mul_f32_e32 v233, s19, v233
	v_exp_f32_e32 v156, v156
	v_exp_f32_e32 v218, v218
	v_exp_f32_e32 v157, v157
	v_exp_f32_e32 v219, v219
	v_exp_f32_e32 v158, v158
	v_exp_f32_e32 v232, v232
	v_exp_f32_e32 v159, v159
	v_exp_f32_e32 v233, v233
	v_add_f32_e32 v156, 1.0, v156
	v_add_f32_e32 v218, 1.0, v218
	v_add_f32_e32 v157, 1.0, v157
	v_add_f32_e32 v219, 1.0, v219
	v_add_f32_e32 v158, 1.0, v158
	v_add_f32_e32 v232, 1.0, v232
	v_add_f32_e32 v159, 1.0, v159
	v_add_f32_e32 v233, 1.0, v233
	v_rcp_f32_e32 v156, v156
	v_rcp_f32_e32 v218, v218
	v_rcp_f32_e32 v157, v157
	v_rcp_f32_e32 v219, v219
	v_rcp_f32_e32 v158, v158
	v_rcp_f32_e32 v232, v232
	v_rcp_f32_e32 v159, v159
	v_rcp_f32_e32 v233, v233
	v_mul_f32_e32 v100, v100, v156
	v_mul_f32_e32 v101, v101, v218
	v_mul_f32_e32 v102, v102, v157
	v_mul_f32_e32 v103, v103, v219
	v_mul_f32_e32 v96, v96, v158
	v_mul_f32_e32 v97, v97, v232
	v_mul_f32_e32 v98, v98, v159
	v_mul_f32_e32 v99, v99, v233
	v_add_f32_e32 v100, v100, v168
	v_add_f32_e32 v101, v101, v169
	v_add_f32_e32 v102, v102, v170
	v_add_f32_e32 v103, v103, v171
	v_add_f32_e32 v96, v96, v172
	v_add_f32_e32 v97, v97, v173
	v_add_f32_e32 v98, v98, v174
	v_add_f32_e32 v99, v99, v175
	s_add_u32 s22, s52, 0x20000
	s_addc_u32 s23, s53, 0
	global_store_dwordx4 v244, v[108:111], s[22:23] offset:0
	global_store_dwordx4 v244, v[104:107], s[22:23] offset:16
	global_store_dwordx4 v244, v[100:103], s[22:23] offset:512
	global_store_dwordx4 v244, v[96:99], s[22:23] offset:528
	s_add_u32 s20, s4, 0x3f0000
	s_addc_u32 s21, s5, 0
	global_load_dwordx4 v[152:155], v242, s[20:21] offset:0
	global_load_dwordx4 v[156:159], v242, s[20:21] offset:256
	s_add_u32 s22, s52, 0x100000
	s_addc_u32 s23, s53, 0
	global_load_dwordx4 v[160:163], v244, s[22:23] offset:0
	global_load_dwordx4 v[164:167], v244, s[22:23] offset:16
	global_load_dwordx4 v[168:171], v244, s[22:23] offset:512
	global_load_dwordx4 v[172:175], v244, s[22:23] offset:528
	s_waitcnt vmcnt(20)
	v_and_b32_e32 v218, 0xffff0000, v202
	v_lshlrev_b32_e32 v202, 16, v202
	v_and_b32_e32 v219, 0xffff0000, v203
	v_lshlrev_b32_e32 v203, 16, v203
	v_and_b32_e32 v232, 0xffff0000, v204
	v_lshlrev_b32_e32 v204, 16, v204
	v_and_b32_e32 v233, 0xffff0000, v205
	v_lshlrev_b32_e32 v205, 16, v205
	v_mul_f32_e32 v202, s19, v202
	v_mul_f32_e32 v218, s19, v218
	v_mul_f32_e32 v203, s19, v203
	v_mul_f32_e32 v219, s19, v219
	v_mul_f32_e32 v204, s19, v204
	v_mul_f32_e32 v232, s19, v232
	v_mul_f32_e32 v205, s19, v205
	v_mul_f32_e32 v233, s19, v233
	v_exp_f32_e32 v202, v202
	v_exp_f32_e32 v218, v218
	v_exp_f32_e32 v203, v203
	v_exp_f32_e32 v219, v219
	v_exp_f32_e32 v204, v204
	v_exp_f32_e32 v232, v232
	v_exp_f32_e32 v205, v205
	v_exp_f32_e32 v233, v233
	v_add_f32_e32 v202, 1.0, v202
	v_add_f32_e32 v218, 1.0, v218
	v_add_f32_e32 v203, 1.0, v203
	v_add_f32_e32 v219, 1.0, v219
	v_add_f32_e32 v204, 1.0, v204
	v_add_f32_e32 v232, 1.0, v232
	v_add_f32_e32 v205, 1.0, v205
	v_add_f32_e32 v233, 1.0, v233
	v_rcp_f32_e32 v202, v202
	v_rcp_f32_e32 v218, v218
	v_rcp_f32_e32 v203, v203
	v_rcp_f32_e32 v219, v219
	v_rcp_f32_e32 v204, v204
	v_rcp_f32_e32 v232, v232
	v_rcp_f32_e32 v205, v205
	v_rcp_f32_e32 v233, v233
	v_mul_f32_e32 v92, v92, v202
	v_mul_f32_e32 v93, v93, v218
	v_mul_f32_e32 v94, v94, v203
	v_mul_f32_e32 v95, v95, v219
	v_mul_f32_e32 v88, v88, v204
	v_mul_f32_e32 v89, v89, v232
	v_mul_f32_e32 v90, v90, v205
	v_mul_f32_e32 v91, v91, v233
	v_add_f32_e32 v92, v92, v210
; __device__ __forceinline__ float lo16(unsigned u) { return __uint_as_float(u << 16); }
; __device__ __forceinline__ float hi16(unsigned u) { return __uint_as_float(u & 0xffff0000u); }
; __device__ __forceinline__ float sigmoidf_(float x) { return __builtin_amdgcn_rcpf(1.0f + __expf(-x)); }
; __device__ __forceinline__ unsigned cvt_pk_bf16(float lo, float hi) { return pk2(lo, hi); }
;     template <int Z> __device__ __forceinline__ void run(const f32x4 (&acc)[2][2][4][2], const Unit& u, int wr, int wc, int fr, int fq) const {
;     ...
;                 u32x4 graw[2][2]; f32x4 old0[2][2], old1[2][2];
; #pragma unroll
;                 for (int mm = 0; mm < 2; ++mm)
; #pragma unroll
;                     for (int bj = 0; bj < 2; ++bj) { const int row = row0 + ai * HALF + (m2 + mm) * 16, col = col0 + bj * HALF;
;                         graw[mm][bj] = *(const u32x4*)(proj + (size_t)row * NP + C_BR + Z * 2048 + col);
;                         if (Z > 0) { const float* mp = mix + (size_t)row * 2048 + col; old0[mm][bj] = *(const f32x4*)mp; old1[mm][bj] = *(const f32x4*)(mp + 4); } }
; #pragma unroll
;                 for (int mm = 0; mm < 2; ++mm)
; #pragma unroll
;                     for (int bj = 0; bj < 2; ++bj) { const int row = row0 + ai * HALF + (m2 + mm) * 16, col = col0 + bj * HALF;
;                         const u32x4 g = graw[mm][bj];
;                         f32x4 v0 = acc[ai][bj][m2 + mm][0], v1 = acc[ai][bj][m2 + mm][1];
;                         v0[0] *= sigmoidf_(lo16(g.x)); v0[1] *= sigmoidf_(hi16(g.x)); v0[2] *= sigmoidf_(lo16(g.y)); v0[3] *= sigmoidf_(hi16(g.y));
;                         v1[0] *= sigmoidf_(lo16(g.z)); v1[1] *= sigmoidf_(hi16(g.z)); v1[2] *= sigmoidf_(lo16(g.w)); v1[3] *= sigmoidf_(hi16(g.w));
;                         if (Z > 0) { v0 += old0[mm][bj]; v1 += old1[mm][bj]; }
;                         if (Z < 2) { float* mp = mix + (size_t)row * 2048 + col; *(f32x4*)mp = v0; *(f32x4*)(mp + 4) = v1; }
;                         else { u32x4 w; w.x = cvt_pk_bf16(v0[0], v0[1]); w.y = cvt_pk_bf16(v0[2], v0[3]); w.z = cvt_pk_bf16(v1[0], v1[1]); w.w = cvt_pk_bf16(v1[2], v1[3]);
;                             *(u32x4*)(mixb + (size_t)row * 2048 + col) = w; } }
	v_add_f32_e32 v93, v93, v211
	v_add_f32_e32 v94, v94, v212
	v_add_f32_e32 v95, v95, v213
	v_add_f32_e32 v88, v88, v214
	v_add_f32_e32 v89, v89, v215
	v_add_f32_e32 v90, v90, v216
	v_add_f32_e32 v91, v91, v217
	v_and_b32_e32 v218, 0xffff0000, v206
	v_lshlrev_b32_e32 v206, 16, v206
	v_and_b32_e32 v219, 0xffff0000, v207
	v_lshlrev_b32_e32 v207, 16, v207
	v_and_b32_e32 v232, 0xffff0000, v208
	v_lshlrev_b32_e32 v208, 16, v208
	v_and_b32_e32 v233, 0xffff0000, v209
	v_lshlrev_b32_e32 v209, 16, v209
	v_mul_f32_e32 v206, s19, v206
	v_mul_f32_e32 v218, s19, v218
	v_mul_f32_e32 v207, s19, v207
	v_mul_f32_e32 v219, s19, v219
	v_mul_f32_e32 v208, s19, v208
	v_mul_f32_e32 v232, s19, v232
	v_mul_f32_e32 v209, s19, v209
	v_mul_f32_e32 v233, s19, v233
	v_exp_f32_e32 v206, v206
	v_exp_f32_e32 v218, v218
	v_exp_f32_e32 v207, v207
	v_exp_f32_e32 v219, v219
	v_exp_f32_e32 v208, v208
	v_exp_f32_e32 v232, v232
	v_exp_f32_e32 v209, v209
	v_exp_f32_e32 v233, v233
	v_add_f32_e32 v206, 1.0, v206
	v_add_f32_e32 v218, 1.0, v218
	v_add_f32_e32 v207, 1.0, v207
	v_add_f32_e32 v219, 1.0, v219
	v_add_f32_e32 v208, 1.0, v208
	v_add_f32_e32 v232, 1.0, v232
	v_add_f32_e32 v209, 1.0, v209
	v_add_f32_e32 v233, 1.0, v233
	v_rcp_f32_e32 v206, v206
	v_rcp_f32_e32 v218, v218
	v_rcp_f32_e32 v207, v207
	v_rcp_f32_e32 v219, v219
	v_rcp_f32_e32 v208, v208
	v_rcp_f32_e32 v232, v232
	v_rcp_f32_e32 v209, v209
	v_rcp_f32_e32 v233, v233
	v_mul_f32_e32 v84, v84, v206
	v_mul_f32_e32 v85, v85, v218
	v_mul_f32_e32 v86, v86, v207
	v_mul_f32_e32 v87, v87, v219
	v_mul_f32_e32 v80, v80, v208
	v_mul_f32_e32 v81, v81, v232
	v_mul_f32_e32 v82, v82, v209
	v_mul_f32_e32 v83, v83, v233
	v_add_f32_e32 v84, v84, v224
	v_add_f32_e32 v85, v85, v225
	v_add_f32_e32 v86, v86, v226
	v_add_f32_e32 v87, v87, v227
	v_add_f32_e32 v80, v80, v228
	v_add_f32_e32 v81, v81, v229
	v_add_f32_e32 v82, v82, v230
	v_add_f32_e32 v83, v83, v231
	s_add_u32 s22, s52, 0x40000
	s_addc_u32 s23, s53, 0
	global_store_dwordx4 v244, v[92:95], s[22:23] offset:0
	global_store_dwordx4 v244, v[88:91], s[22:23] offset:16
	global_store_dwordx4 v244, v[84:87], s[22:23] offset:512
	global_store_dwordx4 v244, v[80:83], s[22:23] offset:528
	s_add_u32 s20, s4, 0x46e000
	s_addc_u32 s21, s5, 0
	global_load_dwordx4 v[202:205], v242, s[20:21] offset:0
	global_load_dwordx4 v[206:209], v242, s[20:21] offset:256
	s_add_u32 s22, s52, 0x120000
	s_addc_u32 s23, s53, 0
	global_load_dwordx4 v[210:213], v244, s[22:23] offset:0
	global_load_dwordx4 v[214:217], v244, s[22:23] offset:16
	global_load_dwordx4 v[224:227], v244, s[22:23] offset:512
	global_load_dwordx4 v[228:231], v244, s[22:23] offset:528
	s_waitcnt vmcnt(20)
	v_and_b32_e32 v218, 0xffff0000, v128
	v_lshlrev_b32_e32 v128, 16, v128
	v_and_b32_e32 v219, 0xffff0000, v129
	v_lshlrev_b32_e32 v129, 16, v129
	v_and_b32_e32 v232, 0xffff0000, v130
	v_lshlrev_b32_e32 v130, 16, v130
	v_and_b32_e32 v233, 0xffff0000, v131
	v_lshlrev_b32_e32 v131, 16, v131
	v_mul_f32_e32 v128, s19, v128
	v_mul_f32_e32 v218, s19, v218
	v_mul_f32_e32 v129, s19, v129
	v_mul_f32_e32 v219, s19, v219
	v_mul_f32_e32 v130, s19, v130
	v_mul_f32_e32 v232, s19, v232
	v_mul_f32_e32 v131, s19, v131
	v_mul_f32_e32 v233, s19, v233
	v_exp_f32_e32 v128, v128
	v_exp_f32_e32 v218, v218
	v_exp_f32_e32 v129, v129
	v_exp_f32_e32 v219, v219
	v_exp_f32_e32 v130, v130
	v_exp_f32_e32 v232, v232
	v_exp_f32_e32 v131, v131
	v_exp_f32_e32 v233, v233
	v_add_f32_e32 v128, 1.0, v128
	v_add_f32_e32 v218, 1.0, v218
	v_add_f32_e32 v129, 1.0, v129
	v_add_f32_e32 v219, 1.0, v219
	v_add_f32_e32 v130, 1.0, v130
	v_add_f32_e32 v232, 1.0, v232
	v_add_f32_e32 v131, 1.0, v131
	v_add_f32_e32 v233, 1.0, v233
	v_rcp_f32_e32 v128, v128
	v_rcp_f32_e32 v218, v218
	v_rcp_f32_e32 v129, v129
	v_rcp_f32_e32 v219, v219
	v_rcp_f32_e32 v130, v130
	v_rcp_f32_e32 v232, v232
	v_rcp_f32_e32 v131, v131
	v_rcp_f32_e32 v233, v233
	v_mul_f32_e32 v76, v76, v128
	v_mul_f32_e32 v77, v77, v218
	v_mul_f32_e32 v78, v78, v129
	v_mul_f32_e32 v79, v79, v219
	v_mul_f32_e32 v72, v72, v130
	v_mul_f32_e32 v73, v73, v232
	v_mul_f32_e32 v74, v74, v131
	v_mul_f32_e32 v75, v75, v233
	v_add_f32_e32 v76, v76, v136
	v_add_f32_e32 v77, v77, v137
	v_add_f32_e32 v78, v78, v138
	v_add_f32_e32 v79, v79, v139
	v_add_f32_e32 v72, v72, v140
	v_add_f32_e32 v73, v73, v141
	v_add_f32_e32 v74, v74, v142
	v_add_f32_e32 v75, v75, v143
	v_and_b32_e32 v218, 0xffff0000, v132
	v_lshlrev_b32_e32 v132, 16, v132
	v_and_b32_e32 v219, 0xffff0000, v133
	v_lshlrev_b32_e32 v133, 16, v133
	v_and_b32_e32 v232, 0xffff0000, v134
	v_lshlrev_b32_e32 v134, 16, v134
	v_and_b32_e32 v233, 0xffff0000, v135
	v_lshlrev_b32_e32 v135, 16, v135
	v_mul_f32_e32 v132, s19, v132
	v_mul_f32_e32 v218, s19, v218
	v_mul_f32_e32 v133, s19, v133
	v_mul_f32_e32 v219, s19, v219
	v_mul_f32_e32 v134, s19, v134
	v_mul_f32_e32 v232, s19, v232
	v_mul_f32_e32 v135, s19, v135
	v_mul_f32_e32 v233, s19, v233
	v_exp_f32_e32 v132, v132
	v_exp_f32_e32 v218, v218
	v_exp_f32_e32 v133, v133
	v_exp_f32_e32 v219, v219
	v_exp_f32_e32 v134, v134
	v_exp_f32_e32 v232, v232
	v_exp_f32_e32 v135, v135
	v_exp_f32_e32 v233, v233
	v_add_f32_e32 v132, 1.0, v132
	v_add_f32_e32 v218, 1.0, v218
	v_add_f32_e32 v133, 1.0, v133
	v_add_f32_e32 v219, 1.0, v219
	v_add_f32_e32 v134, 1.0, v134
	v_add_f32_e32 v232, 1.0, v232
	v_add_f32_e32 v135, 1.0, v135
	v_add_f32_e32 v233, 1.0, v233
	v_rcp_f32_e32 v132, v132
	v_rcp_f32_e32 v218, v218
	v_rcp_f32_e32 v133, v133
	v_rcp_f32_e32 v219, v219
	v_rcp_f32_e32 v134, v134
	v_rcp_f32_e32 v232, v232
	v_rcp_f32_e32 v135, v135
	v_rcp_f32_e32 v233, v233
	v_mul_f32_e32 v68, v68, v132
	v_mul_f32_e32 v69, v69, v218
	v_mul_f32_e32 v70, v70, v133
	v_mul_f32_e32 v71, v71, v219
	v_mul_f32_e32 v64, v64, v134
	v_mul_f32_e32 v65, v65, v232
	v_mul_f32_e32 v66, v66, v135
	v_mul_f32_e32 v67, v67, v233
	v_add_f32_e32 v68, v68, v144
	v_add_f32_e32 v69, v69, v145
	v_add_f32_e32 v70, v70, v146
	v_add_f32_e32 v71, v71, v147
	v_add_f32_e32 v64, v64, v148
	v_add_f32_e32 v65, v65, v149
	v_add_f32_e32 v66, v66, v150
	v_add_f32_e32 v67, v67, v151
	s_add_u32 s22, s52, 0x60000
	s_addc_u32 s23, s53, 0
	global_store_dwordx4 v244, v[76:79], s[22:23] offset:0
	global_store_dwordx4 v244, v[72:75], s[22:23] offset:16
	global_store_dwordx4 v244, v[68:71], s[22:23] offset:512
	global_store_dwordx4 v244, v[64:67], s[22:23] offset:528
	s_add_u32 s20, s4, 0x4ec000
	s_addc_u32 s21, s5, 0
	global_load_dwordx4 v[128:131], v242, s[20:21] offset:0
	global_load_dwordx4 v[132:135], v242, s[20:21] offset:256
	s_add_u32 s22, s52, 0x140000
	s_addc_u32 s23, s53, 0
	global_load_dwordx4 v[136:139], v244, s[22:23] offset:0
	global_load_dwordx4 v[140:143], v244, s[22:23] offset:16
	global_load_dwordx4 v[144:147], v244, s[22:23] offset:512
	global_load_dwordx4 v[148:151], v244, s[22:23] offset:528
	s_waitcnt vmcnt(20)
; __device__ __forceinline__ float lo16(unsigned u) { return __uint_as_float(u << 16); }
; __device__ __forceinline__ float hi16(unsigned u) { return __uint_as_float(u & 0xffff0000u); }
; __device__ __forceinline__ float sigmoidf_(float x) { return __builtin_amdgcn_rcpf(1.0f + __expf(-x)); }
; __device__ __forceinline__ unsigned cvt_pk_bf16(float lo, float hi) { return pk2(lo, hi); }
;     template <int Z> __device__ __forceinline__ void run(const f32x4 (&acc)[2][2][4][2], const Unit& u, int wr, int wc, int fr, int fq) const {
;     ...
;                 u32x4 graw[2][2]; f32x4 old0[2][2], old1[2][2];
; #pragma unroll
;                 for (int mm = 0; mm < 2; ++mm)
; #pragma unroll
;                     for (int bj = 0; bj < 2; ++bj) { const int row = row0 + ai * HALF + (m2 + mm) * 16, col = col0 + bj * HALF;
;                         graw[mm][bj] = *(const u32x4*)(proj + (size_t)row * NP + C_BR + Z * 2048 + col);
;                         if (Z > 0) { const float* mp = mix + (size_t)row * 2048 + col; old0[mm][bj] = *(const f32x4*)mp; old1[mm][bj] = *(const f32x4*)(mp + 4); } }
; #pragma unroll
;                 for (int mm = 0; mm < 2; ++mm)
; #pragma unroll
;                     for (int bj = 0; bj < 2; ++bj) { const int row = row0 + ai * HALF + (m2 + mm) * 16, col = col0 + bj * HALF;
;                         const u32x4 g = graw[mm][bj];
;                         f32x4 v0 = acc[ai][bj][m2 + mm][0], v1 = acc[ai][bj][m2 + mm][1];
;                         v0[0] *= sigmoidf_(lo16(g.x)); v0[1] *= sigmoidf_(hi16(g.x)); v0[2] *= sigmoidf_(lo16(g.y)); v0[3] *= sigmoidf_(hi16(g.y));
;                         v1[0] *= sigmoidf_(lo16(g.z)); v1[1] *= sigmoidf_(hi16(g.z)); v1[2] *= sigmoidf_(lo16(g.w)); v1[3] *= sigmoidf_(hi16(g.w));
;                         if (Z > 0) { v0 += old0[mm][bj]; v1 += old1[mm][bj]; }
;                         if (Z < 2) { float* mp = mix + (size_t)row * 2048 + col; *(f32x4*)mp = v0; *(f32x4*)(mp + 4) = v1; }
;                         else { u32x4 w; w.x = cvt_pk_bf16(v0[0], v0[1]); w.y = cvt_pk_bf16(v0[2], v0[3]); w.z = cvt_pk_bf16(v1[0], v1[1]); w.w = cvt_pk_bf16(v1[2], v1[3]);
;                             *(u32x4*)(mixb + (size_t)row * 2048 + col) = w; } }
	v_and_b32_e32 v218, 0xffff0000, v152
	v_lshlrev_b32_e32 v152, 16, v152
	v_and_b32_e32 v219, 0xffff0000, v153
	v_lshlrev_b32_e32 v153, 16, v153
	v_and_b32_e32 v232, 0xffff0000, v154
	v_lshlrev_b32_e32 v154, 16, v154
	v_and_b32_e32 v233, 0xffff0000, v155
	v_lshlrev_b32_e32 v155, 16, v155
	v_mul_f32_e32 v152, s19, v152
	v_mul_f32_e32 v218, s19, v218
	v_mul_f32_e32 v153, s19, v153
	v_mul_f32_e32 v219, s19, v219
	v_mul_f32_e32 v154, s19, v154
	v_mul_f32_e32 v232, s19, v232
	v_mul_f32_e32 v155, s19, v155
	v_mul_f32_e32 v233, s19, v233
	v_exp_f32_e32 v152, v152
	v_exp_f32_e32 v218, v218
	v_exp_f32_e32 v153, v153
	v_exp_f32_e32 v219, v219
	v_exp_f32_e32 v154, v154
	v_exp_f32_e32 v232, v232
	v_exp_f32_e32 v155, v155
	v_exp_f32_e32 v233, v233
	v_add_f32_e32 v152, 1.0, v152
	v_add_f32_e32 v218, 1.0, v218
	v_add_f32_e32 v153, 1.0, v153
	v_add_f32_e32 v219, 1.0, v219
	v_add_f32_e32 v154, 1.0, v154
	v_add_f32_e32 v232, 1.0, v232
	v_add_f32_e32 v155, 1.0, v155
	v_add_f32_e32 v233, 1.0, v233
	v_rcp_f32_e32 v152, v152
	v_rcp_f32_e32 v218, v218
	v_rcp_f32_e32 v153, v153
	v_rcp_f32_e32 v219, v219
	v_rcp_f32_e32 v154, v154
	v_rcp_f32_e32 v232, v232
	v_rcp_f32_e32 v155, v155
	v_rcp_f32_e32 v233, v233
	v_mul_f32_e32 v60, v60, v152
	v_mul_f32_e32 v61, v61, v218
	v_mul_f32_e32 v62, v62, v153
	v_mul_f32_e32 v63, v63, v219
	v_mul_f32_e32 v56, v56, v154
	v_mul_f32_e32 v57, v57, v232
	v_mul_f32_e32 v58, v58, v155
	v_mul_f32_e32 v59, v59, v233
	v_add_f32_e32 v60, v60, v160
	v_add_f32_e32 v61, v61, v161
	v_add_f32_e32 v62, v62, v162
	v_add_f32_e32 v63, v63, v163
	v_add_f32_e32 v56, v56, v164
	v_add_f32_e32 v57, v57, v165
	v_add_f32_e32 v58, v58, v166
	v_add_f32_e32 v59, v59, v167
	v_and_b32_e32 v218, 0xffff0000, v156
	v_lshlrev_b32_e32 v156, 16, v156
	v_and_b32_e32 v219, 0xffff0000, v157
	v_lshlrev_b32_e32 v157, 16, v157
	v_and_b32_e32 v232, 0xffff0000, v158
	v_lshlrev_b32_e32 v158, 16, v158
	v_and_b32_e32 v233, 0xffff0000, v159
	v_lshlrev_b32_e32 v159, 16, v159
	v_mul_f32_e32 v156, s19, v156
	v_mul_f32_e32 v218, s19, v218
	v_mul_f32_e32 v157, s19, v157
	v_mul_f32_e32 v219, s19, v219
	v_mul_f32_e32 v158, s19, v158
	v_mul_f32_e32 v232, s19, v232
	v_mul_f32_e32 v159, s19, v159
	v_mul_f32_e32 v233, s19, v233
	v_exp_f32_e32 v156, v156
	v_exp_f32_e32 v218, v218
	v_exp_f32_e32 v157, v157
	v_exp_f32_e32 v219, v219
	v_exp_f32_e32 v158, v158
	v_exp_f32_e32 v232, v232
	v_exp_f32_e32 v159, v159
	v_exp_f32_e32 v233, v233
	v_add_f32_e32 v156, 1.0, v156
	v_add_f32_e32 v218, 1.0, v218
	v_add_f32_e32 v157, 1.0, v157
	v_add_f32_e32 v219, 1.0, v219
	v_add_f32_e32 v158, 1.0, v158
	v_add_f32_e32 v232, 1.0, v232
	v_add_f32_e32 v159, 1.0, v159
	v_add_f32_e32 v233, 1.0, v233
	v_rcp_f32_e32 v156, v156
	v_rcp_f32_e32 v218, v218
	v_rcp_f32_e32 v157, v157
	v_rcp_f32_e32 v219, v219
	v_rcp_f32_e32 v158, v158
	v_rcp_f32_e32 v232, v232
	v_rcp_f32_e32 v159, v159
	v_rcp_f32_e32 v233, v233
	v_mul_f32_e32 v52, v52, v156
	v_mul_f32_e32 v53, v53, v218
	v_mul_f32_e32 v54, v54, v157
	v_mul_f32_e32 v55, v55, v219
	v_mul_f32_e32 v48, v48, v158
	v_mul_f32_e32 v49, v49, v232
	v_mul_f32_e32 v50, v50, v159
	v_mul_f32_e32 v51, v51, v233
	v_add_f32_e32 v52, v52, v168
	v_add_f32_e32 v53, v53, v169
	v_add_f32_e32 v54, v54, v170
	v_add_f32_e32 v55, v55, v171
	v_add_f32_e32 v48, v48, v172
	v_add_f32_e32 v49, v49, v173
	v_add_f32_e32 v50, v50, v174
	v_add_f32_e32 v51, v51, v175
	s_add_u32 s22, s52, 0x100000
	s_addc_u32 s23, s53, 0
	global_store_dwordx4 v244, v[60:63], s[22:23] offset:0
	global_store_dwordx4 v244, v[56:59], s[22:23] offset:16
	global_store_dwordx4 v244, v[52:55], s[22:23] offset:512
	global_store_dwordx4 v244, v[48:51], s[22:23] offset:528
	s_add_u32 s20, s4, 0x56a000
	s_addc_u32 s21, s5, 0
	global_load_dwordx4 v[152:155], v242, s[20:21] offset:0
	global_load_dwordx4 v[156:159], v242, s[20:21] offset:256
	s_add_u32 s22, s52, 0x160000
	s_addc_u32 s23, s53, 0
	global_load_dwordx4 v[160:163], v244, s[22:23] offset:0
	global_load_dwordx4 v[164:167], v244, s[22:23] offset:16
	global_load_dwordx4 v[168:171], v244, s[22:23] offset:512
	global_load_dwordx4 v[172:175], v244, s[22:23] offset:528
	s_waitcnt vmcnt(20)
	v_and_b32_e32 v218, 0xffff0000, v202
	v_lshlrev_b32_e32 v202, 16, v202
	v_and_b32_e32 v219, 0xffff0000, v203
	v_lshlrev_b32_e32 v203, 16, v203
	v_and_b32_e32 v232, 0xffff0000, v204
	v_lshlrev_b32_e32 v204, 16, v204
	v_and_b32_e32 v233, 0xffff0000, v205
	v_lshlrev_b32_e32 v205, 16, v205
	v_mul_f32_e32 v202, s19, v202
	v_mul_f32_e32 v218, s19, v218
	v_mul_f32_e32 v203, s19, v203
	v_mul_f32_e32 v219, s19, v219
	v_mul_f32_e32 v204, s19, v204
	v_mul_f32_e32 v232, s19, v232
	v_mul_f32_e32 v205, s19, v205
	v_mul_f32_e32 v233, s19, v233
	v_exp_f32_e32 v202, v202
	v_exp_f32_e32 v218, v218
	v_exp_f32_e32 v203, v203
	v_exp_f32_e32 v219, v219
	v_exp_f32_e32 v204, v204
	v_exp_f32_e32 v232, v232
	v_exp_f32_e32 v205, v205
	v_exp_f32_e32 v233, v233
	v_add_f32_e32 v202, 1.0, v202
	v_add_f32_e32 v218, 1.0, v218
	v_add_f32_e32 v203, 1.0, v203
	v_add_f32_e32 v219, 1.0, v219
	v_add_f32_e32 v204, 1.0, v204
	v_add_f32_e32 v232, 1.0, v232
	v_add_f32_e32 v205, 1.0, v205
	v_add_f32_e32 v233, 1.0, v233
	v_rcp_f32_e32 v202, v202
	v_rcp_f32_e32 v218, v218
	v_rcp_f32_e32 v203, v203
	v_rcp_f32_e32 v219, v219
	v_rcp_f32_e32 v204, v204
	v_rcp_f32_e32 v232, v232
	v_rcp_f32_e32 v205, v205
	v_rcp_f32_e32 v233, v233
	v_mul_f32_e32 v44, v44, v202
	v_mul_f32_e32 v45, v45, v218
	v_mul_f32_e32 v46, v46, v203
	v_mul_f32_e32 v47, v47, v219
	v_mul_f32_e32 v40, v40, v204
	v_mul_f32_e32 v41, v41, v232
	v_mul_f32_e32 v42, v42, v205
	v_mul_f32_e32 v43, v43, v233
	v_add_f32_e32 v44, v44, v210
	v_add_f32_e32 v45, v45, v211
	v_add_f32_e32 v46, v46, v212
; __device__ __forceinline__ float lo16(unsigned u) { return __uint_as_float(u << 16); }
; __device__ __forceinline__ float hi16(unsigned u) { return __uint_as_float(u & 0xffff0000u); }
; __device__ __forceinline__ float sigmoidf_(float x) { return __builtin_amdgcn_rcpf(1.0f + __expf(-x)); }
; __device__ __forceinline__ unsigned cvt_pk_bf16(float lo, float hi) { return pk2(lo, hi); }
;     template <int Z> __device__ __forceinline__ void run(const f32x4 (&acc)[2][2][4][2], const Unit& u, int wr, int wc, int fr, int fq) const {
;     ...
;                 u32x4 graw[2][2]; f32x4 old0[2][2], old1[2][2];
; #pragma unroll
;                 for (int mm = 0; mm < 2; ++mm)
; #pragma unroll
;                     for (int bj = 0; bj < 2; ++bj) { const int row = row0 + ai * HALF + (m2 + mm) * 16, col = col0 + bj * HALF;
;                         graw[mm][bj] = *(const u32x4*)(proj + (size_t)row * NP + C_BR + Z * 2048 + col);
;                         if (Z > 0) { const float* mp = mix + (size_t)row * 2048 + col; old0[mm][bj] = *(const f32x4*)mp; old1[mm][bj] = *(const f32x4*)(mp + 4); } }
; #pragma unroll
;                 for (int mm = 0; mm < 2; ++mm)
; #pragma unroll
;                     for (int bj = 0; bj < 2; ++bj) { const int row = row0 + ai * HALF + (m2 + mm) * 16, col = col0 + bj * HALF;
;                         const u32x4 g = graw[mm][bj];
;                         f32x4 v0 = acc[ai][bj][m2 + mm][0], v1 = acc[ai][bj][m2 + mm][1];
;                         v0[0] *= sigmoidf_(lo16(g.x)); v0[1] *= sigmoidf_(hi16(g.x)); v0[2] *= sigmoidf_(lo16(g.y)); v0[3] *= sigmoidf_(hi16(g.y));
;                         v1[0] *= sigmoidf_(lo16(g.z)); v1[1] *= sigmoidf_(hi16(g.z)); v1[2] *= sigmoidf_(lo16(g.w)); v1[3] *= sigmoidf_(hi16(g.w));
;                         if (Z > 0) { v0 += old0[mm][bj]; v1 += old1[mm][bj]; }
;                         if (Z < 2) { float* mp = mix + (size_t)row * 2048 + col; *(f32x4*)mp = v0; *(f32x4*)(mp + 4) = v1; }
;                         else { u32x4 w; w.x = cvt_pk_bf16(v0[0], v0[1]); w.y = cvt_pk_bf16(v0[2], v0[3]); w.z = cvt_pk_bf16(v1[0], v1[1]); w.w = cvt_pk_bf16(v1[2], v1[3]);
;                             *(u32x4*)(mixb + (size_t)row * 2048 + col) = w; } }
	v_add_f32_e32 v47, v47, v213
	v_add_f32_e32 v40, v40, v214
	v_add_f32_e32 v41, v41, v215
	v_add_f32_e32 v42, v42, v216
	v_add_f32_e32 v43, v43, v217
	v_and_b32_e32 v218, 0xffff0000, v206
	v_lshlrev_b32_e32 v206, 16, v206
	v_and_b32_e32 v219, 0xffff0000, v207
	v_lshlrev_b32_e32 v207, 16, v207
	v_and_b32_e32 v232, 0xffff0000, v208
	v_lshlrev_b32_e32 v208, 16, v208
	v_and_b32_e32 v233, 0xffff0000, v209
	v_lshlrev_b32_e32 v209, 16, v209
	v_mul_f32_e32 v206, s19, v206
	v_mul_f32_e32 v218, s19, v218
	v_mul_f32_e32 v207, s19, v207
	v_mul_f32_e32 v219, s19, v219
	v_mul_f32_e32 v208, s19, v208
	v_mul_f32_e32 v232, s19, v232
	v_mul_f32_e32 v209, s19, v209
	v_mul_f32_e32 v233, s19, v233
	v_exp_f32_e32 v206, v206
	v_exp_f32_e32 v218, v218
	v_exp_f32_e32 v207, v207
	v_exp_f32_e32 v219, v219
	v_exp_f32_e32 v208, v208
	v_exp_f32_e32 v232, v232
	v_exp_f32_e32 v209, v209
	v_exp_f32_e32 v233, v233
	v_add_f32_e32 v206, 1.0, v206
	v_add_f32_e32 v218, 1.0, v218
	v_add_f32_e32 v207, 1.0, v207
	v_add_f32_e32 v219, 1.0, v219
	v_add_f32_e32 v208, 1.0, v208
	v_add_f32_e32 v232, 1.0, v232
	v_add_f32_e32 v209, 1.0, v209
	v_add_f32_e32 v233, 1.0, v233
	v_rcp_f32_e32 v206, v206
	v_rcp_f32_e32 v218, v218
	v_rcp_f32_e32 v207, v207
	v_rcp_f32_e32 v219, v219
	v_rcp_f32_e32 v208, v208
	v_rcp_f32_e32 v232, v232
	v_rcp_f32_e32 v209, v209
	v_rcp_f32_e32 v233, v233
	v_mul_f32_e32 v36, v36, v206
	v_mul_f32_e32 v37, v37, v218
	v_mul_f32_e32 v38, v38, v207
	v_mul_f32_e32 v39, v39, v219
	v_mul_f32_e32 v32, v32, v208
	v_mul_f32_e32 v33, v33, v232
	v_mul_f32_e32 v34, v34, v209
	v_mul_f32_e32 v35, v35, v233
	v_add_f32_e32 v36, v36, v224
	v_add_f32_e32 v37, v37, v225
	v_add_f32_e32 v38, v38, v226
	v_add_f32_e32 v39, v39, v227
	v_add_f32_e32 v32, v32, v228
	v_add_f32_e32 v33, v33, v229
	v_add_f32_e32 v34, v34, v230
	v_add_f32_e32 v35, v35, v231
	s_add_u32 s22, s52, 0x120000
	s_addc_u32 s23, s53, 0
	global_store_dwordx4 v244, v[44:47], s[22:23] offset:0
	global_store_dwordx4 v244, v[40:43], s[22:23] offset:16
	global_store_dwordx4 v244, v[36:39], s[22:23] offset:512
	global_store_dwordx4 v244, v[32:35], s[22:23] offset:528
	s_waitcnt vmcnt(14)
	v_and_b32_e32 v218, 0xffff0000, v128
	v_lshlrev_b32_e32 v128, 16, v128
	v_and_b32_e32 v219, 0xffff0000, v129
	v_lshlrev_b32_e32 v129, 16, v129
	v_and_b32_e32 v232, 0xffff0000, v130
	v_lshlrev_b32_e32 v130, 16, v130
	v_and_b32_e32 v233, 0xffff0000, v131
	v_lshlrev_b32_e32 v131, 16, v131
	v_mul_f32_e32 v128, s19, v128
	v_mul_f32_e32 v218, s19, v218
	v_mul_f32_e32 v129, s19, v129
	v_mul_f32_e32 v219, s19, v219
	v_mul_f32_e32 v130, s19, v130
	v_mul_f32_e32 v232, s19, v232
	v_mul_f32_e32 v131, s19, v131
	v_mul_f32_e32 v233, s19, v233
	v_exp_f32_e32 v128, v128
	v_exp_f32_e32 v218, v218
	v_exp_f32_e32 v129, v129
	v_exp_f32_e32 v219, v219
	v_exp_f32_e32 v130, v130
	v_exp_f32_e32 v232, v232
	v_exp_f32_e32 v131, v131
	v_exp_f32_e32 v233, v233
	v_add_f32_e32 v128, 1.0, v128
	v_add_f32_e32 v218, 1.0, v218
	v_add_f32_e32 v129, 1.0, v129
	v_add_f32_e32 v219, 1.0, v219
	v_add_f32_e32 v130, 1.0, v130
	v_add_f32_e32 v232, 1.0, v232
	v_add_f32_e32 v131, 1.0, v131
	v_add_f32_e32 v233, 1.0, v233
	v_rcp_f32_e32 v128, v128
	v_rcp_f32_e32 v218, v218
	v_rcp_f32_e32 v129, v129
	v_rcp_f32_e32 v219, v219
	v_rcp_f32_e32 v130, v130
	v_rcp_f32_e32 v232, v232
	v_rcp_f32_e32 v131, v131
	v_rcp_f32_e32 v233, v233
	v_mul_f32_e32 v28, v28, v128
	v_mul_f32_e32 v29, v29, v218
	v_mul_f32_e32 v30, v30, v129
	v_mul_f32_e32 v31, v31, v219
	v_mul_f32_e32 v24, v24, v130
	v_mul_f32_e32 v25, v25, v232
	v_mul_f32_e32 v26, v26, v131
	v_mul_f32_e32 v27, v27, v233
	v_add_f32_e32 v28, v28, v136
	v_add_f32_e32 v29, v29, v137
	v_add_f32_e32 v30, v30, v138
	v_add_f32_e32 v31, v31, v139
	v_add_f32_e32 v24, v24, v140
	v_add_f32_e32 v25, v25, v141
	v_add_f32_e32 v26, v26, v142
	v_add_f32_e32 v27, v27, v143
	v_and_b32_e32 v218, 0xffff0000, v132
	v_lshlrev_b32_e32 v132, 16, v132
	v_and_b32_e32 v219, 0xffff0000, v133
	v_lshlrev_b32_e32 v133, 16, v133
	v_and_b32_e32 v232, 0xffff0000, v134
	v_lshlrev_b32_e32 v134, 16, v134
	v_and_b32_e32 v233, 0xffff0000, v135
	v_lshlrev_b32_e32 v135, 16, v135
	v_mul_f32_e32 v132, s19, v132
	v_mul_f32_e32 v218, s19, v218
	v_mul_f32_e32 v133, s19, v133
	v_mul_f32_e32 v219, s19, v219
	v_mul_f32_e32 v134, s19, v134
	v_mul_f32_e32 v232, s19, v232
	v_mul_f32_e32 v135, s19, v135
	v_mul_f32_e32 v233, s19, v233
	v_exp_f32_e32 v132, v132
	v_exp_f32_e32 v218, v218
	v_exp_f32_e32 v133, v133
	v_exp_f32_e32 v219, v219
	v_exp_f32_e32 v134, v134
	v_exp_f32_e32 v232, v232
	v_exp_f32_e32 v135, v135
	v_exp_f32_e32 v233, v233
	v_add_f32_e32 v132, 1.0, v132
	v_add_f32_e32 v218, 1.0, v218
	v_add_f32_e32 v133, 1.0, v133
	v_add_f32_e32 v219, 1.0, v219
	v_add_f32_e32 v134, 1.0, v134
	v_add_f32_e32 v232, 1.0, v232
	v_add_f32_e32 v135, 1.0, v135
	v_add_f32_e32 v233, 1.0, v233
	v_rcp_f32_e32 v132, v132
	v_rcp_f32_e32 v218, v218
	v_rcp_f32_e32 v133, v133
	v_rcp_f32_e32 v219, v219
	v_rcp_f32_e32 v134, v134
	v_rcp_f32_e32 v232, v232
	v_rcp_f32_e32 v135, v135
	v_rcp_f32_e32 v233, v233
	v_mul_f32_e32 v20, v20, v132
	v_mul_f32_e32 v21, v21, v218
	v_mul_f32_e32 v22, v22, v133
	v_mul_f32_e32 v23, v23, v219
	v_mul_f32_e32 v16, v16, v134
	v_mul_f32_e32 v17, v17, v232
	v_mul_f32_e32 v18, v18, v135
	v_mul_f32_e32 v19, v19, v233
	v_add_f32_e32 v20, v20, v144
	v_add_f32_e32 v21, v21, v145
	v_add_f32_e32 v22, v22, v146
	v_add_f32_e32 v23, v23, v147
	v_add_f32_e32 v16, v16, v148
	v_add_f32_e32 v17, v17, v149
	v_add_f32_e32 v18, v18, v150
	v_add_f32_e32 v19, v19, v151
	s_add_u32 s22, s52, 0x140000
	s_addc_u32 s23, s53, 0
	global_store_dwordx4 v244, v[28:31], s[22:23] offset:0
	global_store_dwordx4 v244, v[24:27], s[22:23] offset:16
	global_store_dwordx4 v244, v[20:23], s[22:23] offset:512
	global_store_dwordx4 v244, v[16:19], s[22:23] offset:528
	s_waitcnt vmcnt(8)
; __device__ __forceinline__ float lo16(unsigned u) { return __uint_as_float(u << 16); }
; __device__ __forceinline__ float hi16(unsigned u) { return __uint_as_float(u & 0xffff0000u); }
; __device__ __forceinline__ float sigmoidf_(float x) { return __builtin_amdgcn_rcpf(1.0f + __expf(-x)); }
;     template <int Z> __device__ __forceinline__ void run(const f32x4 (&acc)[2][2][4][2], const Unit& u, int wr, int wc, int fr, int fq) const {
;     ...
;                 u32x4 graw[2][2]; f32x4 old0[2][2], old1[2][2];
; #pragma unroll
;                 for (int mm = 0; mm < 2; ++mm)
; #pragma unroll
;                     for (int bj = 0; bj < 2; ++bj) { const int row = row0 + ai * HALF + (m2 + mm) * 16, col = col0 + bj * HALF;
;                         graw[mm][bj] = *(const u32x4*)(proj + (size_t)row * NP + C_BR + Z * 2048 + col);
;                         if (Z > 0) { const float* mp = mix + (size_t)row * 2048 + col; old0[mm][bj] = *(const f32x4*)mp; old1[mm][bj] = *(const f32x4*)(mp + 4); } }
; #pragma unroll
;                 for (int mm = 0; mm < 2; ++mm)
; #pragma unroll
;                     for (int bj = 0; bj < 2; ++bj) { const int row = row0 + ai * HALF + (m2 + mm) * 16, col = col0 + bj * HALF;
;                         const u32x4 g = graw[mm][bj];
;                         f32x4 v0 = acc[ai][bj][m2 + mm][0], v1 = acc[ai][bj][m2 + mm][1];
;                         v0[0] *= sigmoidf_(lo16(g.x)); v0[1] *= sigmoidf_(hi16(g.x)); v0[2] *= sigmoidf_(lo16(g.y)); v0[3] *= sigmoidf_(hi16(g.y));
;                         v1[0] *= sigmoidf_(lo16(g.z)); v1[1] *= sigmoidf_(hi16(g.z)); v1[2] *= sigmoidf_(lo16(g.w)); v1[3] *= sigmoidf_(hi16(g.w));
;                         if (Z > 0) { v0 += old0[mm][bj]; v1 += old1[mm][bj]; }
;                         if (Z < 2) { float* mp = mix + (size_t)row * 2048 + col; *(f32x4*)mp = v0; *(f32x4*)(mp + 4) = v1; }
;                         else { u32x4 w; w.x = cvt_pk_bf16(v0[0], v0[1]); w.y = cvt_pk_bf16(v0[2], v0[3]); w.z = cvt_pk_bf16(v1[0], v1[1]); w.w = cvt_pk_bf16(v1[2], v1[3]);
;                             *(u32x4*)(mixb + (size_t)row * 2048 + col) = w; } }
;     __device__ __forceinline__ void operator()(const f32x4 (&acc)[2][2][4][2], const Unit& u, int wr, int wc, int fr, int fq) const {
;         if (u.z == 0) run<0>(acc, u, wr, wc, fr, fq); else if (u.z == 1) run<1>(acc, u, wr, wc, fr, fq); else run<2>(acc, u, wr, wc, fr, fq);
	v_and_b32_e32 v218, 0xffff0000, v152
	v_lshlrev_b32_e32 v152, 16, v152
	v_and_b32_e32 v219, 0xffff0000, v153
	v_lshlrev_b32_e32 v153, 16, v153
	v_and_b32_e32 v232, 0xffff0000, v154
	v_lshlrev_b32_e32 v154, 16, v154
	v_and_b32_e32 v233, 0xffff0000, v155
	v_lshlrev_b32_e32 v155, 16, v155
	v_mul_f32_e32 v152, s19, v152
	v_mul_f32_e32 v218, s19, v218
	v_mul_f32_e32 v153, s19, v153
	v_mul_f32_e32 v219, s19, v219
	v_mul_f32_e32 v154, s19, v154
	v_mul_f32_e32 v232, s19, v232
	v_mul_f32_e32 v155, s19, v155
	v_mul_f32_e32 v233, s19, v233
	v_exp_f32_e32 v152, v152
	v_exp_f32_e32 v218, v218
	v_exp_f32_e32 v153, v153
	v_exp_f32_e32 v219, v219
	v_exp_f32_e32 v154, v154
	v_exp_f32_e32 v232, v232
	v_exp_f32_e32 v155, v155
	v_exp_f32_e32 v233, v233
	v_add_f32_e32 v152, 1.0, v152
	v_add_f32_e32 v218, 1.0, v218
	v_add_f32_e32 v153, 1.0, v153
	v_add_f32_e32 v219, 1.0, v219
	v_add_f32_e32 v154, 1.0, v154
	v_add_f32_e32 v232, 1.0, v232
	v_add_f32_e32 v155, 1.0, v155
	v_add_f32_e32 v233, 1.0, v233
	v_rcp_f32_e32 v152, v152
	v_rcp_f32_e32 v218, v218
	v_rcp_f32_e32 v153, v153
	v_rcp_f32_e32 v219, v219
	v_rcp_f32_e32 v154, v154
	v_rcp_f32_e32 v232, v232
	v_rcp_f32_e32 v155, v155
	v_rcp_f32_e32 v233, v233
	v_mul_f32_e32 v12, v12, v152
	v_mul_f32_e32 v13, v13, v218
	v_mul_f32_e32 v14, v14, v153
	v_mul_f32_e32 v15, v15, v219
	v_mul_f32_e32 v8, v8, v154
	v_mul_f32_e32 v9, v9, v232
	v_mul_f32_e32 v10, v10, v155
	v_mul_f32_e32 v11, v11, v233
	v_add_f32_e32 v12, v12, v160
	v_add_f32_e32 v13, v13, v161
	v_add_f32_e32 v14, v14, v162
	v_add_f32_e32 v15, v15, v163
	v_add_f32_e32 v8, v8, v164
	v_add_f32_e32 v9, v9, v165
	v_add_f32_e32 v10, v10, v166
	v_add_f32_e32 v11, v11, v167
	v_and_b32_e32 v218, 0xffff0000, v156
	v_lshlrev_b32_e32 v156, 16, v156
	v_and_b32_e32 v219, 0xffff0000, v157
	v_lshlrev_b32_e32 v157, 16, v157
	v_and_b32_e32 v232, 0xffff0000, v158
	v_lshlrev_b32_e32 v158, 16, v158
	v_and_b32_e32 v233, 0xffff0000, v159
	v_lshlrev_b32_e32 v159, 16, v159
	v_mul_f32_e32 v156, s19, v156
	v_mul_f32_e32 v218, s19, v218
	v_mul_f32_e32 v157, s19, v157
	v_mul_f32_e32 v219, s19, v219
	v_mul_f32_e32 v158, s19, v158
	v_mul_f32_e32 v232, s19, v232
	v_mul_f32_e32 v159, s19, v159
	v_mul_f32_e32 v233, s19, v233
	v_exp_f32_e32 v156, v156
	v_exp_f32_e32 v218, v218
	v_exp_f32_e32 v157, v157
	v_exp_f32_e32 v219, v219
	v_exp_f32_e32 v158, v158
	v_exp_f32_e32 v232, v232
	v_exp_f32_e32 v159, v159
	v_exp_f32_e32 v233, v233
	v_add_f32_e32 v156, 1.0, v156
	v_add_f32_e32 v218, 1.0, v218
	v_add_f32_e32 v157, 1.0, v157
	v_add_f32_e32 v219, 1.0, v219
	v_add_f32_e32 v158, 1.0, v158
	v_add_f32_e32 v232, 1.0, v232
	v_add_f32_e32 v159, 1.0, v159
	v_add_f32_e32 v233, 1.0, v233
	v_rcp_f32_e32 v156, v156
	v_rcp_f32_e32 v218, v218
	v_rcp_f32_e32 v157, v157
	v_rcp_f32_e32 v219, v219
	v_rcp_f32_e32 v158, v158
	v_rcp_f32_e32 v232, v232
	v_rcp_f32_e32 v159, v159
	v_rcp_f32_e32 v233, v233
	v_mul_f32_e32 v4, v4, v156
	v_mul_f32_e32 v5, v5, v218
	v_mul_f32_e32 v6, v6, v157
	v_mul_f32_e32 v7, v7, v219
	v_mul_f32_e32 v0, v0, v158
	v_mul_f32_e32 v1, v1, v232
	v_mul_f32_e32 v2, v2, v159
	v_mul_f32_e32 v3, v3, v233
	v_add_f32_e32 v4, v4, v168
	v_add_f32_e32 v5, v5, v169
	v_add_f32_e32 v6, v6, v170
	v_add_f32_e32 v7, v7, v171
	v_add_f32_e32 v0, v0, v172
	v_add_f32_e32 v1, v1, v173
	v_add_f32_e32 v2, v2, v174
	v_add_f32_e32 v3, v3, v175
	s_add_u32 s22, s52, 0x160000
	s_addc_u32 s23, s53, 0
	global_store_dwordx4 v244, v[12:15], s[22:23] offset:0
	global_store_dwordx4 v244, v[8:11], s[22:23] offset:16
	global_store_dwordx4 v244, v[4:7], s[22:23] offset:512
	global_store_dwordx4 v244, v[0:3], s[22:23] offset:528
	s_branch .LBB0_394
.Lebr_z2:
	s_add_u32 s20, s4, 0x0
	s_addc_u32 s21, s5, 0
	global_load_dwordx4 v[128:131], v242, s[20:21] offset:0
	global_load_dwordx4 v[132:135], v242, s[20:21] offset:256
	s_add_u32 s22, s52, 0x0
	s_addc_u32 s23, s53, 0
	global_load_dwordx4 v[136:139], v244, s[22:23] offset:0
	global_load_dwordx4 v[140:143], v244, s[22:23] offset:16
	global_load_dwordx4 v[144:147], v244, s[22:23] offset:512
	global_load_dwordx4 v[148:151], v244, s[22:23] offset:528
	s_add_u32 s20, s4, 0x7e000
	s_addc_u32 s21, s5, 0
	global_load_dwordx4 v[152:155], v242, s[20:21] offset:0
	global_load_dwordx4 v[156:159], v242, s[20:21] offset:256
	s_add_u32 s22, s52, 0x20000
	s_addc_u32 s23, s53, 0
	global_load_dwordx4 v[160:163], v244, s[22:23] offset:0
	global_load_dwordx4 v[164:167], v244, s[22:23] offset:16
	global_load_dwordx4 v[168:171], v244, s[22:23] offset:512
	global_load_dwordx4 v[172:175], v244, s[22:23] offset:528
	s_add_u32 s20, s4, 0xfc000
	s_addc_u32 s21, s5, 0
	global_load_dwordx4 v[202:205], v242, s[20:21] offset:0
	global_load_dwordx4 v[206:209], v242, s[20:21] offset:256
	s_add_u32 s22, s52, 0x40000
	s_addc_u32 s23, s53, 0
	global_load_dwordx4 v[210:213], v244, s[22:23] offset:0
	global_load_dwordx4 v[214:217], v244, s[22:23] offset:16
	global_load_dwordx4 v[224:227], v244, s[22:23] offset:512
	global_load_dwordx4 v[228:231], v244, s[22:23] offset:528
	s_waitcnt vmcnt(12)
; __device__ __forceinline__ float lo16(unsigned u) { return __uint_as_float(u << 16); }
; __device__ __forceinline__ float hi16(unsigned u) { return __uint_as_float(u & 0xffff0000u); }
; __device__ __forceinline__ float sigmoidf_(float x) { return __builtin_amdgcn_rcpf(1.0f + __expf(-x)); }
; __device__ __forceinline__ unsigned cvt_pk_bf16(float lo, float hi) { return pk2(lo, hi); }
;     template <int Z> __device__ __forceinline__ void run(const f32x4 (&acc)[2][2][4][2], const Unit& u, int wr, int wc, int fr, int fq) const {
;     ...
;                 u32x4 graw[2][2]; f32x4 old0[2][2], old1[2][2];
; #pragma unroll
;                 for (int mm = 0; mm < 2; ++mm)
; #pragma unroll
;                     for (int bj = 0; bj < 2; ++bj) { const int row = row0 + ai * HALF + (m2 + mm) * 16, col = col0 + bj * HALF;
;                         graw[mm][bj] = *(const u32x4*)(proj + (size_t)row * NP + C_BR + Z * 2048 + col);
;                         if (Z > 0) { const float* mp = mix + (size_t)row * 2048 + col; old0[mm][bj] = *(const f32x4*)mp; old1[mm][bj] = *(const f32x4*)(mp + 4); } }
; #pragma unroll
;                 for (int mm = 0; mm < 2; ++mm)
; #pragma unroll
;                     for (int bj = 0; bj < 2; ++bj) { const int row = row0 + ai * HALF + (m2 + mm) * 16, col = col0 + bj * HALF;
;                         const u32x4 g = graw[mm][bj];
;                         f32x4 v0 = acc[ai][bj][m2 + mm][0], v1 = acc[ai][bj][m2 + mm][1];
;                         v0[0] *= sigmoidf_(lo16(g.x)); v0[1] *= sigmoidf_(hi16(g.x)); v0[2] *= sigmoidf_(lo16(g.y)); v0[3] *= sigmoidf_(hi16(g.y));
;                         v1[0] *= sigmoidf_(lo16(g.z)); v1[1] *= sigmoidf_(hi16(g.z)); v1[2] *= sigmoidf_(lo16(g.w)); v1[3] *= sigmoidf_(hi16(g.w));
;                         if (Z > 0) { v0 += old0[mm][bj]; v1 += old1[mm][bj]; }
;                         if (Z < 2) { float* mp = mix + (size_t)row * 2048 + col; *(f32x4*)mp = v0; *(f32x4*)(mp + 4) = v1; }
;                         else { u32x4 w; w.x = cvt_pk_bf16(v0[0], v0[1]); w.y = cvt_pk_bf16(v0[2], v0[3]); w.z = cvt_pk_bf16(v1[0], v1[1]); w.w = cvt_pk_bf16(v1[2], v1[3]);
;                             *(u32x4*)(mixb + (size_t)row * 2048 + col) = w; } }
	v_and_b32_e32 v218, 0xffff0000, v128
	v_lshlrev_b32_e32 v128, 16, v128
	v_and_b32_e32 v219, 0xffff0000, v129
	v_lshlrev_b32_e32 v129, 16, v129
	v_and_b32_e32 v232, 0xffff0000, v130
	v_lshlrev_b32_e32 v130, 16, v130
	v_and_b32_e32 v233, 0xffff0000, v131
	v_lshlrev_b32_e32 v131, 16, v131
	v_mul_f32_e32 v128, s19, v128
	v_mul_f32_e32 v218, s19, v218
	v_mul_f32_e32 v129, s19, v129
	v_mul_f32_e32 v219, s19, v219
	v_mul_f32_e32 v130, s19, v130
	v_mul_f32_e32 v232, s19, v232
	v_mul_f32_e32 v131, s19, v131
	v_mul_f32_e32 v233, s19, v233
	v_exp_f32_e32 v128, v128
	v_exp_f32_e32 v218, v218
	v_exp_f32_e32 v129, v129
	v_exp_f32_e32 v219, v219
	v_exp_f32_e32 v130, v130
	v_exp_f32_e32 v232, v232
	v_exp_f32_e32 v131, v131
	v_exp_f32_e32 v233, v233
	v_add_f32_e32 v128, 1.0, v128
	v_add_f32_e32 v218, 1.0, v218
	v_add_f32_e32 v129, 1.0, v129
	v_add_f32_e32 v219, 1.0, v219
	v_add_f32_e32 v130, 1.0, v130
	v_add_f32_e32 v232, 1.0, v232
	v_add_f32_e32 v131, 1.0, v131
	v_add_f32_e32 v233, 1.0, v233
	v_rcp_f32_e32 v128, v128
	v_rcp_f32_e32 v218, v218
	v_rcp_f32_e32 v129, v129
	v_rcp_f32_e32 v219, v219
	v_rcp_f32_e32 v130, v130
	v_rcp_f32_e32 v232, v232
	v_rcp_f32_e32 v131, v131
	v_rcp_f32_e32 v233, v233
	v_mul_f32_e32 v124, v124, v128
	v_mul_f32_e32 v125, v125, v218
	v_mul_f32_e32 v126, v126, v129
	v_mul_f32_e32 v127, v127, v219
	v_mul_f32_e32 v120, v120, v130
	v_mul_f32_e32 v121, v121, v232
	v_mul_f32_e32 v122, v122, v131
	v_mul_f32_e32 v123, v123, v233
	v_add_f32_e32 v124, v124, v136
	v_add_f32_e32 v125, v125, v137
	v_add_f32_e32 v126, v126, v138
	v_add_f32_e32 v127, v127, v139
	v_add_f32_e32 v120, v120, v140
	v_add_f32_e32 v121, v121, v141
	v_add_f32_e32 v122, v122, v142
	v_add_f32_e32 v123, v123, v143
	v_and_b32_e32 v218, 0xffff0000, v132
	v_lshlrev_b32_e32 v132, 16, v132
	v_and_b32_e32 v219, 0xffff0000, v133
	v_lshlrev_b32_e32 v133, 16, v133
	v_and_b32_e32 v232, 0xffff0000, v134
	v_lshlrev_b32_e32 v134, 16, v134
	v_and_b32_e32 v233, 0xffff0000, v135
	v_lshlrev_b32_e32 v135, 16, v135
	v_mul_f32_e32 v132, s19, v132
	v_mul_f32_e32 v218, s19, v218
	v_mul_f32_e32 v133, s19, v133
	v_mul_f32_e32 v219, s19, v219
	v_mul_f32_e32 v134, s19, v134
	v_mul_f32_e32 v232, s19, v232
	v_mul_f32_e32 v135, s19, v135
	v_mul_f32_e32 v233, s19, v233
	v_exp_f32_e32 v132, v132
	v_exp_f32_e32 v218, v218
	v_exp_f32_e32 v133, v133
	v_exp_f32_e32 v219, v219
	v_exp_f32_e32 v134, v134
	v_exp_f32_e32 v232, v232
	v_exp_f32_e32 v135, v135
	v_exp_f32_e32 v233, v233
	v_add_f32_e32 v132, 1.0, v132
	v_add_f32_e32 v218, 1.0, v218
	v_add_f32_e32 v133, 1.0, v133
	v_add_f32_e32 v219, 1.0, v219
	v_add_f32_e32 v134, 1.0, v134
	v_add_f32_e32 v232, 1.0, v232
	v_add_f32_e32 v135, 1.0, v135
	v_add_f32_e32 v233, 1.0, v233
	v_rcp_f32_e32 v132, v132
	v_rcp_f32_e32 v218, v218
	v_rcp_f32_e32 v133, v133
	v_rcp_f32_e32 v219, v219
	v_rcp_f32_e32 v134, v134
	v_rcp_f32_e32 v232, v232
	v_rcp_f32_e32 v135, v135
	v_rcp_f32_e32 v233, v233
	v_mul_f32_e32 v116, v116, v132
	v_mul_f32_e32 v117, v117, v218
	v_mul_f32_e32 v118, v118, v133
	v_mul_f32_e32 v119, v119, v219
	v_mul_f32_e32 v112, v112, v134
	v_mul_f32_e32 v113, v113, v232
	v_mul_f32_e32 v114, v114, v135
	v_mul_f32_e32 v115, v115, v233
	v_add_f32_e32 v116, v116, v144
	v_add_f32_e32 v117, v117, v145
	v_add_f32_e32 v118, v118, v146
	v_add_f32_e32 v119, v119, v147
	v_add_f32_e32 v112, v112, v148
	v_add_f32_e32 v113, v113, v149
	v_add_f32_e32 v114, v114, v150
	v_add_f32_e32 v115, v115, v151
	s_add_u32 s22, s52, 0x0
	s_addc_u32 s23, s53, 0
	v_cvt_pk_bf16_f32 v128, v124, v125
	v_cvt_pk_bf16_f32 v129, v126, v127
	v_cvt_pk_bf16_f32 v130, v120, v121
	v_cvt_pk_bf16_f32 v131, v122, v123
	global_store_dwordx4 v245, v[128:131], s[22:23] offset:0
	v_cvt_pk_bf16_f32 v132, v116, v117
	v_cvt_pk_bf16_f32 v133, v118, v119
	v_cvt_pk_bf16_f32 v134, v112, v113
	v_cvt_pk_bf16_f32 v135, v114, v115
	global_store_dwordx4 v245, v[132:135], s[22:23] offset:256
	s_add_u32 s20, s4, 0x17a000
	s_addc_u32 s21, s5, 0
	global_load_dwordx4 v[128:131], v242, s[20:21] offset:0
	global_load_dwordx4 v[132:135], v242, s[20:21] offset:256
	s_add_u32 s22, s52, 0x60000
	s_addc_u32 s23, s53, 0
	global_load_dwordx4 v[136:139], v244, s[22:23] offset:0
	global_load_dwordx4 v[140:143], v244, s[22:23] offset:16
	global_load_dwordx4 v[144:147], v244, s[22:23] offset:512
	global_load_dwordx4 v[148:151], v244, s[22:23] offset:528
	s_waitcnt vmcnt(14)
; __device__ __forceinline__ float lo16(unsigned u) { return __uint_as_float(u << 16); }
; __device__ __forceinline__ float hi16(unsigned u) { return __uint_as_float(u & 0xffff0000u); }
; __device__ __forceinline__ float sigmoidf_(float x) { return __builtin_amdgcn_rcpf(1.0f + __expf(-x)); }
; __device__ __forceinline__ unsigned cvt_pk_bf16(float lo, float hi) { return pk2(lo, hi); }
;     template <int Z> __device__ __forceinline__ void run(const f32x4 (&acc)[2][2][4][2], const Unit& u, int wr, int wc, int fr, int fq) const {
;     ...
;                 u32x4 graw[2][2]; f32x4 old0[2][2], old1[2][2];
; #pragma unroll
;                 for (int mm = 0; mm < 2; ++mm)
; #pragma unroll
;                     for (int bj = 0; bj < 2; ++bj) { const int row = row0 + ai * HALF + (m2 + mm) * 16, col = col0 + bj * HALF;
;                         graw[mm][bj] = *(const u32x4*)(proj + (size_t)row * NP + C_BR + Z * 2048 + col);
;                         if (Z > 0) { const float* mp = mix + (size_t)row * 2048 + col; old0[mm][bj] = *(const f32x4*)mp; old1[mm][bj] = *(const f32x4*)(mp + 4); } }
; #pragma unroll
;                 for (int mm = 0; mm < 2; ++mm)
; #pragma unroll
;                     for (int bj = 0; bj < 2; ++bj) { const int row = row0 + ai * HALF + (m2 + mm) * 16, col = col0 + bj * HALF;
;                         const u32x4 g = graw[mm][bj];
;                         f32x4 v0 = acc[ai][bj][m2 + mm][0], v1 = acc[ai][bj][m2 + mm][1];
;                         v0[0] *= sigmoidf_(lo16(g.x)); v0[1] *= sigmoidf_(hi16(g.x)); v0[2] *= sigmoidf_(lo16(g.y)); v0[3] *= sigmoidf_(hi16(g.y));
;                         v1[0] *= sigmoidf_(lo16(g.z)); v1[1] *= sigmoidf_(hi16(g.z)); v1[2] *= sigmoidf_(lo16(g.w)); v1[3] *= sigmoidf_(hi16(g.w));
;                         if (Z > 0) { v0 += old0[mm][bj]; v1 += old1[mm][bj]; }
;                         if (Z < 2) { float* mp = mix + (size_t)row * 2048 + col; *(f32x4*)mp = v0; *(f32x4*)(mp + 4) = v1; }
;                         else { u32x4 w; w.x = cvt_pk_bf16(v0[0], v0[1]); w.y = cvt_pk_bf16(v0[2], v0[3]); w.z = cvt_pk_bf16(v1[0], v1[1]); w.w = cvt_pk_bf16(v1[2], v1[3]);
;                             *(u32x4*)(mixb + (size_t)row * 2048 + col) = w; } }
	v_and_b32_e32 v218, 0xffff0000, v152
	v_lshlrev_b32_e32 v152, 16, v152
	v_and_b32_e32 v219, 0xffff0000, v153
	v_lshlrev_b32_e32 v153, 16, v153
	v_and_b32_e32 v232, 0xffff0000, v154
	v_lshlrev_b32_e32 v154, 16, v154
	v_and_b32_e32 v233, 0xffff0000, v155
	v_lshlrev_b32_e32 v155, 16, v155
	v_mul_f32_e32 v152, s19, v152
	v_mul_f32_e32 v218, s19, v218
	v_mul_f32_e32 v153, s19, v153
	v_mul_f32_e32 v219, s19, v219
	v_mul_f32_e32 v154, s19, v154
	v_mul_f32_e32 v232, s19, v232
	v_mul_f32_e32 v155, s19, v155
	v_mul_f32_e32 v233, s19, v233
	v_exp_f32_e32 v152, v152
	v_exp_f32_e32 v218, v218
	v_exp_f32_e32 v153, v153
	v_exp_f32_e32 v219, v219
	v_exp_f32_e32 v154, v154
	v_exp_f32_e32 v232, v232
	v_exp_f32_e32 v155, v155
	v_exp_f32_e32 v233, v233
	v_add_f32_e32 v152, 1.0, v152
	v_add_f32_e32 v218, 1.0, v218
	v_add_f32_e32 v153, 1.0, v153
	v_add_f32_e32 v219, 1.0, v219
	v_add_f32_e32 v154, 1.0, v154
	v_add_f32_e32 v232, 1.0, v232
	v_add_f32_e32 v155, 1.0, v155
	v_add_f32_e32 v233, 1.0, v233
	v_rcp_f32_e32 v152, v152
	v_rcp_f32_e32 v218, v218
	v_rcp_f32_e32 v153, v153
	v_rcp_f32_e32 v219, v219
	v_rcp_f32_e32 v154, v154
	v_rcp_f32_e32 v232, v232
	v_rcp_f32_e32 v155, v155
	v_rcp_f32_e32 v233, v233
	v_mul_f32_e32 v108, v108, v152
	v_mul_f32_e32 v109, v109, v218
	v_mul_f32_e32 v110, v110, v153
	v_mul_f32_e32 v111, v111, v219
	v_mul_f32_e32 v104, v104, v154
	v_mul_f32_e32 v105, v105, v232
	v_mul_f32_e32 v106, v106, v155
	v_mul_f32_e32 v107, v107, v233
	v_add_f32_e32 v108, v108, v160
	v_add_f32_e32 v109, v109, v161
	v_add_f32_e32 v110, v110, v162
	v_add_f32_e32 v111, v111, v163
	v_add_f32_e32 v104, v104, v164
	v_add_f32_e32 v105, v105, v165
	v_add_f32_e32 v106, v106, v166
	v_add_f32_e32 v107, v107, v167
	v_and_b32_e32 v218, 0xffff0000, v156
	v_lshlrev_b32_e32 v156, 16, v156
	v_and_b32_e32 v219, 0xffff0000, v157
	v_lshlrev_b32_e32 v157, 16, v157
	v_and_b32_e32 v232, 0xffff0000, v158
	v_lshlrev_b32_e32 v158, 16, v158
	v_and_b32_e32 v233, 0xffff0000, v159
	v_lshlrev_b32_e32 v159, 16, v159
	v_mul_f32_e32 v156, s19, v156
	v_mul_f32_e32 v218, s19, v218
	v_mul_f32_e32 v157, s19, v157
	v_mul_f32_e32 v219, s19, v219
	v_mul_f32_e32 v158, s19, v158
	v_mul_f32_e32 v232, s19, v232
	v_mul_f32_e32 v159, s19, v159
	v_mul_f32_e32 v233, s19, v233
	v_exp_f32_e32 v156, v156
	v_exp_f32_e32 v218, v218
	v_exp_f32_e32 v157, v157
	v_exp_f32_e32 v219, v219
	v_exp_f32_e32 v158, v158
	v_exp_f32_e32 v232, v232
	v_exp_f32_e32 v159, v159
	v_exp_f32_e32 v233, v233
	v_add_f32_e32 v156, 1.0, v156
	v_add_f32_e32 v218, 1.0, v218
	v_add_f32_e32 v157, 1.0, v157
	v_add_f32_e32 v219, 1.0, v219
	v_add_f32_e32 v158, 1.0, v158
	v_add_f32_e32 v232, 1.0, v232
	v_add_f32_e32 v159, 1.0, v159
	v_add_f32_e32 v233, 1.0, v233
	v_rcp_f32_e32 v156, v156
	v_rcp_f32_e32 v218, v218
	v_rcp_f32_e32 v157, v157
	v_rcp_f32_e32 v219, v219
	v_rcp_f32_e32 v158, v158
	v_rcp_f32_e32 v232, v232
	v_rcp_f32_e32 v159, v159
	v_rcp_f32_e32 v233, v233
	v_mul_f32_e32 v100, v100, v156
	v_mul_f32_e32 v101, v101, v218
	v_mul_f32_e32 v102, v102, v157
	v_mul_f32_e32 v103, v103, v219
	v_mul_f32_e32 v96, v96, v158
	v_mul_f32_e32 v97, v97, v232
	v_mul_f32_e32 v98, v98, v159
	v_mul_f32_e32 v99, v99, v233
	v_add_f32_e32 v100, v100, v168
	v_add_f32_e32 v101, v101, v169
	v_add_f32_e32 v102, v102, v170
	v_add_f32_e32 v103, v103, v171
	v_add_f32_e32 v96, v96, v172
	v_add_f32_e32 v97, v97, v173
	v_add_f32_e32 v98, v98, v174
	v_add_f32_e32 v99, v99, v175
	s_add_u32 s22, s52, 0x10000
	s_addc_u32 s23, s53, 0
	v_cvt_pk_bf16_f32 v152, v108, v109
	v_cvt_pk_bf16_f32 v153, v110, v111
	v_cvt_pk_bf16_f32 v154, v104, v105
	v_cvt_pk_bf16_f32 v155, v106, v107
	global_store_dwordx4 v245, v[152:155], s[22:23] offset:0
	v_cvt_pk_bf16_f32 v156, v100, v101
	v_cvt_pk_bf16_f32 v157, v102, v103
	v_cvt_pk_bf16_f32 v158, v96, v97
	v_cvt_pk_bf16_f32 v159, v98, v99
	global_store_dwordx4 v245, v[156:159], s[22:23] offset:256
	s_add_u32 s20, s4, 0x3f0000
	s_addc_u32 s21, s5, 0
	global_load_dwordx4 v[152:155], v242, s[20:21] offset:0
	global_load_dwordx4 v[156:159], v242, s[20:21] offset:256
	s_add_u32 s22, s52, 0x100000
	s_addc_u32 s23, s53, 0
	global_load_dwordx4 v[160:163], v244, s[22:23] offset:0
	global_load_dwordx4 v[164:167], v244, s[22:23] offset:16
	global_load_dwordx4 v[168:171], v244, s[22:23] offset:512
	global_load_dwordx4 v[172:175], v244, s[22:23] offset:528
	s_waitcnt vmcnt(16)
; __device__ __forceinline__ float lo16(unsigned u) { return __uint_as_float(u << 16); }
; __device__ __forceinline__ float hi16(unsigned u) { return __uint_as_float(u & 0xffff0000u); }
; __device__ __forceinline__ float sigmoidf_(float x) { return __builtin_amdgcn_rcpf(1.0f + __expf(-x)); }
; __device__ __forceinline__ unsigned cvt_pk_bf16(float lo, float hi) { return pk2(lo, hi); }
;     template <int Z> __device__ __forceinline__ void run(const f32x4 (&acc)[2][2][4][2], const Unit& u, int wr, int wc, int fr, int fq) const {
;     ...
;                 u32x4 graw[2][2]; f32x4 old0[2][2], old1[2][2];
; #pragma unroll
;                 for (int mm = 0; mm < 2; ++mm)
; #pragma unroll
;                     for (int bj = 0; bj < 2; ++bj) { const int row = row0 + ai * HALF + (m2 + mm) * 16, col = col0 + bj * HALF;
;                         graw[mm][bj] = *(const u32x4*)(proj + (size_t)row * NP + C_BR + Z * 2048 + col);
;                         if (Z > 0) { const float* mp = mix + (size_t)row * 2048 + col; old0[mm][bj] = *(const f32x4*)mp; old1[mm][bj] = *(const f32x4*)(mp + 4); } }
; #pragma unroll
;                 for (int mm = 0; mm < 2; ++mm)
; #pragma unroll
;                     for (int bj = 0; bj < 2; ++bj) { const int row = row0 + ai * HALF + (m2 + mm) * 16, col = col0 + bj * HALF;
;                         const u32x4 g = graw[mm][bj];
;                         f32x4 v0 = acc[ai][bj][m2 + mm][0], v1 = acc[ai][bj][m2 + mm][1];
;                         v0[0] *= sigmoidf_(lo16(g.x)); v0[1] *= sigmoidf_(hi16(g.x)); v0[2] *= sigmoidf_(lo16(g.y)); v0[3] *= sigmoidf_(hi16(g.y));
;                         v1[0] *= sigmoidf_(lo16(g.z)); v1[1] *= sigmoidf_(hi16(g.z)); v1[2] *= sigmoidf_(lo16(g.w)); v1[3] *= sigmoidf_(hi16(g.w));
;                         if (Z > 0) { v0 += old0[mm][bj]; v1 += old1[mm][bj]; }
;                         if (Z < 2) { float* mp = mix + (size_t)row * 2048 + col; *(f32x4*)mp = v0; *(f32x4*)(mp + 4) = v1; }
;                         else { u32x4 w; w.x = cvt_pk_bf16(v0[0], v0[1]); w.y = cvt_pk_bf16(v0[2], v0[3]); w.z = cvt_pk_bf16(v1[0], v1[1]); w.w = cvt_pk_bf16(v1[2], v1[3]);
;                             *(u32x4*)(mixb + (size_t)row * 2048 + col) = w; } }
	v_and_b32_e32 v218, 0xffff0000, v202
	v_lshlrev_b32_e32 v202, 16, v202
	v_and_b32_e32 v219, 0xffff0000, v203
	v_lshlrev_b32_e32 v203, 16, v203
	v_and_b32_e32 v232, 0xffff0000, v204
	v_lshlrev_b32_e32 v204, 16, v204
	v_and_b32_e32 v233, 0xffff0000, v205
	v_lshlrev_b32_e32 v205, 16, v205
	v_mul_f32_e32 v202, s19, v202
	v_mul_f32_e32 v218, s19, v218
	v_mul_f32_e32 v203, s19, v203
	v_mul_f32_e32 v219, s19, v219
	v_mul_f32_e32 v204, s19, v204
	v_mul_f32_e32 v232, s19, v232
	v_mul_f32_e32 v205, s19, v205
	v_mul_f32_e32 v233, s19, v233
	v_exp_f32_e32 v202, v202
	v_exp_f32_e32 v218, v218
	v_exp_f32_e32 v203, v203
	v_exp_f32_e32 v219, v219
	v_exp_f32_e32 v204, v204
	v_exp_f32_e32 v232, v232
	v_exp_f32_e32 v205, v205
	v_exp_f32_e32 v233, v233
	v_add_f32_e32 v202, 1.0, v202
	v_add_f32_e32 v218, 1.0, v218
	v_add_f32_e32 v203, 1.0, v203
	v_add_f32_e32 v219, 1.0, v219
	v_add_f32_e32 v204, 1.0, v204
	v_add_f32_e32 v232, 1.0, v232
	v_add_f32_e32 v205, 1.0, v205
	v_add_f32_e32 v233, 1.0, v233
	v_rcp_f32_e32 v202, v202
	v_rcp_f32_e32 v218, v218
	v_rcp_f32_e32 v203, v203
	v_rcp_f32_e32 v219, v219
	v_rcp_f32_e32 v204, v204
	v_rcp_f32_e32 v232, v232
	v_rcp_f32_e32 v205, v205
	v_rcp_f32_e32 v233, v233
	v_mul_f32_e32 v92, v92, v202
	v_mul_f32_e32 v93, v93, v218
	v_mul_f32_e32 v94, v94, v203
	v_mul_f32_e32 v95, v95, v219
	v_mul_f32_e32 v88, v88, v204
	v_mul_f32_e32 v89, v89, v232
	v_mul_f32_e32 v90, v90, v205
	v_mul_f32_e32 v91, v91, v233
	v_add_f32_e32 v92, v92, v210
	v_add_f32_e32 v93, v93, v211
	v_add_f32_e32 v94, v94, v212
	v_add_f32_e32 v95, v95, v213
	v_add_f32_e32 v88, v88, v214
	v_add_f32_e32 v89, v89, v215
	v_add_f32_e32 v90, v90, v216
	v_add_f32_e32 v91, v91, v217
	v_and_b32_e32 v218, 0xffff0000, v206
	v_lshlrev_b32_e32 v206, 16, v206
	v_and_b32_e32 v219, 0xffff0000, v207
	v_lshlrev_b32_e32 v207, 16, v207
	v_and_b32_e32 v232, 0xffff0000, v208
	v_lshlrev_b32_e32 v208, 16, v208
	v_and_b32_e32 v233, 0xffff0000, v209
	v_lshlrev_b32_e32 v209, 16, v209
	v_mul_f32_e32 v206, s19, v206
	v_mul_f32_e32 v218, s19, v218
	v_mul_f32_e32 v207, s19, v207
	v_mul_f32_e32 v219, s19, v219
	v_mul_f32_e32 v208, s19, v208
	v_mul_f32_e32 v232, s19, v232
	v_mul_f32_e32 v209, s19, v209
	v_mul_f32_e32 v233, s19, v233
	v_exp_f32_e32 v206, v206
	v_exp_f32_e32 v218, v218
	v_exp_f32_e32 v207, v207
	v_exp_f32_e32 v219, v219
	v_exp_f32_e32 v208, v208
	v_exp_f32_e32 v232, v232
	v_exp_f32_e32 v209, v209
	v_exp_f32_e32 v233, v233
	v_add_f32_e32 v206, 1.0, v206
	v_add_f32_e32 v218, 1.0, v218
	v_add_f32_e32 v207, 1.0, v207
	v_add_f32_e32 v219, 1.0, v219
	v_add_f32_e32 v208, 1.0, v208
	v_add_f32_e32 v232, 1.0, v232
	v_add_f32_e32 v209, 1.0, v209
	v_add_f32_e32 v233, 1.0, v233
	v_rcp_f32_e32 v206, v206
	v_rcp_f32_e32 v218, v218
	v_rcp_f32_e32 v207, v207
	v_rcp_f32_e32 v219, v219
	v_rcp_f32_e32 v208, v208
	v_rcp_f32_e32 v232, v232
	v_rcp_f32_e32 v209, v209
	v_rcp_f32_e32 v233, v233
	v_mul_f32_e32 v84, v84, v206
	v_mul_f32_e32 v85, v85, v218
	v_mul_f32_e32 v86, v86, v207
	v_mul_f32_e32 v87, v87, v219
	v_mul_f32_e32 v80, v80, v208
	v_mul_f32_e32 v81, v81, v232
	v_mul_f32_e32 v82, v82, v209
	v_mul_f32_e32 v83, v83, v233
	v_add_f32_e32 v84, v84, v224
	v_add_f32_e32 v85, v85, v225
	v_add_f32_e32 v86, v86, v226
	v_add_f32_e32 v87, v87, v227
	v_add_f32_e32 v80, v80, v228
	v_add_f32_e32 v81, v81, v229
	v_add_f32_e32 v82, v82, v230
	v_add_f32_e32 v83, v83, v231
	s_add_u32 s22, s52, 0x20000
	s_addc_u32 s23, s53, 0
	v_cvt_pk_bf16_f32 v202, v92, v93
	v_cvt_pk_bf16_f32 v203, v94, v95
	v_cvt_pk_bf16_f32 v204, v88, v89
	v_cvt_pk_bf16_f32 v205, v90, v91
	global_store_dwordx4 v245, v[202:205], s[22:23] offset:0
	v_cvt_pk_bf16_f32 v206, v84, v85
	v_cvt_pk_bf16_f32 v207, v86, v87
	v_cvt_pk_bf16_f32 v208, v80, v81
	v_cvt_pk_bf16_f32 v209, v82, v83
	global_store_dwordx4 v245, v[206:209], s[22:23] offset:256
	s_add_u32 s20, s4, 0x46e000
	s_addc_u32 s21, s5, 0
	global_load_dwordx4 v[202:205], v242, s[20:21] offset:0
	global_load_dwordx4 v[206:209], v242, s[20:21] offset:256
	s_add_u32 s22, s52, 0x120000
	s_addc_u32 s23, s53, 0
	global_load_dwordx4 v[210:213], v244, s[22:23] offset:0
	global_load_dwordx4 v[214:217], v244, s[22:23] offset:16
	global_load_dwordx4 v[224:227], v244, s[22:23] offset:512
	global_load_dwordx4 v[228:231], v244, s[22:23] offset:528
	s_waitcnt vmcnt(16)
; __device__ __forceinline__ float lo16(unsigned u) { return __uint_as_float(u << 16); }
; __device__ __forceinline__ float hi16(unsigned u) { return __uint_as_float(u & 0xffff0000u); }
; __device__ __forceinline__ float sigmoidf_(float x) { return __builtin_amdgcn_rcpf(1.0f + __expf(-x)); }
; __device__ __forceinline__ unsigned cvt_pk_bf16(float lo, float hi) { return pk2(lo, hi); }
;     template <int Z> __device__ __forceinline__ void run(const f32x4 (&acc)[2][2][4][2], const Unit& u, int wr, int wc, int fr, int fq) const {
;     ...
;                 u32x4 graw[2][2]; f32x4 old0[2][2], old1[2][2];
; #pragma unroll
;                 for (int mm = 0; mm < 2; ++mm)
; #pragma unroll
;                     for (int bj = 0; bj < 2; ++bj) { const int row = row0 + ai * HALF + (m2 + mm) * 16, col = col0 + bj * HALF;
;                         graw[mm][bj] = *(const u32x4*)(proj + (size_t)row * NP + C_BR + Z * 2048 + col);
;                         if (Z > 0) { const float* mp = mix + (size_t)row * 2048 + col; old0[mm][bj] = *(const f32x4*)mp; old1[mm][bj] = *(const f32x4*)(mp + 4); } }
; #pragma unroll
;                 for (int mm = 0; mm < 2; ++mm)
; #pragma unroll
;                     for (int bj = 0; bj < 2; ++bj) { const int row = row0 + ai * HALF + (m2 + mm) * 16, col = col0 + bj * HALF;
;                         const u32x4 g = graw[mm][bj];
;                         f32x4 v0 = acc[ai][bj][m2 + mm][0], v1 = acc[ai][bj][m2 + mm][1];
;                         v0[0] *= sigmoidf_(lo16(g.x)); v0[1] *= sigmoidf_(hi16(g.x)); v0[2] *= sigmoidf_(lo16(g.y)); v0[3] *= sigmoidf_(hi16(g.y));
;                         v1[0] *= sigmoidf_(lo16(g.z)); v1[1] *= sigmoidf_(hi16(g.z)); v1[2] *= sigmoidf_(lo16(g.w)); v1[3] *= sigmoidf_(hi16(g.w));
;                         if (Z > 0) { v0 += old0[mm][bj]; v1 += old1[mm][bj]; }
;                         if (Z < 2) { float* mp = mix + (size_t)row * 2048 + col; *(f32x4*)mp = v0; *(f32x4*)(mp + 4) = v1; }
;                         else { u32x4 w; w.x = cvt_pk_bf16(v0[0], v0[1]); w.y = cvt_pk_bf16(v0[2], v0[3]); w.z = cvt_pk_bf16(v1[0], v1[1]); w.w = cvt_pk_bf16(v1[2], v1[3]);
;                             *(u32x4*)(mixb + (size_t)row * 2048 + col) = w; } }
	v_and_b32_e32 v218, 0xffff0000, v128
	v_lshlrev_b32_e32 v128, 16, v128
	v_and_b32_e32 v219, 0xffff0000, v129
	v_lshlrev_b32_e32 v129, 16, v129
	v_and_b32_e32 v232, 0xffff0000, v130
	v_lshlrev_b32_e32 v130, 16, v130
	v_and_b32_e32 v233, 0xffff0000, v131
	v_lshlrev_b32_e32 v131, 16, v131
	v_mul_f32_e32 v128, s19, v128
	v_mul_f32_e32 v218, s19, v218
	v_mul_f32_e32 v129, s19, v129
	v_mul_f32_e32 v219, s19, v219
	v_mul_f32_e32 v130, s19, v130
	v_mul_f32_e32 v232, s19, v232
	v_mul_f32_e32 v131, s19, v131
	v_mul_f32_e32 v233, s19, v233
	v_exp_f32_e32 v128, v128
	v_exp_f32_e32 v218, v218
	v_exp_f32_e32 v129, v129
	v_exp_f32_e32 v219, v219
	v_exp_f32_e32 v130, v130
	v_exp_f32_e32 v232, v232
	v_exp_f32_e32 v131, v131
	v_exp_f32_e32 v233, v233
	v_add_f32_e32 v128, 1.0, v128
	v_add_f32_e32 v218, 1.0, v218
	v_add_f32_e32 v129, 1.0, v129
	v_add_f32_e32 v219, 1.0, v219
	v_add_f32_e32 v130, 1.0, v130
	v_add_f32_e32 v232, 1.0, v232
	v_add_f32_e32 v131, 1.0, v131
	v_add_f32_e32 v233, 1.0, v233
	v_rcp_f32_e32 v128, v128
	v_rcp_f32_e32 v218, v218
	v_rcp_f32_e32 v129, v129
	v_rcp_f32_e32 v219, v219
	v_rcp_f32_e32 v130, v130
	v_rcp_f32_e32 v232, v232
	v_rcp_f32_e32 v131, v131
	v_rcp_f32_e32 v233, v233
	v_mul_f32_e32 v76, v76, v128
	v_mul_f32_e32 v77, v77, v218
	v_mul_f32_e32 v78, v78, v129
	v_mul_f32_e32 v79, v79, v219
	v_mul_f32_e32 v72, v72, v130
	v_mul_f32_e32 v73, v73, v232
	v_mul_f32_e32 v74, v74, v131
	v_mul_f32_e32 v75, v75, v233
	v_add_f32_e32 v76, v76, v136
	v_add_f32_e32 v77, v77, v137
	v_add_f32_e32 v78, v78, v138
	v_add_f32_e32 v79, v79, v139
	v_add_f32_e32 v72, v72, v140
	v_add_f32_e32 v73, v73, v141
	v_add_f32_e32 v74, v74, v142
	v_add_f32_e32 v75, v75, v143
	v_and_b32_e32 v218, 0xffff0000, v132
	v_lshlrev_b32_e32 v132, 16, v132
	v_and_b32_e32 v219, 0xffff0000, v133
	v_lshlrev_b32_e32 v133, 16, v133
	v_and_b32_e32 v232, 0xffff0000, v134
	v_lshlrev_b32_e32 v134, 16, v134
	v_and_b32_e32 v233, 0xffff0000, v135
	v_lshlrev_b32_e32 v135, 16, v135
	v_mul_f32_e32 v132, s19, v132
	v_mul_f32_e32 v218, s19, v218
	v_mul_f32_e32 v133, s19, v133
	v_mul_f32_e32 v219, s19, v219
	v_mul_f32_e32 v134, s19, v134
	v_mul_f32_e32 v232, s19, v232
	v_mul_f32_e32 v135, s19, v135
	v_mul_f32_e32 v233, s19, v233
	v_exp_f32_e32 v132, v132
	v_exp_f32_e32 v218, v218
	v_exp_f32_e32 v133, v133
	v_exp_f32_e32 v219, v219
	v_exp_f32_e32 v134, v134
	v_exp_f32_e32 v232, v232
	v_exp_f32_e32 v135, v135
	v_exp_f32_e32 v233, v233
	v_add_f32_e32 v132, 1.0, v132
	v_add_f32_e32 v218, 1.0, v218
	v_add_f32_e32 v133, 1.0, v133
	v_add_f32_e32 v219, 1.0, v219
	v_add_f32_e32 v134, 1.0, v134
	v_add_f32_e32 v232, 1.0, v232
	v_add_f32_e32 v135, 1.0, v135
	v_add_f32_e32 v233, 1.0, v233
	v_rcp_f32_e32 v132, v132
	v_rcp_f32_e32 v218, v218
	v_rcp_f32_e32 v133, v133
	v_rcp_f32_e32 v219, v219
	v_rcp_f32_e32 v134, v134
	v_rcp_f32_e32 v232, v232
	v_rcp_f32_e32 v135, v135
	v_rcp_f32_e32 v233, v233
	v_mul_f32_e32 v68, v68, v132
	v_mul_f32_e32 v69, v69, v218
	v_mul_f32_e32 v70, v70, v133
	v_mul_f32_e32 v71, v71, v219
	v_mul_f32_e32 v64, v64, v134
	v_mul_f32_e32 v65, v65, v232
	v_mul_f32_e32 v66, v66, v135
	v_mul_f32_e32 v67, v67, v233
	v_add_f32_e32 v68, v68, v144
	v_add_f32_e32 v69, v69, v145
	v_add_f32_e32 v70, v70, v146
	v_add_f32_e32 v71, v71, v147
	v_add_f32_e32 v64, v64, v148
	v_add_f32_e32 v65, v65, v149
	v_add_f32_e32 v66, v66, v150
	v_add_f32_e32 v67, v67, v151
	s_add_u32 s22, s52, 0x30000
	s_addc_u32 s23, s53, 0
	v_cvt_pk_bf16_f32 v128, v76, v77
	v_cvt_pk_bf16_f32 v129, v78, v79
	v_cvt_pk_bf16_f32 v130, v72, v73
	v_cvt_pk_bf16_f32 v131, v74, v75
	global_store_dwordx4 v245, v[128:131], s[22:23] offset:0
	v_cvt_pk_bf16_f32 v132, v68, v69
	v_cvt_pk_bf16_f32 v133, v70, v71
	v_cvt_pk_bf16_f32 v134, v64, v65
	v_cvt_pk_bf16_f32 v135, v66, v67
	global_store_dwordx4 v245, v[132:135], s[22:23] offset:256
	s_add_u32 s20, s4, 0x4ec000
	s_addc_u32 s21, s5, 0
	global_load_dwordx4 v[128:131], v242, s[20:21] offset:0
	global_load_dwordx4 v[132:135], v242, s[20:21] offset:256
	s_add_u32 s22, s52, 0x140000
	s_addc_u32 s23, s53, 0
	global_load_dwordx4 v[136:139], v244, s[22:23] offset:0
	global_load_dwordx4 v[140:143], v244, s[22:23] offset:16
	global_load_dwordx4 v[144:147], v244, s[22:23] offset:512
	global_load_dwordx4 v[148:151], v244, s[22:23] offset:528
	s_waitcnt vmcnt(16)
; __device__ __forceinline__ float lo16(unsigned u) { return __uint_as_float(u << 16); }
; __device__ __forceinline__ float hi16(unsigned u) { return __uint_as_float(u & 0xffff0000u); }
; __device__ __forceinline__ float sigmoidf_(float x) { return __builtin_amdgcn_rcpf(1.0f + __expf(-x)); }
; __device__ __forceinline__ unsigned cvt_pk_bf16(float lo, float hi) { return pk2(lo, hi); }
;     template <int Z> __device__ __forceinline__ void run(const f32x4 (&acc)[2][2][4][2], const Unit& u, int wr, int wc, int fr, int fq) const {
;     ...
;                 u32x4 graw[2][2]; f32x4 old0[2][2], old1[2][2];
; #pragma unroll
;                 for (int mm = 0; mm < 2; ++mm)
; #pragma unroll
;                     for (int bj = 0; bj < 2; ++bj) { const int row = row0 + ai * HALF + (m2 + mm) * 16, col = col0 + bj * HALF;
;                         graw[mm][bj] = *(const u32x4*)(proj + (size_t)row * NP + C_BR + Z * 2048 + col);
;                         if (Z > 0) { const float* mp = mix + (size_t)row * 2048 + col; old0[mm][bj] = *(const f32x4*)mp; old1[mm][bj] = *(const f32x4*)(mp + 4); } }
; #pragma unroll
;                 for (int mm = 0; mm < 2; ++mm)
; #pragma unroll
;                     for (int bj = 0; bj < 2; ++bj) { const int row = row0 + ai * HALF + (m2 + mm) * 16, col = col0 + bj * HALF;
;                         const u32x4 g = graw[mm][bj];
;                         f32x4 v0 = acc[ai][bj][m2 + mm][0], v1 = acc[ai][bj][m2 + mm][1];
;                         v0[0] *= sigmoidf_(lo16(g.x)); v0[1] *= sigmoidf_(hi16(g.x)); v0[2] *= sigmoidf_(lo16(g.y)); v0[3] *= sigmoidf_(hi16(g.y));
;                         v1[0] *= sigmoidf_(lo16(g.z)); v1[1] *= sigmoidf_(hi16(g.z)); v1[2] *= sigmoidf_(lo16(g.w)); v1[3] *= sigmoidf_(hi16(g.w));
;                         if (Z > 0) { v0 += old0[mm][bj]; v1 += old1[mm][bj]; }
;                         if (Z < 2) { float* mp = mix + (size_t)row * 2048 + col; *(f32x4*)mp = v0; *(f32x4*)(mp + 4) = v1; }
;                         else { u32x4 w; w.x = cvt_pk_bf16(v0[0], v0[1]); w.y = cvt_pk_bf16(v0[2], v0[3]); w.z = cvt_pk_bf16(v1[0], v1[1]); w.w = cvt_pk_bf16(v1[2], v1[3]);
;                             *(u32x4*)(mixb + (size_t)row * 2048 + col) = w; } }
	v_and_b32_e32 v218, 0xffff0000, v152
	v_lshlrev_b32_e32 v152, 16, v152
	v_and_b32_e32 v219, 0xffff0000, v153
	v_lshlrev_b32_e32 v153, 16, v153
	v_and_b32_e32 v232, 0xffff0000, v154
	v_lshlrev_b32_e32 v154, 16, v154
	v_and_b32_e32 v233, 0xffff0000, v155
	v_lshlrev_b32_e32 v155, 16, v155
	v_mul_f32_e32 v152, s19, v152
	v_mul_f32_e32 v218, s19, v218
	v_mul_f32_e32 v153, s19, v153
	v_mul_f32_e32 v219, s19, v219
	v_mul_f32_e32 v154, s19, v154
	v_mul_f32_e32 v232, s19, v232
	v_mul_f32_e32 v155, s19, v155
	v_mul_f32_e32 v233, s19, v233
	v_exp_f32_e32 v152, v152
	v_exp_f32_e32 v218, v218
	v_exp_f32_e32 v153, v153
	v_exp_f32_e32 v219, v219
	v_exp_f32_e32 v154, v154
	v_exp_f32_e32 v232, v232
	v_exp_f32_e32 v155, v155
	v_exp_f32_e32 v233, v233
	v_add_f32_e32 v152, 1.0, v152
	v_add_f32_e32 v218, 1.0, v218
	v_add_f32_e32 v153, 1.0, v153
	v_add_f32_e32 v219, 1.0, v219
	v_add_f32_e32 v154, 1.0, v154
	v_add_f32_e32 v232, 1.0, v232
	v_add_f32_e32 v155, 1.0, v155
	v_add_f32_e32 v233, 1.0, v233
	v_rcp_f32_e32 v152, v152
	v_rcp_f32_e32 v218, v218
	v_rcp_f32_e32 v153, v153
	v_rcp_f32_e32 v219, v219
	v_rcp_f32_e32 v154, v154
	v_rcp_f32_e32 v232, v232
	v_rcp_f32_e32 v155, v155
	v_rcp_f32_e32 v233, v233
	v_mul_f32_e32 v60, v60, v152
	v_mul_f32_e32 v61, v61, v218
	v_mul_f32_e32 v62, v62, v153
	v_mul_f32_e32 v63, v63, v219
	v_mul_f32_e32 v56, v56, v154
	v_mul_f32_e32 v57, v57, v232
	v_mul_f32_e32 v58, v58, v155
	v_mul_f32_e32 v59, v59, v233
	v_add_f32_e32 v60, v60, v160
	v_add_f32_e32 v61, v61, v161
	v_add_f32_e32 v62, v62, v162
	v_add_f32_e32 v63, v63, v163
	v_add_f32_e32 v56, v56, v164
	v_add_f32_e32 v57, v57, v165
	v_add_f32_e32 v58, v58, v166
	v_add_f32_e32 v59, v59, v167
	v_and_b32_e32 v218, 0xffff0000, v156
	v_lshlrev_b32_e32 v156, 16, v156
	v_and_b32_e32 v219, 0xffff0000, v157
	v_lshlrev_b32_e32 v157, 16, v157
	v_and_b32_e32 v232, 0xffff0000, v158
	v_lshlrev_b32_e32 v158, 16, v158
	v_and_b32_e32 v233, 0xffff0000, v159
	v_lshlrev_b32_e32 v159, 16, v159
	v_mul_f32_e32 v156, s19, v156
	v_mul_f32_e32 v218, s19, v218
	v_mul_f32_e32 v157, s19, v157
	v_mul_f32_e32 v219, s19, v219
	v_mul_f32_e32 v158, s19, v158
	v_mul_f32_e32 v232, s19, v232
	v_mul_f32_e32 v159, s19, v159
	v_mul_f32_e32 v233, s19, v233
	v_exp_f32_e32 v156, v156
	v_exp_f32_e32 v218, v218
	v_exp_f32_e32 v157, v157
	v_exp_f32_e32 v219, v219
	v_exp_f32_e32 v158, v158
	v_exp_f32_e32 v232, v232
	v_exp_f32_e32 v159, v159
	v_exp_f32_e32 v233, v233
	v_add_f32_e32 v156, 1.0, v156
	v_add_f32_e32 v218, 1.0, v218
	v_add_f32_e32 v157, 1.0, v157
	v_add_f32_e32 v219, 1.0, v219
	v_add_f32_e32 v158, 1.0, v158
	v_add_f32_e32 v232, 1.0, v232
	v_add_f32_e32 v159, 1.0, v159
	v_add_f32_e32 v233, 1.0, v233
	v_rcp_f32_e32 v156, v156
	v_rcp_f32_e32 v218, v218
	v_rcp_f32_e32 v157, v157
	v_rcp_f32_e32 v219, v219
	v_rcp_f32_e32 v158, v158
	v_rcp_f32_e32 v232, v232
	v_rcp_f32_e32 v159, v159
	v_rcp_f32_e32 v233, v233
	v_mul_f32_e32 v52, v52, v156
	v_mul_f32_e32 v53, v53, v218
	v_mul_f32_e32 v54, v54, v157
	v_mul_f32_e32 v55, v55, v219
	v_mul_f32_e32 v48, v48, v158
	v_mul_f32_e32 v49, v49, v232
	v_mul_f32_e32 v50, v50, v159
	v_mul_f32_e32 v51, v51, v233
	v_add_f32_e32 v52, v52, v168
	v_add_f32_e32 v53, v53, v169
	v_add_f32_e32 v54, v54, v170
	v_add_f32_e32 v55, v55, v171
	v_add_f32_e32 v48, v48, v172
	v_add_f32_e32 v49, v49, v173
	v_add_f32_e32 v50, v50, v174
	v_add_f32_e32 v51, v51, v175
	s_add_u32 s22, s52, 0x80000
	s_addc_u32 s23, s53, 0
	v_cvt_pk_bf16_f32 v152, v60, v61
	v_cvt_pk_bf16_f32 v153, v62, v63
	v_cvt_pk_bf16_f32 v154, v56, v57
	v_cvt_pk_bf16_f32 v155, v58, v59
	global_store_dwordx4 v245, v[152:155], s[22:23] offset:0
	v_cvt_pk_bf16_f32 v156, v52, v53
	v_cvt_pk_bf16_f32 v157, v54, v55
	v_cvt_pk_bf16_f32 v158, v48, v49
	v_cvt_pk_bf16_f32 v159, v50, v51
	global_store_dwordx4 v245, v[156:159], s[22:23] offset:256
	s_add_u32 s20, s4, 0x56a000
	s_addc_u32 s21, s5, 0
	global_load_dwordx4 v[152:155], v242, s[20:21] offset:0
	global_load_dwordx4 v[156:159], v242, s[20:21] offset:256
	s_add_u32 s22, s52, 0x160000
	s_addc_u32 s23, s53, 0
	global_load_dwordx4 v[160:163], v244, s[22:23] offset:0
	global_load_dwordx4 v[164:167], v244, s[22:23] offset:16
	global_load_dwordx4 v[168:171], v244, s[22:23] offset:512
	global_load_dwordx4 v[172:175], v244, s[22:23] offset:528
	s_waitcnt vmcnt(16)
; __device__ __forceinline__ float lo16(unsigned u) { return __uint_as_float(u << 16); }
; __device__ __forceinline__ float hi16(unsigned u) { return __uint_as_float(u & 0xffff0000u); }
; __device__ __forceinline__ float sigmoidf_(float x) { return __builtin_amdgcn_rcpf(1.0f + __expf(-x)); }
; __device__ __forceinline__ unsigned cvt_pk_bf16(float lo, float hi) { return pk2(lo, hi); }
;     template <int Z> __device__ __forceinline__ void run(const f32x4 (&acc)[2][2][4][2], const Unit& u, int wr, int wc, int fr, int fq) const {
;     ...
;                 u32x4 graw[2][2]; f32x4 old0[2][2], old1[2][2];
; #pragma unroll
;                 for (int mm = 0; mm < 2; ++mm)
; #pragma unroll
;                     for (int bj = 0; bj < 2; ++bj) { const int row = row0 + ai * HALF + (m2 + mm) * 16, col = col0 + bj * HALF;
;                         graw[mm][bj] = *(const u32x4*)(proj + (size_t)row * NP + C_BR + Z * 2048 + col);
;                         if (Z > 0) { const float* mp = mix + (size_t)row * 2048 + col; old0[mm][bj] = *(const f32x4*)mp; old1[mm][bj] = *(const f32x4*)(mp + 4); } }
; #pragma unroll
;                 for (int mm = 0; mm < 2; ++mm)
; #pragma unroll
;                     for (int bj = 0; bj < 2; ++bj) { const int row = row0 + ai * HALF + (m2 + mm) * 16, col = col0 + bj * HALF;
;                         const u32x4 g = graw[mm][bj];
;                         f32x4 v0 = acc[ai][bj][m2 + mm][0], v1 = acc[ai][bj][m2 + mm][1];
;                         v0[0] *= sigmoidf_(lo16(g.x)); v0[1] *= sigmoidf_(hi16(g.x)); v0[2] *= sigmoidf_(lo16(g.y)); v0[3] *= sigmoidf_(hi16(g.y));
;                         v1[0] *= sigmoidf_(lo16(g.z)); v1[1] *= sigmoidf_(hi16(g.z)); v1[2] *= sigmoidf_(lo16(g.w)); v1[3] *= sigmoidf_(hi16(g.w));
;                         if (Z > 0) { v0 += old0[mm][bj]; v1 += old1[mm][bj]; }
;                         if (Z < 2) { float* mp = mix + (size_t)row * 2048 + col; *(f32x4*)mp = v0; *(f32x4*)(mp + 4) = v1; }
;                         else { u32x4 w; w.x = cvt_pk_bf16(v0[0], v0[1]); w.y = cvt_pk_bf16(v0[2], v0[3]); w.z = cvt_pk_bf16(v1[0], v1[1]); w.w = cvt_pk_bf16(v1[2], v1[3]);
;                             *(u32x4*)(mixb + (size_t)row * 2048 + col) = w; } }
	v_and_b32_e32 v218, 0xffff0000, v202
	v_lshlrev_b32_e32 v202, 16, v202
	v_and_b32_e32 v219, 0xffff0000, v203
	v_lshlrev_b32_e32 v203, 16, v203
	v_and_b32_e32 v232, 0xffff0000, v204
	v_lshlrev_b32_e32 v204, 16, v204
	v_and_b32_e32 v233, 0xffff0000, v205
	v_lshlrev_b32_e32 v205, 16, v205
	v_mul_f32_e32 v202, s19, v202
	v_mul_f32_e32 v218, s19, v218
	v_mul_f32_e32 v203, s19, v203
	v_mul_f32_e32 v219, s19, v219
	v_mul_f32_e32 v204, s19, v204
	v_mul_f32_e32 v232, s19, v232
	v_mul_f32_e32 v205, s19, v205
	v_mul_f32_e32 v233, s19, v233
	v_exp_f32_e32 v202, v202
	v_exp_f32_e32 v218, v218
	v_exp_f32_e32 v203, v203
	v_exp_f32_e32 v219, v219
	v_exp_f32_e32 v204, v204
	v_exp_f32_e32 v232, v232
	v_exp_f32_e32 v205, v205
	v_exp_f32_e32 v233, v233
	v_add_f32_e32 v202, 1.0, v202
	v_add_f32_e32 v218, 1.0, v218
	v_add_f32_e32 v203, 1.0, v203
	v_add_f32_e32 v219, 1.0, v219
	v_add_f32_e32 v204, 1.0, v204
	v_add_f32_e32 v232, 1.0, v232
	v_add_f32_e32 v205, 1.0, v205
	v_add_f32_e32 v233, 1.0, v233
	v_rcp_f32_e32 v202, v202
	v_rcp_f32_e32 v218, v218
	v_rcp_f32_e32 v203, v203
	v_rcp_f32_e32 v219, v219
	v_rcp_f32_e32 v204, v204
	v_rcp_f32_e32 v232, v232
	v_rcp_f32_e32 v205, v205
	v_rcp_f32_e32 v233, v233
	v_mul_f32_e32 v44, v44, v202
	v_mul_f32_e32 v45, v45, v218
	v_mul_f32_e32 v46, v46, v203
	v_mul_f32_e32 v47, v47, v219
	v_mul_f32_e32 v40, v40, v204
	v_mul_f32_e32 v41, v41, v232
	v_mul_f32_e32 v42, v42, v205
	v_mul_f32_e32 v43, v43, v233
	v_add_f32_e32 v44, v44, v210
	v_add_f32_e32 v45, v45, v211
	v_add_f32_e32 v46, v46, v212
	v_add_f32_e32 v47, v47, v213
	v_add_f32_e32 v40, v40, v214
	v_add_f32_e32 v41, v41, v215
	v_add_f32_e32 v42, v42, v216
	v_add_f32_e32 v43, v43, v217
	v_and_b32_e32 v218, 0xffff0000, v206
	v_lshlrev_b32_e32 v206, 16, v206
	v_and_b32_e32 v219, 0xffff0000, v207
	v_lshlrev_b32_e32 v207, 16, v207
	v_and_b32_e32 v232, 0xffff0000, v208
	v_lshlrev_b32_e32 v208, 16, v208
	v_and_b32_e32 v233, 0xffff0000, v209
	v_lshlrev_b32_e32 v209, 16, v209
	v_mul_f32_e32 v206, s19, v206
	v_mul_f32_e32 v218, s19, v218
	v_mul_f32_e32 v207, s19, v207
	v_mul_f32_e32 v219, s19, v219
	v_mul_f32_e32 v208, s19, v208
	v_mul_f32_e32 v232, s19, v232
	v_mul_f32_e32 v209, s19, v209
	v_mul_f32_e32 v233, s19, v233
	v_exp_f32_e32 v206, v206
	v_exp_f32_e32 v218, v218
	v_exp_f32_e32 v207, v207
	v_exp_f32_e32 v219, v219
	v_exp_f32_e32 v208, v208
	v_exp_f32_e32 v232, v232
	v_exp_f32_e32 v209, v209
	v_exp_f32_e32 v233, v233
	v_add_f32_e32 v206, 1.0, v206
	v_add_f32_e32 v218, 1.0, v218
	v_add_f32_e32 v207, 1.0, v207
	v_add_f32_e32 v219, 1.0, v219
	v_add_f32_e32 v208, 1.0, v208
	v_add_f32_e32 v232, 1.0, v232
	v_add_f32_e32 v209, 1.0, v209
	v_add_f32_e32 v233, 1.0, v233
	v_rcp_f32_e32 v206, v206
	v_rcp_f32_e32 v218, v218
	v_rcp_f32_e32 v207, v207
	v_rcp_f32_e32 v219, v219
	v_rcp_f32_e32 v208, v208
	v_rcp_f32_e32 v232, v232
	v_rcp_f32_e32 v209, v209
	v_rcp_f32_e32 v233, v233
	v_mul_f32_e32 v36, v36, v206
	v_mul_f32_e32 v37, v37, v218
	v_mul_f32_e32 v38, v38, v207
	v_mul_f32_e32 v39, v39, v219
	v_mul_f32_e32 v32, v32, v208
	v_mul_f32_e32 v33, v33, v232
	v_mul_f32_e32 v34, v34, v209
	v_mul_f32_e32 v35, v35, v233
	v_add_f32_e32 v36, v36, v224
	v_add_f32_e32 v37, v37, v225
	v_add_f32_e32 v38, v38, v226
	v_add_f32_e32 v39, v39, v227
	v_add_f32_e32 v32, v32, v228
	v_add_f32_e32 v33, v33, v229
	v_add_f32_e32 v34, v34, v230
	v_add_f32_e32 v35, v35, v231
	s_add_u32 s22, s52, 0x90000
	s_addc_u32 s23, s53, 0
	v_cvt_pk_bf16_f32 v202, v44, v45
	v_cvt_pk_bf16_f32 v203, v46, v47
	v_cvt_pk_bf16_f32 v204, v40, v41
	v_cvt_pk_bf16_f32 v205, v42, v43
	global_store_dwordx4 v245, v[202:205], s[22:23] offset:0
	v_cvt_pk_bf16_f32 v206, v36, v37
	v_cvt_pk_bf16_f32 v207, v38, v39
	v_cvt_pk_bf16_f32 v208, v32, v33
	v_cvt_pk_bf16_f32 v209, v34, v35
	global_store_dwordx4 v245, v[206:209], s[22:23] offset:256
	s_waitcnt vmcnt(10)
	v_and_b32_e32 v218, 0xffff0000, v128
	v_lshlrev_b32_e32 v128, 16, v128
	v_and_b32_e32 v219, 0xffff0000, v129
	v_lshlrev_b32_e32 v129, 16, v129
	v_and_b32_e32 v232, 0xffff0000, v130
	v_lshlrev_b32_e32 v130, 16, v130
	v_and_b32_e32 v233, 0xffff0000, v131
	v_lshlrev_b32_e32 v131, 16, v131
	v_mul_f32_e32 v128, s19, v128
	v_mul_f32_e32 v218, s19, v218
	v_mul_f32_e32 v129, s19, v129
	v_mul_f32_e32 v219, s19, v219
	v_mul_f32_e32 v130, s19, v130
	v_mul_f32_e32 v232, s19, v232
	v_mul_f32_e32 v131, s19, v131
	v_mul_f32_e32 v233, s19, v233
	v_exp_f32_e32 v128, v128
	v_exp_f32_e32 v218, v218
	v_exp_f32_e32 v129, v129
	v_exp_f32_e32 v219, v219
	v_exp_f32_e32 v130, v130
	v_exp_f32_e32 v232, v232
	v_exp_f32_e32 v131, v131
	v_exp_f32_e32 v233, v233
	v_add_f32_e32 v128, 1.0, v128
	v_add_f32_e32 v218, 1.0, v218
	v_add_f32_e32 v129, 1.0, v129
	v_add_f32_e32 v219, 1.0, v219
	v_add_f32_e32 v130, 1.0, v130
	v_add_f32_e32 v232, 1.0, v232
	v_add_f32_e32 v131, 1.0, v131
	v_add_f32_e32 v233, 1.0, v233
	v_rcp_f32_e32 v128, v128
	v_rcp_f32_e32 v218, v218
	v_rcp_f32_e32 v129, v129
	v_rcp_f32_e32 v219, v219
	v_rcp_f32_e32 v130, v130
	v_rcp_f32_e32 v232, v232
	v_rcp_f32_e32 v131, v131
	v_rcp_f32_e32 v233, v233
	v_mul_f32_e32 v28, v28, v128
	v_mul_f32_e32 v29, v29, v218
	v_mul_f32_e32 v30, v30, v129
	v_mul_f32_e32 v31, v31, v219
	v_mul_f32_e32 v24, v24, v130
	v_mul_f32_e32 v25, v25, v232
	v_mul_f32_e32 v26, v26, v131
	v_mul_f32_e32 v27, v27, v233
	v_add_f32_e32 v28, v28, v136
	v_add_f32_e32 v29, v29, v137
	v_add_f32_e32 v30, v30, v138
	v_add_f32_e32 v31, v31, v139
	v_add_f32_e32 v24, v24, v140
	v_add_f32_e32 v25, v25, v141
	v_add_f32_e32 v26, v26, v142
	v_add_f32_e32 v27, v27, v143
	v_and_b32_e32 v218, 0xffff0000, v132
	v_lshlrev_b32_e32 v132, 16, v132
	v_and_b32_e32 v219, 0xffff0000, v133
	v_lshlrev_b32_e32 v133, 16, v133
; __device__ __forceinline__ float lo16(unsigned u) { return __uint_as_float(u << 16); }
; __device__ __forceinline__ float hi16(unsigned u) { return __uint_as_float(u & 0xffff0000u); }
; __device__ __forceinline__ float sigmoidf_(float x) { return __builtin_amdgcn_rcpf(1.0f + __expf(-x)); }
; __device__ __forceinline__ unsigned cvt_pk_bf16(float lo, float hi) { return pk2(lo, hi); }
;     template <int Z> __device__ __forceinline__ void run(const f32x4 (&acc)[2][2][4][2], const Unit& u, int wr, int wc, int fr, int fq) const {
;     ...
;                 u32x4 graw[2][2]; f32x4 old0[2][2], old1[2][2];
; #pragma unroll
;                 for (int mm = 0; mm < 2; ++mm)
; #pragma unroll
;                     for (int bj = 0; bj < 2; ++bj) { const int row = row0 + ai * HALF + (m2 + mm) * 16, col = col0 + bj * HALF;
;                         graw[mm][bj] = *(const u32x4*)(proj + (size_t)row * NP + C_BR + Z * 2048 + col);
;                         if (Z > 0) { const float* mp = mix + (size_t)row * 2048 + col; old0[mm][bj] = *(const f32x4*)mp; old1[mm][bj] = *(const f32x4*)(mp + 4); } }
; #pragma unroll
;                 for (int mm = 0; mm < 2; ++mm)
; #pragma unroll
;                     for (int bj = 0; bj < 2; ++bj) { const int row = row0 + ai * HALF + (m2 + mm) * 16, col = col0 + bj * HALF;
;                         const u32x4 g = graw[mm][bj];
;                         f32x4 v0 = acc[ai][bj][m2 + mm][0], v1 = acc[ai][bj][m2 + mm][1];
;                         v0[0] *= sigmoidf_(lo16(g.x)); v0[1] *= sigmoidf_(hi16(g.x)); v0[2] *= sigmoidf_(lo16(g.y)); v0[3] *= sigmoidf_(hi16(g.y));
;                         v1[0] *= sigmoidf_(lo16(g.z)); v1[1] *= sigmoidf_(hi16(g.z)); v1[2] *= sigmoidf_(lo16(g.w)); v1[3] *= sigmoidf_(hi16(g.w));
;                         if (Z > 0) { v0 += old0[mm][bj]; v1 += old1[mm][bj]; }
;                         if (Z < 2) { float* mp = mix + (size_t)row * 2048 + col; *(f32x4*)mp = v0; *(f32x4*)(mp + 4) = v1; }
;                         else { u32x4 w; w.x = cvt_pk_bf16(v0[0], v0[1]); w.y = cvt_pk_bf16(v0[2], v0[3]); w.z = cvt_pk_bf16(v1[0], v1[1]); w.w = cvt_pk_bf16(v1[2], v1[3]);
;                             *(u32x4*)(mixb + (size_t)row * 2048 + col) = w; } }
	v_and_b32_e32 v232, 0xffff0000, v134
	v_lshlrev_b32_e32 v134, 16, v134
	v_and_b32_e32 v233, 0xffff0000, v135
	v_lshlrev_b32_e32 v135, 16, v135
	v_mul_f32_e32 v132, s19, v132
	v_mul_f32_e32 v218, s19, v218
	v_mul_f32_e32 v133, s19, v133
	v_mul_f32_e32 v219, s19, v219
	v_mul_f32_e32 v134, s19, v134
	v_mul_f32_e32 v232, s19, v232
	v_mul_f32_e32 v135, s19, v135
	v_mul_f32_e32 v233, s19, v233
	v_exp_f32_e32 v132, v132
	v_exp_f32_e32 v218, v218
	v_exp_f32_e32 v133, v133
	v_exp_f32_e32 v219, v219
	v_exp_f32_e32 v134, v134
	v_exp_f32_e32 v232, v232
	v_exp_f32_e32 v135, v135
	v_exp_f32_e32 v233, v233
	v_add_f32_e32 v132, 1.0, v132
	v_add_f32_e32 v218, 1.0, v218
	v_add_f32_e32 v133, 1.0, v133
	v_add_f32_e32 v219, 1.0, v219
	v_add_f32_e32 v134, 1.0, v134
	v_add_f32_e32 v232, 1.0, v232
	v_add_f32_e32 v135, 1.0, v135
	v_add_f32_e32 v233, 1.0, v233
	v_rcp_f32_e32 v132, v132
	v_rcp_f32_e32 v218, v218
	v_rcp_f32_e32 v133, v133
	v_rcp_f32_e32 v219, v219
	v_rcp_f32_e32 v134, v134
	v_rcp_f32_e32 v232, v232
	v_rcp_f32_e32 v135, v135
	v_rcp_f32_e32 v233, v233
	v_mul_f32_e32 v20, v20, v132
	v_mul_f32_e32 v21, v21, v218
	v_mul_f32_e32 v22, v22, v133
	v_mul_f32_e32 v23, v23, v219
	v_mul_f32_e32 v16, v16, v134
	v_mul_f32_e32 v17, v17, v232
	v_mul_f32_e32 v18, v18, v135
	v_mul_f32_e32 v19, v19, v233
	v_add_f32_e32 v20, v20, v144
	v_add_f32_e32 v21, v21, v145
	v_add_f32_e32 v22, v22, v146
	v_add_f32_e32 v23, v23, v147
	v_add_f32_e32 v16, v16, v148
	v_add_f32_e32 v17, v17, v149
	v_add_f32_e32 v18, v18, v150
	v_add_f32_e32 v19, v19, v151
	s_add_u32 s22, s52, 0xa0000
	s_addc_u32 s23, s53, 0
	v_cvt_pk_bf16_f32 v128, v28, v29
	v_cvt_pk_bf16_f32 v129, v30, v31
	v_cvt_pk_bf16_f32 v130, v24, v25
	v_cvt_pk_bf16_f32 v131, v26, v27
	global_store_dwordx4 v245, v[128:131], s[22:23] offset:0
	v_cvt_pk_bf16_f32 v132, v20, v21
	v_cvt_pk_bf16_f32 v133, v22, v23
	v_cvt_pk_bf16_f32 v134, v16, v17
	v_cvt_pk_bf16_f32 v135, v18, v19
	global_store_dwordx4 v245, v[132:135], s[22:23] offset:256
	s_waitcnt vmcnt(4)
	v_and_b32_e32 v218, 0xffff0000, v152
	v_lshlrev_b32_e32 v152, 16, v152
	v_and_b32_e32 v219, 0xffff0000, v153
	v_lshlrev_b32_e32 v153, 16, v153
	v_and_b32_e32 v232, 0xffff0000, v154
	v_lshlrev_b32_e32 v154, 16, v154
	v_and_b32_e32 v233, 0xffff0000, v155
	v_lshlrev_b32_e32 v155, 16, v155
	v_mul_f32_e32 v152, s19, v152
	v_mul_f32_e32 v218, s19, v218
	v_mul_f32_e32 v153, s19, v153
	v_mul_f32_e32 v219, s19, v219
	v_mul_f32_e32 v154, s19, v154
	v_mul_f32_e32 v232, s19, v232
	v_mul_f32_e32 v155, s19, v155
	v_mul_f32_e32 v233, s19, v233
	v_exp_f32_e32 v152, v152
	v_exp_f32_e32 v218, v218
	v_exp_f32_e32 v153, v153
	v_exp_f32_e32 v219, v219
	v_exp_f32_e32 v154, v154
	v_exp_f32_e32 v232, v232
	v_exp_f32_e32 v155, v155
	v_exp_f32_e32 v233, v233
	v_add_f32_e32 v152, 1.0, v152
	v_add_f32_e32 v218, 1.0, v218
	v_add_f32_e32 v153, 1.0, v153
	v_add_f32_e32 v219, 1.0, v219
	v_add_f32_e32 v154, 1.0, v154
	v_add_f32_e32 v232, 1.0, v232
	v_add_f32_e32 v155, 1.0, v155
	v_add_f32_e32 v233, 1.0, v233
	v_rcp_f32_e32 v152, v152
	v_rcp_f32_e32 v218, v218
	v_rcp_f32_e32 v153, v153
	v_rcp_f32_e32 v219, v219
	v_rcp_f32_e32 v154, v154
	v_rcp_f32_e32 v232, v232
	v_rcp_f32_e32 v155, v155
	v_rcp_f32_e32 v233, v233
	v_mul_f32_e32 v12, v12, v152
	v_mul_f32_e32 v13, v13, v218
	v_mul_f32_e32 v14, v14, v153
	v_mul_f32_e32 v15, v15, v219
	v_mul_f32_e32 v8, v8, v154
	v_mul_f32_e32 v9, v9, v232
	v_mul_f32_e32 v10, v10, v155
	v_mul_f32_e32 v11, v11, v233
	v_add_f32_e32 v12, v12, v160
	v_add_f32_e32 v13, v13, v161
	v_add_f32_e32 v14, v14, v162
	v_add_f32_e32 v15, v15, v163
	v_add_f32_e32 v8, v8, v164
	v_add_f32_e32 v9, v9, v165
	v_add_f32_e32 v10, v10, v166
	v_add_f32_e32 v11, v11, v167
	v_and_b32_e32 v218, 0xffff0000, v156
	v_lshlrev_b32_e32 v156, 16, v156
	v_and_b32_e32 v219, 0xffff0000, v157
	v_lshlrev_b32_e32 v157, 16, v157
	v_and_b32_e32 v232, 0xffff0000, v158
	v_lshlrev_b32_e32 v158, 16, v158
	v_and_b32_e32 v233, 0xffff0000, v159
	v_lshlrev_b32_e32 v159, 16, v159
	v_mul_f32_e32 v156, s19, v156
	v_mul_f32_e32 v218, s19, v218
	v_mul_f32_e32 v157, s19, v157
	v_mul_f32_e32 v219, s19, v219
	v_mul_f32_e32 v158, s19, v158
	v_mul_f32_e32 v232, s19, v232
	v_mul_f32_e32 v159, s19, v159
	v_mul_f32_e32 v233, s19, v233
	v_exp_f32_e32 v156, v156
	v_exp_f32_e32 v218, v218
	v_exp_f32_e32 v157, v157
	v_exp_f32_e32 v219, v219
	v_exp_f32_e32 v158, v158
	v_exp_f32_e32 v232, v232
	v_exp_f32_e32 v159, v159
	v_exp_f32_e32 v233, v233
	v_add_f32_e32 v156, 1.0, v156
	v_add_f32_e32 v218, 1.0, v218
	v_add_f32_e32 v157, 1.0, v157
	v_add_f32_e32 v219, 1.0, v219
	v_add_f32_e32 v158, 1.0, v158
	v_add_f32_e32 v232, 1.0, v232
	v_add_f32_e32 v159, 1.0, v159
	v_add_f32_e32 v233, 1.0, v233
	v_rcp_f32_e32 v156, v156
	v_rcp_f32_e32 v218, v218
	v_rcp_f32_e32 v157, v157
	v_rcp_f32_e32 v219, v219
	v_rcp_f32_e32 v158, v158
	v_rcp_f32_e32 v232, v232
	v_rcp_f32_e32 v159, v159
	v_rcp_f32_e32 v233, v233
	v_mul_f32_e32 v4, v4, v156
	v_mul_f32_e32 v5, v5, v218
	v_mul_f32_e32 v6, v6, v157
	v_mul_f32_e32 v7, v7, v219
	v_mul_f32_e32 v0, v0, v158
	v_mul_f32_e32 v1, v1, v232
	v_mul_f32_e32 v2, v2, v159
	v_mul_f32_e32 v3, v3, v233
	v_add_f32_e32 v4, v4, v168
	v_add_f32_e32 v5, v5, v169
	v_add_f32_e32 v6, v6, v170
	v_add_f32_e32 v7, v7, v171
	v_add_f32_e32 v0, v0, v172
	v_add_f32_e32 v1, v1, v173
	v_add_f32_e32 v2, v2, v174
	v_add_f32_e32 v3, v3, v175
	s_add_u32 s22, s52, 0xb0000
	s_addc_u32 s23, s53, 0
	v_cvt_pk_bf16_f32 v152, v12, v13
	v_cvt_pk_bf16_f32 v153, v14, v15
	v_cvt_pk_bf16_f32 v154, v8, v9
	v_cvt_pk_bf16_f32 v155, v10, v11
	global_store_dwordx4 v245, v[152:155], s[22:23] offset:0
	v_cvt_pk_bf16_f32 v156, v4, v5
	v_cvt_pk_bf16_f32 v157, v6, v7
	v_cvt_pk_bf16_f32 v158, v0, v1
	v_cvt_pk_bf16_f32 v159, v2, v3
	global_store_dwordx4 v245, v[156:159], s[22:23] offset:256
	s_branch .LBB0_394
